# adds: GEMM epilogue rss loads hoisted; IEEE-expanded 1/sqrtf sequences (35 VALU each) in GEMM epilogue, ctx GEMM, conv LN and SGU LN stats replaced by v_rsq_f32 (f32)
# speedup vs baseline: 1.0242x; 1.0078x over previous
.LBB0_231:
	v_mul_hi_i32 v40, v63, s84
	v_lshrrev_b32_e32 v41, 31, v40
	v_ashrrev_i32_e32 v40, 2, v40
	v_add_u32_e32 v76, v40, v41
	v_lshl_add_u32 v72, v76, 4, v62
	ds_read_b128 v[40:43], v72
	ds_read_b128 v[52:55], v72 offset:16
	v_add_u32_e32 v62, 0x4000, v62
	s_waitcnt lgkmcnt(1)
	v_pk_add_f32 v[64:65], v[42:43], 0 op_sel_hi:[1,0]
	v_pk_add_f32 v[66:67], v[40:41], 0 op_sel_hi:[1,0]
	ds_read_b128 v[40:43], v72 offset:10752
	s_waitcnt lgkmcnt(1)
	v_pk_add_f32 v[54:55], v[54:55], 0 op_sel_hi:[1,0]
	v_pk_add_f32 v[52:53], v[52:53], 0 op_sel_hi:[1,0]
	s_waitcnt lgkmcnt(0)
	v_pk_add_f32 v[64:65], v[64:65], v[42:43]
	v_pk_add_f32 v[66:67], v[66:67], v[40:41]
	ds_read_b128 v[40:43], v72 offset:10768
	s_waitcnt lgkmcnt(0)
	v_pk_add_f32 v[54:55], v[54:55], v[42:43]
	v_pk_add_f32 v[52:53], v[52:53], v[40:41]
	ds_read_b128 v[40:43], v72 offset:21504
	s_waitcnt lgkmcnt(0)
	v_pk_add_f32 v[64:65], v[64:65], v[42:43]
	v_pk_add_f32 v[66:67], v[66:67], v[40:41]
	ds_read_b128 v[40:43], v72 offset:21520
	s_waitcnt lgkmcnt(0)
	v_pk_add_f32 v[54:55], v[54:55], v[42:43]
	v_pk_add_f32 v[52:53], v[52:53], v[40:41]
	ds_read_b128 v[40:43], v72 offset:32256
	s_waitcnt lgkmcnt(0)
	v_pk_add_f32 v[64:65], v[64:65], v[42:43]
	v_pk_add_f32 v[66:67], v[66:67], v[40:41]
	ds_read_b128 v[40:43], v72 offset:32272
	s_waitcnt lgkmcnt(0)
	v_pk_add_f32 v[54:55], v[54:55], v[42:43]
	v_pk_add_f32 v[52:53], v[52:53], v[40:41]
	ds_read_b128 v[40:43], v72 offset:43008
	s_waitcnt lgkmcnt(0)
	v_pk_add_f32 v[64:65], v[64:65], v[42:43]
	v_pk_add_f32 v[66:67], v[66:67], v[40:41]
	ds_read_b128 v[40:43], v72 offset:43024
	s_waitcnt lgkmcnt(0)
	v_pk_add_f32 v[54:55], v[54:55], v[42:43]
	v_pk_add_f32 v[52:53], v[52:53], v[40:41]
	ds_read_b128 v[40:43], v72 offset:53760
	s_waitcnt lgkmcnt(0)
	v_pk_add_f32 v[64:65], v[64:65], v[42:43]
	v_pk_add_f32 v[66:67], v[66:67], v[40:41]
	ds_read_b128 v[40:43], v72 offset:53776
	s_waitcnt lgkmcnt(0)
	v_pk_add_f32 v[54:55], v[54:55], v[42:43]
	v_pk_add_f32 v[52:53], v[52:53], v[40:41]
	ds_read_b128 v[40:43], v72 offset:64512
	s_waitcnt lgkmcnt(0)
	v_pk_add_f32 v[64:65], v[64:65], v[42:43]
	v_pk_add_f32 v[66:67], v[66:67], v[40:41]
	ds_read_b128 v[40:43], v72 offset:64528
	s_waitcnt lgkmcnt(0)
	v_pk_add_f32 v[52:53], v[52:53], v[40:41]
	v_add_u32_e32 v40, 0x12600, v72
	v_pk_add_f32 v[54:55], v[54:55], v[42:43]
	ds_read_b128 v[40:43], v40
	s_waitcnt lgkmcnt(0)
	v_pk_add_f32 v[70:71], v[66:67], v[40:41]
	v_add_u32_e32 v40, 0x12610, v72
	v_pk_add_f32 v[68:69], v[64:65], v[42:43]
	ds_read_b128 v[40:43], v40
	s_waitcnt lgkmcnt(0)
	v_pk_add_f32 v[74:75], v[52:53], v[40:41]
	v_add_u32_e32 v52, s48, v76
	v_ashrrev_i32_e32 v53, 31, v52
	v_lshl_add_u64 v[40:41], v[52:53], 2, s[0:1]
	global_load_dword v40, v[40:41], off
	v_pk_add_f32 v[72:73], v[54:55], v[42:43]
	v_mad_u64_u32 v[54:55], s[6:7], v76, s78, v[50:51]
	v_add_u32_e32 v50, 0x1000, v50
	s_waitcnt vmcnt(0)
	v_fmamk_f32 v40, v40, 0x3a000000, v176
	v_ashrrev_i32_e32 v55, 31, v54
	v_lshl_add_u64 v[64:65], v[54:55], 2, s[44:45]
	v_rsq_f32_e32 v76, v40
	global_load_dwordx4 v[40:43], v[64:65], off offset:16
	s_nop 0
	global_load_dwordx4 v[64:67], v[64:65], off
	v_cmp_lt_i32_e32 vcc, s75, v63
	s_or_b64 s[52:53], vcc, s[52:53]
	s_waitcnt vmcnt(0)
	v_pk_fma_f32 v[64:65], v[70:71], v[76:77], v[64:65] op_sel_hi:[1,0,1]
	v_pk_fma_f32 v[66:67], v[68:69], v[76:77], v[66:67] op_sel_hi:[1,0,1]
	v_pk_fma_f32 v[68:69], v[72:73], v[76:77], v[42:43] op_sel_hi:[1,0,1]
	v_pk_fma_f32 v[42:43], v[74:75], v[76:77], v[40:41] op_sel_hi:[1,0,1]
	v_cvt_pk_bf16_f32 v40, v64, v65
	v_mov_b64_e32 v[64:65], s[46:47]
	v_mad_i64_i32 v[52:53], s[6:7], v52, s62, v[64:65]
	v_lshl_add_u64 v[52:53], v[54:55], 1, v[52:53]
	v_cvt_pk_bf16_f32 v41, v66, v67
	v_cvt_pk_bf16_f32 v42, v42, v43
	v_cvt_pk_bf16_f32 v43, v68, v69
	global_store_dwordx4 v[52:53], v[40:43], off
	s_nop 1
	v_add_u32_e32 v40, 0x200, v63
	v_mov_b32_e32 v63, v40
	s_andn2_b64 exec, exec, s[52:53]
	s_cbranch_execnz .LBB0_231

.LBB0_234:
	v_mul_hi_i32 v0, v7, s84
	v_lshrrev_b32_e32 v1, 31, v0
	v_ashrrev_i32_e32 v0, 2, v0
	v_add_u32_e32 v12, v0, v1
	v_lshl_add_u32 v13, v12, 4, v6
	ds_read_b128 v[0:3], v13
	ds_read_b128 v[8:11], v13 offset:16
	v_add_u32_e32 v6, 0x4000, v6
	s_waitcnt lgkmcnt(1)
	v_pk_add_f32 v[4:5], v[2:3], 0 op_sel_hi:[1,0]
	v_pk_add_f32 v[14:15], v[0:1], 0 op_sel_hi:[1,0]
	ds_read_b128 v[0:3], v13 offset:10752
	s_waitcnt lgkmcnt(1)
	v_pk_add_f32 v[10:11], v[10:11], 0 op_sel_hi:[1,0]
	v_pk_add_f32 v[8:9], v[8:9], 0 op_sel_hi:[1,0]
	s_waitcnt lgkmcnt(0)
	v_pk_add_f32 v[4:5], v[4:5], v[2:3]
	v_pk_add_f32 v[14:15], v[14:15], v[0:1]
	ds_read_b128 v[0:3], v13 offset:10768
	s_waitcnt lgkmcnt(0)
	v_pk_add_f32 v[10:11], v[10:11], v[2:3]
	v_pk_add_f32 v[8:9], v[8:9], v[0:1]
	ds_read_b128 v[0:3], v13 offset:21504
	s_waitcnt lgkmcnt(0)
	v_pk_add_f32 v[4:5], v[4:5], v[2:3]
	v_pk_add_f32 v[14:15], v[14:15], v[0:1]
	ds_read_b128 v[0:3], v13 offset:21520
	s_waitcnt lgkmcnt(0)
	v_pk_add_f32 v[10:11], v[10:11], v[2:3]
	v_pk_add_f32 v[8:9], v[8:9], v[0:1]
	ds_read_b128 v[0:3], v13 offset:32256
	s_waitcnt lgkmcnt(0)
	v_pk_add_f32 v[4:5], v[4:5], v[2:3]
	v_pk_add_f32 v[14:15], v[14:15], v[0:1]
	ds_read_b128 v[0:3], v13 offset:32272
	s_waitcnt lgkmcnt(0)
	v_pk_add_f32 v[10:11], v[10:11], v[2:3]
	v_pk_add_f32 v[8:9], v[8:9], v[0:1]
	ds_read_b128 v[0:3], v13 offset:43008
	s_waitcnt lgkmcnt(0)
	v_pk_add_f32 v[4:5], v[4:5], v[2:3]
	v_pk_add_f32 v[14:15], v[14:15], v[0:1]
	ds_read_b128 v[0:3], v13 offset:43024
	s_waitcnt lgkmcnt(0)
	v_pk_add_f32 v[10:11], v[10:11], v[2:3]
	v_pk_add_f32 v[8:9], v[8:9], v[0:1]
	ds_read_b128 v[0:3], v13 offset:53760
	s_waitcnt lgkmcnt(0)
	v_pk_add_f32 v[4:5], v[4:5], v[2:3]
	v_pk_add_f32 v[14:15], v[14:15], v[0:1]
	ds_read_b128 v[0:3], v13 offset:53776
	s_waitcnt lgkmcnt(0)
	v_pk_add_f32 v[10:11], v[10:11], v[2:3]
	v_pk_add_f32 v[8:9], v[8:9], v[0:1]
	ds_read_b128 v[0:3], v13 offset:64512
	s_waitcnt lgkmcnt(0)
	v_pk_add_f32 v[4:5], v[4:5], v[2:3]
	v_pk_add_f32 v[14:15], v[14:15], v[0:1]
	ds_read_b128 v[0:3], v13 offset:64528
	s_waitcnt lgkmcnt(0)
	v_pk_add_f32 v[8:9], v[8:9], v[0:1]
	v_add_u32_e32 v0, 0x12600, v13
	v_pk_add_f32 v[10:11], v[10:11], v[2:3]
	ds_read_b128 v[0:3], v0
	s_waitcnt lgkmcnt(0)
	v_pk_add_f32 v[14:15], v[14:15], v[0:1]
	v_add_u32_e32 v0, 0x12610, v13
	v_pk_add_f32 v[16:17], v[4:5], v[2:3]
	ds_read_b128 v[0:3], v0
	v_ashrrev_i32_e32 v13, 31, v12
	v_mad_u64_u32 v[4:5], s[8:9], v12, s78, v[48:49]
	v_add_u32_e32 v48, 0x1000, v48
	s_waitcnt lgkmcnt(0)
	v_pk_add_f32 v[20:21], v[8:9], v[0:1]
	v_lshl_add_u64 v[0:1], s[48:49], 0, v[12:13]
	v_lshl_add_u64 v[0:1], v[0:1], 2, s[0:1]
	global_load_dword v0, v[0:1], off offset:128
	v_pk_add_f32 v[18:19], v[10:11], v[2:3]
	v_add_u32_e32 v8, s6, v12
	s_waitcnt vmcnt(0)
	v_fmamk_f32 v0, v0, 0x3a000000, v176
	v_ashrrev_i32_e32 v5, 31, v4
	v_lshl_add_u64 v[10:11], v[4:5], 2, s[44:45]
	v_rsq_f32_e32 v22, v0
	global_load_dwordx4 v[0:3], v[10:11], off offset:16
	s_nop 0
	global_load_dwordx4 v[10:13], v[10:11], off
	v_cmp_lt_i32_e32 vcc, s75, v7
	s_or_b64 s[52:53], vcc, s[52:53]
	s_waitcnt vmcnt(0)
	v_pk_fma_f32 v[10:11], v[14:15], v[22:23], v[10:11] op_sel_hi:[1,0,1]
	v_pk_fma_f32 v[14:15], v[18:19], v[22:23], v[2:3] op_sel_hi:[1,0,1]
	v_pk_fma_f32 v[2:3], v[20:21], v[22:23], v[0:1] op_sel_hi:[1,0,1]
	v_cvt_pk_bf16_f32 v0, v10, v11
	v_mov_b64_e32 v[10:11], s[46:47]
	v_mad_i64_i32 v[8:9], s[8:9], v8, s62, v[10:11]
	v_lshl_add_u64 v[4:5], v[4:5], 1, v[8:9]
	v_pk_fma_f32 v[12:13], v[16:17], v[22:23], v[12:13] op_sel_hi:[1,0,1]
	s_nop 0
	v_cvt_pk_bf16_f32 v1, v12, v13
	v_cvt_pk_bf16_f32 v2, v2, v3
	v_cvt_pk_bf16_f32 v3, v14, v15
	global_store_dwordx4 v[4:5], v[0:3], off
	s_nop 1
	v_add_u32_e32 v0, 0x200, v7
	v_mov_b32_e32 v7, v0
	s_andn2_b64 exec, exec, s[52:53]
	s_cbranch_execnz .LBB0_234
	s_branch .LBB0_228

.LBB0_248:
	v_lshl_or_b32 v172, s10, 8, v190
	v_lshl_add_u32 v168, s9, 8, v189
	v_ashrrev_i32_e32 v173, 31, v172
	v_ashrrev_i32_e32 v169, 31, v168
	v_lshl_add_u64 v[60:61], v[172:173], 2, s[46:47]
	v_lshl_add_u64 v[166:167], v[168:169], 2, s[44:45]
	global_load_dwordx4 v[64:67], v[60:61], off offset:16
	global_load_dwordx4 v[68:71], v[60:61], off
	global_load_dwordx4 v[56:59], v[60:61], off offset:528
	s_nop 0
	global_load_dwordx4 v[60:63], v[60:61], off offset:512
	v_lshlrev_b64 v[172:173], 1, v[172:173]
	global_load_dword v200, v[166:167], off
	global_load_dword v201, v[166:167], off offset:64
	global_load_dword v202, v[166:167], off offset:128
	global_load_dword v203, v[166:167], off offset:192
	global_load_dword v204, v[166:167], off offset:512
	global_load_dword v205, v[166:167], off offset:576
	global_load_dword v206, v[166:167], off offset:640
	global_load_dword v207, v[166:167], off offset:704
	s_waitcnt vmcnt(0)
	v_fmamk_f32 v169, v200, 0x3a000000, v176
	v_readlane_b32 s10, v244, 4
	v_readlane_b32 s11, v244, 5
	v_rsq_f32_e32 v174, v169
	s_nop 0
	v_mov_b64_e32 v[170:171], s[10:11]
	v_mad_i64_i32 v[192:193], s[10:11], v168, s62, v[170:171]
	v_lshl_add_u64 v[192:193], v[192:193], 0, v[172:173]
	v_pk_fma_f32 v[142:143], v[142:143], v[174:175], v[70:71] op_sel_hi:[1,0,1]
	v_pk_fma_f32 v[140:141], v[140:141], v[174:175], v[68:69] op_sel_hi:[1,0,1]
	v_pk_fma_f32 v[194:195], v[138:139], v[174:175], v[66:67] op_sel_hi:[1,0,1]
	v_pk_fma_f32 v[138:139], v[136:137], v[174:175], v[64:65] op_sel_hi:[1,0,1]
	v_cvt_pk_bf16_f32 v136, v140, v141
	v_cvt_pk_bf16_f32 v137, v142, v143
	v_pk_fma_f32 v[134:135], v[134:135], v[174:175], v[62:63] op_sel_hi:[1,0,1]
	v_cvt_pk_bf16_f32 v138, v138, v139
	v_cvt_pk_bf16_f32 v139, v194, v195
	global_store_dwordx4 v[192:193], v[136:139], off
	v_pk_fma_f32 v[132:133], v[132:133], v[174:175], v[60:61] op_sel_hi:[1,0,1]
	s_nop 0
	v_pk_fma_f32 v[136:137], v[130:131], v[174:175], v[58:59] op_sel_hi:[1,0,1]
	v_pk_fma_f32 v[130:131], v[128:129], v[174:175], v[56:57] op_sel_hi:[1,0,1]
	v_cvt_pk_bf16_f32 v128, v132, v133
	v_cvt_pk_bf16_f32 v129, v134, v135
	s_nop 0
	v_cvt_pk_bf16_f32 v130, v130, v131
	v_cvt_pk_bf16_f32 v131, v136, v137
	global_store_dwordx4 v[192:193], v[128:131], off offset:256
	s_nop 0
	s_nop 0
	v_or_b32_e32 v129, 16, v168
	v_fmamk_f32 v128, v201, 0x3a000000, v176
	v_rsq_f32_e32 v128, v128
	v_mad_i64_i32 v[130:131], s[10:11], v129, s62, v[170:171]
	v_lshl_add_u64 v[130:131], v[130:131], 0, v[172:173]
	v_pk_fma_f32 v[126:127], v[126:127], v[128:129], v[70:71] op_sel_hi:[1,0,1]
	v_pk_fma_f32 v[124:125], v[124:125], v[128:129], v[68:69] op_sel_hi:[1,0,1]
	v_pk_fma_f32 v[132:133], v[122:123], v[128:129], v[66:67] op_sel_hi:[1,0,1]
	v_pk_fma_f32 v[122:123], v[120:121], v[128:129], v[64:65] op_sel_hi:[1,0,1]
	v_cvt_pk_bf16_f32 v120, v124, v125
	v_cvt_pk_bf16_f32 v121, v126, v127
	v_pk_fma_f32 v[118:119], v[118:119], v[128:129], v[62:63] op_sel_hi:[1,0,1]
	v_cvt_pk_bf16_f32 v122, v122, v123
	v_cvt_pk_bf16_f32 v123, v132, v133
	global_store_dwordx4 v[130:131], v[120:123], off
	v_pk_fma_f32 v[116:117], v[116:117], v[128:129], v[60:61] op_sel_hi:[1,0,1]
	s_nop 0
	v_pk_fma_f32 v[120:121], v[114:115], v[128:129], v[58:59] op_sel_hi:[1,0,1]
	v_pk_fma_f32 v[114:115], v[112:113], v[128:129], v[56:57] op_sel_hi:[1,0,1]
	v_cvt_pk_bf16_f32 v112, v116, v117
	v_cvt_pk_bf16_f32 v113, v118, v119
	s_nop 0
	v_cvt_pk_bf16_f32 v114, v114, v115
	v_cvt_pk_bf16_f32 v115, v120, v121
	global_store_dwordx4 v[130:131], v[112:115], off offset:256
	s_nop 0
	s_nop 0
	v_or_b32_e32 v113, 32, v168
	v_fmamk_f32 v112, v202, 0x3a000000, v176
	v_rsq_f32_e32 v112, v112
	v_mad_i64_i32 v[114:115], s[10:11], v113, s62, v[170:171]
	v_lshl_add_u64 v[114:115], v[114:115], 0, v[172:173]
	v_pk_fma_f32 v[110:111], v[110:111], v[112:113], v[70:71] op_sel_hi:[1,0,1]
	v_pk_fma_f32 v[108:109], v[108:109], v[112:113], v[68:69] op_sel_hi:[1,0,1]
	v_pk_fma_f32 v[116:117], v[106:107], v[112:113], v[66:67] op_sel_hi:[1,0,1]
	v_pk_fma_f32 v[106:107], v[104:105], v[112:113], v[64:65] op_sel_hi:[1,0,1]
	v_cvt_pk_bf16_f32 v104, v108, v109
	v_cvt_pk_bf16_f32 v105, v110, v111
	v_pk_fma_f32 v[102:103], v[102:103], v[112:113], v[62:63] op_sel_hi:[1,0,1]
	v_cvt_pk_bf16_f32 v106, v106, v107
	v_cvt_pk_bf16_f32 v107, v116, v117
	global_store_dwordx4 v[114:115], v[104:107], off
	v_pk_fma_f32 v[100:101], v[100:101], v[112:113], v[60:61] op_sel_hi:[1,0,1]
	s_nop 0
	v_pk_fma_f32 v[104:105], v[98:99], v[112:113], v[58:59] op_sel_hi:[1,0,1]
	v_pk_fma_f32 v[98:99], v[96:97], v[112:113], v[56:57] op_sel_hi:[1,0,1]
	v_cvt_pk_bf16_f32 v96, v100, v101
	v_cvt_pk_bf16_f32 v97, v102, v103
	s_nop 0
	v_cvt_pk_bf16_f32 v98, v98, v99
	v_cvt_pk_bf16_f32 v99, v104, v105
	global_store_dwordx4 v[114:115], v[96:99], off offset:256
	s_nop 0
	s_nop 0
	v_or_b32_e32 v97, 48, v168
	v_fmamk_f32 v96, v203, 0x3a000000, v176
	v_rsq_f32_e32 v96, v96
	v_mad_i64_i32 v[98:99], s[10:11], v97, s62, v[170:171]
	v_lshl_add_u64 v[98:99], v[98:99], 0, v[172:173]
	v_pk_fma_f32 v[94:95], v[94:95], v[96:97], v[70:71] op_sel_hi:[1,0,1]
	v_pk_fma_f32 v[92:93], v[92:93], v[96:97], v[68:69] op_sel_hi:[1,0,1]
	v_pk_fma_f32 v[100:101], v[90:91], v[96:97], v[66:67] op_sel_hi:[1,0,1]
	v_pk_fma_f32 v[90:91], v[88:89], v[96:97], v[64:65] op_sel_hi:[1,0,1]
	v_cvt_pk_bf16_f32 v88, v92, v93
	v_cvt_pk_bf16_f32 v89, v94, v95
	v_pk_fma_f32 v[86:87], v[86:87], v[96:97], v[62:63] op_sel_hi:[1,0,1]
	v_cvt_pk_bf16_f32 v90, v90, v91
	v_cvt_pk_bf16_f32 v91, v100, v101
	global_store_dwordx4 v[98:99], v[88:91], off
	v_pk_fma_f32 v[84:85], v[84:85], v[96:97], v[60:61] op_sel_hi:[1,0,1]
	s_nop 0
	v_pk_fma_f32 v[88:89], v[82:83], v[96:97], v[58:59] op_sel_hi:[1,0,1]
	v_pk_fma_f32 v[82:83], v[80:81], v[96:97], v[56:57] op_sel_hi:[1,0,1]
	v_cvt_pk_bf16_f32 v80, v84, v85
	v_cvt_pk_bf16_f32 v81, v86, v87
	s_nop 0
	v_cvt_pk_bf16_f32 v82, v82, v83
	v_cvt_pk_bf16_f32 v83, v88, v89
	global_store_dwordx4 v[98:99], v[80:83], off offset:256
	s_nop 0
	s_nop 0
	v_add_u32_e32 v81, 0x80, v168
	v_fmamk_f32 v80, v204, 0x3a000000, v176
	v_rsq_f32_e32 v80, v80
	v_mad_i64_i32 v[82:83], s[10:11], v81, s62, v[170:171]
	v_lshl_add_u64 v[82:83], v[82:83], 0, v[172:173]
	v_pk_fma_f32 v[78:79], v[78:79], v[80:81], v[70:71] op_sel_hi:[1,0,1]
	v_pk_fma_f32 v[76:77], v[76:77], v[80:81], v[68:69] op_sel_hi:[1,0,1]
	v_pk_fma_f32 v[84:85], v[74:75], v[80:81], v[66:67] op_sel_hi:[1,0,1]
	v_pk_fma_f32 v[74:75], v[72:73], v[80:81], v[64:65] op_sel_hi:[1,0,1]
	v_cvt_pk_bf16_f32 v72, v76, v77
	v_cvt_pk_bf16_f32 v73, v78, v79
	v_pk_fma_f32 v[54:55], v[54:55], v[80:81], v[62:63] op_sel_hi:[1,0,1]
	v_cvt_pk_bf16_f32 v74, v74, v75
	v_cvt_pk_bf16_f32 v75, v84, v85
	global_store_dwordx4 v[82:83], v[72:75], off
	v_pk_fma_f32 v[52:53], v[52:53], v[80:81], v[60:61] op_sel_hi:[1,0,1]
	s_nop 0
	v_pk_fma_f32 v[72:73], v[50:51], v[80:81], v[58:59] op_sel_hi:[1,0,1]
	v_pk_fma_f32 v[50:51], v[48:49], v[80:81], v[56:57] op_sel_hi:[1,0,1]
	v_cvt_pk_bf16_f32 v48, v52, v53
	v_cvt_pk_bf16_f32 v49, v54, v55
	s_nop 0
	v_cvt_pk_bf16_f32 v50, v50, v51
	v_cvt_pk_bf16_f32 v51, v72, v73
	global_store_dwordx4 v[82:83], v[48:51], off offset:256
	s_nop 0
	s_nop 0
	v_add_u32_e32 v49, 0x90, v168
	v_fmamk_f32 v48, v205, 0x3a000000, v176
	v_rsq_f32_e32 v48, v48
	v_mad_i64_i32 v[50:51], s[10:11], v49, s62, v[170:171]
	v_lshl_add_u64 v[50:51], v[50:51], 0, v[172:173]
	v_pk_fma_f32 v[46:47], v[46:47], v[48:49], v[70:71] op_sel_hi:[1,0,1]
	v_pk_fma_f32 v[44:45], v[44:45], v[48:49], v[68:69] op_sel_hi:[1,0,1]
	v_pk_fma_f32 v[52:53], v[42:43], v[48:49], v[66:67] op_sel_hi:[1,0,1]
	v_pk_fma_f32 v[42:43], v[40:41], v[48:49], v[64:65] op_sel_hi:[1,0,1]
	v_cvt_pk_bf16_f32 v40, v44, v45
	v_cvt_pk_bf16_f32 v41, v46, v47
	v_pk_fma_f32 v[38:39], v[38:39], v[48:49], v[62:63] op_sel_hi:[1,0,1]
	v_cvt_pk_bf16_f32 v42, v42, v43
	v_cvt_pk_bf16_f32 v43, v52, v53
	global_store_dwordx4 v[50:51], v[40:43], off
	v_pk_fma_f32 v[36:37], v[36:37], v[48:49], v[60:61] op_sel_hi:[1,0,1]
	s_nop 0
	v_pk_fma_f32 v[40:41], v[34:35], v[48:49], v[58:59] op_sel_hi:[1,0,1]
	v_pk_fma_f32 v[34:35], v[32:33], v[48:49], v[56:57] op_sel_hi:[1,0,1]
	v_cvt_pk_bf16_f32 v32, v36, v37
	v_cvt_pk_bf16_f32 v33, v38, v39
	s_nop 0
	v_cvt_pk_bf16_f32 v34, v34, v35
	v_cvt_pk_bf16_f32 v35, v40, v41
	global_store_dwordx4 v[50:51], v[32:35], off offset:256
	s_nop 0
	s_nop 0
	v_add_u32_e32 v33, 0xa0, v168
	v_fmamk_f32 v32, v206, 0x3a000000, v176
	v_rsq_f32_e32 v32, v32
	v_mad_i64_i32 v[34:35], s[10:11], v33, s62, v[170:171]
	v_lshl_add_u64 v[34:35], v[34:35], 0, v[172:173]
	v_pk_fma_f32 v[30:31], v[30:31], v[32:33], v[70:71] op_sel_hi:[1,0,1]
	v_pk_fma_f32 v[28:29], v[28:29], v[32:33], v[68:69] op_sel_hi:[1,0,1]
	v_pk_fma_f32 v[36:37], v[26:27], v[32:33], v[66:67] op_sel_hi:[1,0,1]
	v_pk_fma_f32 v[26:27], v[24:25], v[32:33], v[64:65] op_sel_hi:[1,0,1]
	v_cvt_pk_bf16_f32 v24, v28, v29
	v_cvt_pk_bf16_f32 v25, v30, v31
	v_pk_fma_f32 v[22:23], v[22:23], v[32:33], v[62:63] op_sel_hi:[1,0,1]
	v_cvt_pk_bf16_f32 v26, v26, v27
	v_cvt_pk_bf16_f32 v27, v36, v37
	global_store_dwordx4 v[34:35], v[24:27], off
	v_pk_fma_f32 v[20:21], v[20:21], v[32:33], v[60:61] op_sel_hi:[1,0,1]
	s_nop 0
	v_pk_fma_f32 v[24:25], v[18:19], v[32:33], v[58:59] op_sel_hi:[1,0,1]
	v_pk_fma_f32 v[18:19], v[16:17], v[32:33], v[56:57] op_sel_hi:[1,0,1]
	v_cvt_pk_bf16_f32 v16, v20, v21
	v_cvt_pk_bf16_f32 v17, v22, v23
	s_nop 0
	v_cvt_pk_bf16_f32 v18, v18, v19
	v_cvt_pk_bf16_f32 v19, v24, v25
	global_store_dwordx4 v[34:35], v[16:19], off offset:256
	s_nop 0
	s_nop 0
	v_add_u32_e32 v17, 0xb0, v168
	v_fmamk_f32 v16, v207, 0x3a000000, v176
	s_mov_b64 s[42:43], -1
	v_rsq_f32_e32 v16, v16
	v_mad_i64_i32 v[18:19], s[10:11], v17, s62, v[170:171]
	v_lshl_add_u64 v[18:19], v[18:19], 0, v[172:173]
	v_pk_fma_f32 v[14:15], v[14:15], v[16:17], v[70:71] op_sel_hi:[1,0,1]
	v_pk_fma_f32 v[12:13], v[12:13], v[16:17], v[68:69] op_sel_hi:[1,0,1]
	v_pk_fma_f32 v[20:21], v[10:11], v[16:17], v[66:67] op_sel_hi:[1,0,1]
	v_pk_fma_f32 v[10:11], v[8:9], v[16:17], v[64:65] op_sel_hi:[1,0,1]
	v_cvt_pk_bf16_f32 v8, v12, v13
	v_cvt_pk_bf16_f32 v9, v14, v15
	s_andn2_b64 vcc, exec, s[40:41]
	v_cvt_pk_bf16_f32 v10, v10, v11
	v_cvt_pk_bf16_f32 v11, v20, v21
	global_store_dwordx4 v[18:19], v[8:11], off
	v_pk_fma_f32 v[6:7], v[6:7], v[16:17], v[62:63] op_sel_hi:[1,0,1]
	v_pk_fma_f32 v[4:5], v[4:5], v[16:17], v[60:61] op_sel_hi:[1,0,1]
	v_pk_fma_f32 v[8:9], v[2:3], v[16:17], v[58:59] op_sel_hi:[1,0,1]
	v_pk_fma_f32 v[2:3], v[0:1], v[16:17], v[56:57] op_sel_hi:[1,0,1]
	v_cvt_pk_bf16_f32 v0, v4, v5
	v_cvt_pk_bf16_f32 v1, v6, v7
	s_nop 0
	v_cvt_pk_bf16_f32 v2, v2, v3
	v_cvt_pk_bf16_f32 v3, v8, v9
	global_store_dwordx4 v[18:19], v[0:3], off offset:256
	s_cbranch_vccnz .LBB0_241
	s_andn2_b64 vcc, exec, s[0:1]
	s_cbranch_vccnz .LBB0_240
	s_barrier
	s_branch .LBB0_240

.LBB0_395:
	v_fma_f32 v48, v125, v48, v140
	v_fmac_f32_e32 v48, v126, v34
	v_fma_f32 v34, v125, v34, v140
	v_fmac_f32_e32 v34, v126, v49
	v_fmac_f32_e32 v48, v109, v49
	v_fmac_f32_e32 v34, v109, v35
	v_fmac_f32_e32 v48, v127, v35
	v_fmac_f32_e32 v34, v127, v50
	v_fmac_f32_e32 v48, v110, v50
	v_fmac_f32_e32 v34, v110, v36
	v_fmac_f32_e32 v48, v111, v36
	v_fmac_f32_e32 v34, v111, v51
	v_fmac_f32_e32 v48, v112, v51
	v_fmac_f32_e32 v34, v112, v37
	v_fmac_f32_e32 v48, v128, v37
	v_fmac_f32_e32 v34, v128, v52
	v_fma_f32 v49, v125, v49, v140
	v_fmac_f32_e32 v48, v113, v52
	v_fmac_f32_e32 v34, v113, v38
	v_fmac_f32_e32 v49, v126, v35
	v_fma_f32 v35, v125, v35, v140
	v_fmac_f32_e32 v48, v114, v38
	v_fmac_f32_e32 v34, v114, v53
	v_fmac_f32_e32 v35, v126, v50
	v_fmac_f32_e32 v48, v115, v53
	v_fmac_f32_e32 v34, v115, v39
	v_fmac_f32_e32 v49, v109, v50
	v_fmac_f32_e32 v35, v109, v36
	v_fmac_f32_e32 v48, v129, v39
	v_fmac_f32_e32 v34, v129, v54
	v_fmac_f32_e32 v49, v127, v36
	v_fmac_f32_e32 v35, v127, v51
	v_fmac_f32_e32 v48, v116, v54
	v_fmac_f32_e32 v34, v116, v40
	v_fmac_f32_e32 v49, v110, v51
	v_fmac_f32_e32 v35, v110, v37
	s_lshl_b32 s4, s42, 5
	v_fmac_f32_e32 v48, v117, v40
	v_fmac_f32_e32 v34, v117, v62
	v_fmac_f32_e32 v49, v111, v37
	v_fmac_f32_e32 v35, v111, v52
	v_add_u32_e32 v66, s4, v28
	v_mov_b64_e32 v[24:25], s[48:49]
	v_fmac_f32_e32 v48, v118, v62
	v_fmac_f32_e32 v34, v118, v61
	v_fmac_f32_e32 v49, v112, v52
	v_fmac_f32_e32 v35, v112, v38
	s_or_b32 s83, s4, s82
	v_mad_i64_i32 v[16:17], s[4:5], v66, s62, v[24:25]
	v_fmac_f32_e32 v48, v130, v61
	v_fmac_f32_e32 v34, v130, v55
	v_fmac_f32_e32 v49, v128, v38
	v_fmac_f32_e32 v35, v128, v53
	v_fma_f32 v50, v125, v50, v140
	v_lshl_add_u64 v[16:17], v[16:17], 0, v[144:145]
	v_fmac_f32_e32 v48, v119, v55
	v_fmac_f32_e32 v34, v119, v41
	v_fmac_f32_e32 v49, v113, v53
	v_fmac_f32_e32 v35, v113, v39
	v_fmac_f32_e32 v50, v126, v36
	v_fma_f32 v36, v125, v36, v140
	v_add_co_u32_e32 v16, vcc, s74, v16
	v_fmac_f32_e32 v48, v120, v41
	v_fmac_f32_e32 v34, v120, v56
	v_fmac_f32_e32 v49, v114, v39
	v_fmac_f32_e32 v35, v114, v54
	v_fmac_f32_e32 v36, v126, v51
	v_addc_co_u32_e32 v17, vcc, 0, v17, vcc
	v_fmac_f32_e32 v48, v121, v56
	v_fmac_f32_e32 v34, v121, v42
	v_fmac_f32_e32 v49, v115, v54
	v_fmac_f32_e32 v35, v115, v40
	v_fmac_f32_e32 v50, v109, v51
	v_fmac_f32_e32 v36, v109, v37
	global_load_dwordx4 v[20:23], v[16:17], off offset:2048
	v_or_b32_e32 v16, 1, v66
	v_fmac_f32_e32 v48, v131, v42
	v_fmac_f32_e32 v34, v131, v57
	v_fmac_f32_e32 v49, v129, v40
	v_fmac_f32_e32 v35, v129, v62
	v_fmac_f32_e32 v50, v127, v37
	v_fmac_f32_e32 v36, v127, v52
	v_mad_i64_i32 v[16:17], s[4:5], v16, s62, v[24:25]
	v_fmac_f32_e32 v48, v122, v57
	v_fmac_f32_e32 v34, v122, v43
	v_fmac_f32_e32 v49, v116, v62
	v_fmac_f32_e32 v35, v116, v61
	v_fmac_f32_e32 v50, v110, v52
	v_fmac_f32_e32 v36, v110, v38
	v_lshl_add_u64 v[16:17], v[16:17], 0, v[144:145]
	v_fmac_f32_e32 v48, v123, v43
	v_fmac_f32_e32 v34, v123, v58
	v_fmac_f32_e32 v49, v117, v61
	v_fmac_f32_e32 v35, v117, v55
	v_fmac_f32_e32 v50, v111, v38
	v_fmac_f32_e32 v36, v111, v53
	v_add_co_u32_e32 v16, vcc, s74, v16
	v_fmac_f32_e32 v48, v124, v58
	v_fmac_f32_e32 v34, v124, v44
	v_fmac_f32_e32 v49, v118, v55
	v_fmac_f32_e32 v35, v118, v41
	v_fmac_f32_e32 v50, v112, v53
	v_fmac_f32_e32 v36, v112, v39
	v_addc_co_u32_e32 v17, vcc, 0, v17, vcc
	v_lshl_add_u32 v63, s42, 15, v26
	v_fmac_f32_e32 v48, v132, v44
	v_fmac_f32_e32 v34, v132, v59
	v_fmac_f32_e32 v49, v130, v41
	v_fmac_f32_e32 v35, v130, v56
	v_fmac_f32_e32 v50, v128, v39
	v_fmac_f32_e32 v36, v128, v54
	v_fma_f32 v51, v125, v51, v140
	global_load_dwordx4 v[16:19], v[16:17], off offset:2048
	v_fmac_f32_e32 v48, v133, v59
	ds_read_u16 v65, v63 offset:30720
	ds_read_u16 v64, v63 offset:31744
	v_fmac_f32_e32 v34, v133, v45
	v_fmac_f32_e32 v49, v119, v56
	v_fmac_f32_e32 v35, v119, v42
	v_fmac_f32_e32 v50, v113, v54
	v_fmac_f32_e32 v36, v113, v40
	v_fmac_f32_e32 v51, v126, v37
	v_fma_f32 v37, v125, v37, v140
	v_fmac_f32_e32 v48, v134, v45
	v_fmac_f32_e32 v34, v134, v60
	v_fmac_f32_e32 v49, v120, v42
	v_fmac_f32_e32 v35, v120, v57
	v_fmac_f32_e32 v50, v114, v40
	v_fmac_f32_e32 v36, v114, v62
	v_fmac_f32_e32 v37, v126, v52
	v_fmac_f32_e32 v48, v135, v60
	v_fmac_f32_e32 v34, v135, v46
	v_fmac_f32_e32 v49, v121, v57
	v_fmac_f32_e32 v35, v121, v43
	v_fmac_f32_e32 v50, v115, v62
	v_fmac_f32_e32 v36, v115, v61
	v_fmac_f32_e32 v51, v109, v52
	v_fmac_f32_e32 v37, v109, v38
	v_fmac_f32_e32 v48, v138, v46
	v_fmac_f32_e32 v34, v138, v47
	v_fmac_f32_e32 v49, v131, v43
	v_fmac_f32_e32 v35, v131, v58
	v_fmac_f32_e32 v50, v129, v61
	v_fmac_f32_e32 v36, v129, v55
	v_fmac_f32_e32 v51, v127, v38
	v_fmac_f32_e32 v37, v127, v53
	v_fmac_f32_e32 v48, v136, v47
	s_waitcnt lgkmcnt(1)
	v_lshlrev_b32_e32 v65, 16, v65
	v_fmac_f32_e32 v34, v136, v33
	v_fmac_f32_e32 v49, v122, v58
	v_fmac_f32_e32 v35, v122, v44
	v_fmac_f32_e32 v50, v116, v55
	v_fmac_f32_e32 v36, v116, v41
	v_fmac_f32_e32 v51, v110, v53
	v_fmac_f32_e32 v37, v110, v39
	v_fmac_f32_e32 v48, v137, v33
	s_waitcnt lgkmcnt(0)
	v_lshlrev_b32_e32 v64, 16, v64
	v_fmac_f32_e32 v34, v137, v65
	v_fmac_f32_e32 v49, v123, v44
	v_fmac_f32_e32 v35, v123, v59
	v_fmac_f32_e32 v50, v117, v41
	v_fmac_f32_e32 v36, v117, v56
	v_fmac_f32_e32 v51, v111, v39
	v_fmac_f32_e32 v37, v111, v54
	v_fmac_f32_e32 v48, v139, v65
	v_fmac_f32_e32 v34, v139, v64
	v_fmac_f32_e32 v49, v124, v59
	v_fmac_f32_e32 v35, v124, v45
	v_fmac_f32_e32 v50, v118, v56
	v_fmac_f32_e32 v36, v118, v42
	v_fmac_f32_e32 v51, v112, v54
	v_fmac_f32_e32 v37, v112, v40
	ds_write2st64_b32 v29, v48, v34 offset1:8
	v_fmac_f32_e32 v49, v132, v45
	v_fmac_f32_e32 v35, v132, v60
	v_fmac_f32_e32 v50, v130, v42
	v_fmac_f32_e32 v36, v130, v57
	v_fmac_f32_e32 v51, v128, v40
	v_fmac_f32_e32 v37, v128, v62
	v_fma_f32 v52, v125, v52, v140
	v_fmac_f32_e32 v49, v133, v60
	ds_read_u16 v48, v63 offset:32768
	ds_read_u16 v34, v63 offset:33792
	v_fmac_f32_e32 v35, v133, v46
	v_fmac_f32_e32 v50, v119, v57
	v_fmac_f32_e32 v36, v119, v43
	v_fmac_f32_e32 v51, v113, v62
	v_fmac_f32_e32 v37, v113, v61
	v_fmac_f32_e32 v52, v126, v38
	v_fma_f32 v38, v125, v38, v140
	v_fmac_f32_e32 v49, v134, v46
	v_fmac_f32_e32 v35, v134, v47
	v_fmac_f32_e32 v50, v120, v43
	v_fmac_f32_e32 v36, v120, v58
	v_fmac_f32_e32 v51, v114, v61
	v_fmac_f32_e32 v37, v114, v55
	v_fmac_f32_e32 v38, v126, v53
	v_fmac_f32_e32 v49, v135, v47
	v_fmac_f32_e32 v35, v135, v33
	v_fmac_f32_e32 v50, v121, v58
	v_fmac_f32_e32 v36, v121, v44
	v_fmac_f32_e32 v51, v115, v55
	v_fmac_f32_e32 v37, v115, v41
	v_fmac_f32_e32 v52, v109, v53
	v_fmac_f32_e32 v38, v109, v39
	v_fmac_f32_e32 v49, v138, v33
	v_fmac_f32_e32 v35, v138, v65
	v_fmac_f32_e32 v50, v131, v44
	v_fmac_f32_e32 v36, v131, v59
	v_fmac_f32_e32 v51, v129, v41
	v_fmac_f32_e32 v37, v129, v56
	v_fmac_f32_e32 v52, v127, v39
	v_fmac_f32_e32 v38, v127, v54
	v_fmac_f32_e32 v49, v136, v65
	s_waitcnt lgkmcnt(1)
	v_lshlrev_b32_e32 v48, 16, v48
	v_fmac_f32_e32 v35, v136, v64
	v_fmac_f32_e32 v50, v122, v59
	v_fmac_f32_e32 v36, v122, v45
	v_fmac_f32_e32 v51, v116, v56
	v_fmac_f32_e32 v37, v116, v42
	v_fmac_f32_e32 v52, v110, v54
	v_fmac_f32_e32 v38, v110, v40
	v_fmac_f32_e32 v49, v137, v64
	s_waitcnt lgkmcnt(0)
	v_lshlrev_b32_e32 v34, 16, v34
	v_fmac_f32_e32 v35, v137, v48
	v_fmac_f32_e32 v50, v123, v45
	v_fmac_f32_e32 v36, v123, v60
	v_fmac_f32_e32 v51, v117, v42
	v_fmac_f32_e32 v37, v117, v57
	v_fmac_f32_e32 v52, v111, v40
	v_fmac_f32_e32 v38, v111, v62
	v_fmac_f32_e32 v49, v139, v48
	v_fmac_f32_e32 v35, v139, v34
	v_fmac_f32_e32 v50, v124, v60
	v_fmac_f32_e32 v36, v124, v46
	v_fmac_f32_e32 v51, v118, v57
	v_fmac_f32_e32 v37, v118, v43
	v_fmac_f32_e32 v52, v112, v62
	v_fmac_f32_e32 v38, v112, v61
	ds_write2st64_b32 v29, v49, v35 offset0:16 offset1:24
	v_fmac_f32_e32 v50, v132, v46
	v_fmac_f32_e32 v36, v132, v47
	v_fmac_f32_e32 v51, v130, v43
	v_fmac_f32_e32 v37, v130, v58
	v_fmac_f32_e32 v52, v128, v61
	v_fmac_f32_e32 v38, v128, v55
	v_fma_f32 v53, v125, v53, v140
	v_fmac_f32_e32 v50, v133, v47
	ds_read_u16 v49, v63 offset:34816
	ds_read_u16 v35, v63 offset:35840
	v_fmac_f32_e32 v36, v133, v33
	v_fmac_f32_e32 v51, v119, v58
	v_fmac_f32_e32 v37, v119, v44
	v_fmac_f32_e32 v52, v113, v55
	v_fmac_f32_e32 v38, v113, v41
	v_fmac_f32_e32 v53, v126, v39
	v_fma_f32 v39, v125, v39, v140
	v_fmac_f32_e32 v50, v134, v33
	v_fmac_f32_e32 v36, v134, v65
	v_fmac_f32_e32 v51, v120, v44
	v_fmac_f32_e32 v37, v120, v59
	v_fmac_f32_e32 v52, v114, v41
	v_fmac_f32_e32 v38, v114, v56
	v_fmac_f32_e32 v39, v126, v54
	v_fmac_f32_e32 v50, v135, v65
	v_fmac_f32_e32 v36, v135, v64
	v_fmac_f32_e32 v51, v121, v59
	v_fmac_f32_e32 v37, v121, v45
	v_fmac_f32_e32 v52, v115, v56
	v_fmac_f32_e32 v38, v115, v42
	v_fmac_f32_e32 v53, v109, v54
	v_fmac_f32_e32 v39, v109, v40
	v_fmac_f32_e32 v50, v138, v64
	v_fmac_f32_e32 v36, v138, v48
	v_fmac_f32_e32 v51, v131, v45
	v_fmac_f32_e32 v37, v131, v60
	v_fmac_f32_e32 v52, v129, v42
	v_fmac_f32_e32 v38, v129, v57
	v_fmac_f32_e32 v53, v127, v40
	v_fmac_f32_e32 v39, v127, v62
	v_fmac_f32_e32 v50, v136, v48
	s_waitcnt lgkmcnt(1)
	v_lshlrev_b32_e32 v49, 16, v49
	v_fmac_f32_e32 v36, v136, v34
	v_fmac_f32_e32 v51, v122, v60
	v_fmac_f32_e32 v37, v122, v46
	v_fmac_f32_e32 v52, v116, v57
	v_fmac_f32_e32 v38, v116, v43
	v_fmac_f32_e32 v53, v110, v62
	v_fmac_f32_e32 v39, v110, v61
	v_fmac_f32_e32 v50, v137, v34
	s_waitcnt lgkmcnt(0)
	v_lshlrev_b32_e32 v35, 16, v35
	v_fmac_f32_e32 v36, v137, v49
	v_fmac_f32_e32 v51, v123, v46
	v_fmac_f32_e32 v37, v123, v47
	v_fmac_f32_e32 v52, v117, v43
	v_fmac_f32_e32 v38, v117, v58
	v_fmac_f32_e32 v53, v111, v61
	v_fmac_f32_e32 v39, v111, v55
	v_fmac_f32_e32 v50, v139, v49
	v_fmac_f32_e32 v36, v139, v35
	v_fmac_f32_e32 v51, v124, v47
	v_fmac_f32_e32 v37, v124, v33
	v_fmac_f32_e32 v52, v118, v58
	v_fmac_f32_e32 v38, v118, v44
	v_fmac_f32_e32 v53, v112, v55
	v_fmac_f32_e32 v39, v112, v41
	ds_write2st64_b32 v29, v50, v36 offset0:32 offset1:40
	v_fmac_f32_e32 v51, v132, v33
	v_fmac_f32_e32 v37, v132, v65
	v_fmac_f32_e32 v52, v130, v44
	v_fmac_f32_e32 v38, v130, v59
	v_fmac_f32_e32 v53, v128, v41
	v_fmac_f32_e32 v39, v128, v56
	v_fma_f32 v54, v125, v54, v140
	v_fmac_f32_e32 v51, v133, v65
	ds_read_u16 v50, v63 offset:36864
	ds_read_u16 v36, v63 offset:37888
	v_fmac_f32_e32 v37, v133, v64
	v_fmac_f32_e32 v52, v119, v59
	v_fmac_f32_e32 v38, v119, v45
	v_fmac_f32_e32 v53, v113, v56
	v_fmac_f32_e32 v39, v113, v42
	v_fmac_f32_e32 v54, v126, v40
	v_fma_f32 v40, v125, v40, v140
	v_fmac_f32_e32 v51, v134, v64
	v_fmac_f32_e32 v37, v134, v48
	v_fmac_f32_e32 v52, v120, v45
	v_fmac_f32_e32 v38, v120, v60
	v_fmac_f32_e32 v53, v114, v42
	v_fmac_f32_e32 v39, v114, v57
	v_fmac_f32_e32 v40, v126, v62
	v_fmac_f32_e32 v51, v135, v48
	v_fmac_f32_e32 v37, v135, v34
	v_fmac_f32_e32 v52, v121, v60
	v_fmac_f32_e32 v38, v121, v46
	v_fmac_f32_e32 v53, v115, v57
	v_fmac_f32_e32 v39, v115, v43
	v_fmac_f32_e32 v54, v109, v62
	v_fmac_f32_e32 v40, v109, v61
	v_fmac_f32_e32 v51, v138, v34
	v_fmac_f32_e32 v37, v138, v49
	v_fmac_f32_e32 v52, v131, v46
	v_fmac_f32_e32 v38, v131, v47
	v_fmac_f32_e32 v53, v129, v43
	v_fmac_f32_e32 v39, v129, v58
	v_fmac_f32_e32 v54, v127, v61
	v_fmac_f32_e32 v40, v127, v55
	v_fmac_f32_e32 v51, v136, v49
	s_waitcnt lgkmcnt(1)
	v_lshlrev_b32_e32 v50, 16, v50
	v_fmac_f32_e32 v37, v136, v35
	v_fmac_f32_e32 v52, v122, v47
	v_fmac_f32_e32 v38, v122, v33
	v_fmac_f32_e32 v53, v116, v58
	v_fmac_f32_e32 v39, v116, v44
	v_fmac_f32_e32 v54, v110, v55
	v_fmac_f32_e32 v40, v110, v41
	v_fmac_f32_e32 v51, v137, v35
	s_waitcnt lgkmcnt(0)
	v_lshlrev_b32_e32 v36, 16, v36
	v_fmac_f32_e32 v37, v137, v50
	v_fmac_f32_e32 v52, v123, v33
	v_fmac_f32_e32 v38, v123, v65
	v_fmac_f32_e32 v53, v117, v44
	v_fmac_f32_e32 v39, v117, v59
	v_fmac_f32_e32 v54, v111, v41
	v_fmac_f32_e32 v40, v111, v56
	v_fmac_f32_e32 v51, v139, v50
	v_fmac_f32_e32 v37, v139, v36
	v_fmac_f32_e32 v52, v124, v65
	v_fmac_f32_e32 v38, v124, v64
	v_fmac_f32_e32 v53, v118, v59
	v_fmac_f32_e32 v39, v118, v45
	v_fmac_f32_e32 v54, v112, v56
	v_fmac_f32_e32 v40, v112, v42
	ds_write2st64_b32 v29, v51, v37 offset0:48 offset1:56
	v_fmac_f32_e32 v52, v132, v64
	v_fmac_f32_e32 v38, v132, v48
	v_fmac_f32_e32 v53, v130, v45
	v_fmac_f32_e32 v39, v130, v60
	v_fmac_f32_e32 v54, v128, v42
	v_fmac_f32_e32 v40, v128, v57
	v_fma_f32 v62, v125, v62, v140
	v_fmac_f32_e32 v52, v133, v48
	ds_read_u16 v51, v63 offset:38912
	ds_read_u16 v37, v63 offset:39936
	v_fmac_f32_e32 v38, v133, v34
	v_fmac_f32_e32 v53, v119, v60
	v_fmac_f32_e32 v39, v119, v46
	v_fmac_f32_e32 v54, v113, v57
	v_fmac_f32_e32 v40, v113, v43
	v_fmac_f32_e32 v62, v126, v61
	v_fma_f32 v61, v125, v61, v140
	v_fmac_f32_e32 v52, v134, v34
	v_fmac_f32_e32 v38, v134, v49
	v_fmac_f32_e32 v53, v120, v46
	v_fmac_f32_e32 v39, v120, v47
	v_fmac_f32_e32 v54, v114, v43
	v_fmac_f32_e32 v40, v114, v58
	v_fmac_f32_e32 v61, v126, v55
	v_fmac_f32_e32 v52, v135, v49
	v_fmac_f32_e32 v38, v135, v35
	v_fmac_f32_e32 v53, v121, v47
	v_fmac_f32_e32 v39, v121, v33
	v_fmac_f32_e32 v54, v115, v58
	v_fmac_f32_e32 v40, v115, v44
	v_fmac_f32_e32 v62, v109, v55
	v_fmac_f32_e32 v61, v109, v41
	v_fmac_f32_e32 v52, v138, v35
	v_fmac_f32_e32 v38, v138, v50
	v_fmac_f32_e32 v53, v131, v33
	v_fmac_f32_e32 v39, v131, v65
	v_fmac_f32_e32 v54, v129, v44
	v_fmac_f32_e32 v40, v129, v59
	v_fmac_f32_e32 v62, v127, v41
	v_fmac_f32_e32 v61, v127, v56
	v_fmac_f32_e32 v52, v136, v50
	s_waitcnt lgkmcnt(1)
	v_lshlrev_b32_e32 v51, 16, v51
	v_fmac_f32_e32 v38, v136, v36
	v_fmac_f32_e32 v53, v122, v65
	v_fmac_f32_e32 v39, v122, v64
	v_fmac_f32_e32 v54, v116, v59
	v_fmac_f32_e32 v40, v116, v45
	v_fmac_f32_e32 v62, v110, v56
	v_fmac_f32_e32 v61, v110, v42
	v_fmac_f32_e32 v52, v137, v36
	s_waitcnt lgkmcnt(0)
	v_lshlrev_b32_e32 v37, 16, v37
	v_fmac_f32_e32 v38, v137, v51
	v_fmac_f32_e32 v53, v123, v64
	v_fmac_f32_e32 v39, v123, v48
	v_fmac_f32_e32 v54, v117, v45
	v_fmac_f32_e32 v40, v117, v60
	v_fmac_f32_e32 v62, v111, v42
	v_fmac_f32_e32 v61, v111, v57
	v_fmac_f32_e32 v52, v139, v51
	v_fmac_f32_e32 v38, v139, v37
	v_fmac_f32_e32 v53, v124, v48
	v_fmac_f32_e32 v39, v124, v34
	v_fmac_f32_e32 v54, v118, v60
	v_fmac_f32_e32 v40, v118, v46
	v_fmac_f32_e32 v62, v112, v57
	v_fmac_f32_e32 v61, v112, v43
	ds_write2st64_b32 v29, v52, v38 offset0:64 offset1:72
	v_fmac_f32_e32 v53, v132, v34
	v_fmac_f32_e32 v39, v132, v49
	v_fmac_f32_e32 v54, v130, v46
	v_fmac_f32_e32 v40, v130, v47
	v_fmac_f32_e32 v62, v128, v43
	v_fmac_f32_e32 v61, v128, v58
	v_fmac_f32_e32 v53, v133, v49
	ds_read_u16 v52, v63 offset:40960
	ds_read_u16 v38, v63 offset:41984
	v_fmac_f32_e32 v39, v133, v35
	v_fmac_f32_e32 v54, v119, v47
	v_fmac_f32_e32 v40, v119, v33
	v_fmac_f32_e32 v62, v113, v58
	v_fmac_f32_e32 v61, v113, v44
	v_fmac_f32_e32 v53, v134, v35
	v_fmac_f32_e32 v39, v134, v50
	v_fmac_f32_e32 v54, v120, v33
	v_fmac_f32_e32 v40, v120, v65
	v_fmac_f32_e32 v62, v114, v44
	v_fmac_f32_e32 v61, v114, v59
	v_fmac_f32_e32 v53, v135, v50
	v_fmac_f32_e32 v39, v135, v36
	v_fmac_f32_e32 v54, v121, v65
	v_fmac_f32_e32 v40, v121, v64
	v_fmac_f32_e32 v62, v115, v59
	v_fmac_f32_e32 v61, v115, v45
	v_fmac_f32_e32 v53, v138, v36
	v_fmac_f32_e32 v39, v138, v51
	v_fmac_f32_e32 v54, v131, v64
	v_fmac_f32_e32 v40, v131, v48
	v_fmac_f32_e32 v62, v129, v45
	v_fmac_f32_e32 v61, v129, v60
	v_fmac_f32_e32 v53, v136, v51
	s_waitcnt lgkmcnt(1)
	v_lshlrev_b32_e32 v52, 16, v52
	v_fmac_f32_e32 v39, v136, v37
	v_fmac_f32_e32 v54, v122, v48
	v_fmac_f32_e32 v40, v122, v34
	v_fmac_f32_e32 v62, v116, v60
	v_fmac_f32_e32 v61, v116, v46
	v_fmac_f32_e32 v53, v137, v37
	s_waitcnt lgkmcnt(0)
	v_lshlrev_b32_e32 v38, 16, v38
	v_fmac_f32_e32 v39, v137, v52
	v_fmac_f32_e32 v54, v123, v34
	v_fmac_f32_e32 v40, v123, v49
	v_fmac_f32_e32 v62, v117, v46
	v_fmac_f32_e32 v61, v117, v47
	v_fmac_f32_e32 v53, v139, v52
	v_fmac_f32_e32 v39, v139, v38
	v_fmac_f32_e32 v54, v124, v49
	v_fmac_f32_e32 v40, v124, v35
	v_fmac_f32_e32 v62, v118, v47
	v_fmac_f32_e32 v61, v118, v33
	ds_write2st64_b32 v29, v53, v39 offset0:80 offset1:88
	v_fmac_f32_e32 v54, v132, v35
	v_fmac_f32_e32 v40, v132, v50
	v_fmac_f32_e32 v62, v130, v33
	v_fmac_f32_e32 v61, v130, v65
	v_fmac_f32_e32 v54, v133, v50
	ds_read_u16 v53, v63 offset:43008
	ds_read_u16 v39, v63 offset:44032
	v_fmac_f32_e32 v40, v133, v36
	v_fmac_f32_e32 v62, v119, v65
	v_fmac_f32_e32 v61, v119, v64
	v_fmac_f32_e32 v54, v134, v36
	v_fmac_f32_e32 v40, v134, v51
	v_fmac_f32_e32 v62, v120, v64
	v_fmac_f32_e32 v61, v120, v48
	v_fmac_f32_e32 v54, v135, v51
	v_fmac_f32_e32 v40, v135, v37
	v_fmac_f32_e32 v62, v121, v48
	v_fmac_f32_e32 v61, v121, v34
	v_fmac_f32_e32 v54, v138, v37
	v_fmac_f32_e32 v40, v138, v52
	v_fmac_f32_e32 v62, v131, v34
	v_fmac_f32_e32 v61, v131, v49
	v_fmac_f32_e32 v54, v136, v52
	s_waitcnt lgkmcnt(1)
	v_lshlrev_b32_e32 v53, 16, v53
	v_fmac_f32_e32 v40, v136, v38
	v_fmac_f32_e32 v62, v122, v49
	v_fmac_f32_e32 v61, v122, v35
	v_fmac_f32_e32 v54, v137, v38
	s_waitcnt lgkmcnt(0)
	v_lshlrev_b32_e32 v39, 16, v39
	v_fmac_f32_e32 v40, v137, v53
	v_fmac_f32_e32 v62, v123, v35
	v_fmac_f32_e32 v61, v123, v50
	v_fmac_f32_e32 v54, v139, v53
	v_fmac_f32_e32 v40, v139, v39
	v_fmac_f32_e32 v62, v124, v50
	v_fmac_f32_e32 v61, v124, v36
	ds_write2st64_b32 v29, v54, v40 offset0:96 offset1:104
	v_fmac_f32_e32 v62, v132, v36
	v_fmac_f32_e32 v61, v132, v51
	v_fmac_f32_e32 v62, v133, v51
	ds_read_u16 v54, v63 offset:45056
	ds_read_u16 v40, v63 offset:46080
	v_fmac_f32_e32 v61, v133, v37
	v_fmac_f32_e32 v62, v134, v37
	v_fmac_f32_e32 v61, v134, v52
	v_fmac_f32_e32 v62, v135, v52
	v_fmac_f32_e32 v61, v135, v38
	v_fmac_f32_e32 v62, v138, v38
	v_fmac_f32_e32 v61, v138, v53
	v_fmac_f32_e32 v62, v136, v53
	s_waitcnt lgkmcnt(1)
	v_lshlrev_b32_e32 v54, 16, v54
	v_fmac_f32_e32 v61, v136, v39
	v_fmac_f32_e32 v62, v137, v39
	s_waitcnt lgkmcnt(0)
	v_lshlrev_b32_e32 v40, 16, v40
	v_fmac_f32_e32 v61, v137, v54
	v_fmac_f32_e32 v62, v139, v54
	v_fmac_f32_e32 v61, v139, v40
	ds_write2st64_b32 v29, v62, v61 offset0:112 offset1:120
	s_waitcnt lgkmcnt(0)
	s_barrier
	ds_read_b128 v[68:71], v31
	ds_read_b128 v[72:75], v31 offset:16
	s_waitcnt lgkmcnt(1)
	v_add_f32_e32 v61, 0, v68
	v_add_f32_e32 v61, v69, v61
	v_add_f32_e32 v61, v70, v61
	v_add_f32_e32 v61, v71, v61
	s_waitcnt lgkmcnt(0)
	v_add_f32_e32 v61, v72, v61
	v_add_f32_e32 v61, v73, v61
	v_add_f32_e32 v61, v74, v61
	v_add_f32_e32 v61, v75, v61
	s_nop 1
	v_add_f32_dpp v61, v61, v61 quad_perm:[1,0,3,2] row_mask:0xf bank_mask:0xf bound_ctrl:1
	s_nop 1
	v_add_f32_dpp v61, v61, v61 quad_perm:[2,3,0,1] row_mask:0xf bank_mask:0xf bound_ctrl:1
	s_nop 1
	v_add_f32_dpp v61, v61, v61 row_half_mirror row_mask:0xf bank_mask:0xf bound_ctrl:1
	s_nop 1
	v_add_f32_dpp v61, v61, v61 row_mirror row_mask:0xf bank_mask:0xf bound_ctrl:1
	s_nop 0
	v_readlane_b32 s6, v61, 16
	v_readlane_b32 s7, v61, 48
	v_readlane_b32 s4, v61, 0
	v_readlane_b32 s5, v61, 32
	v_mov_b32_e32 v76, s6
	v_mov_b32_e32 v77, s7
	v_pk_add_f32 v[76:77], s[4:5], v[76:77]
	s_nop 0
	v_add_f32_e32 v61, v76, v77
	v_mul_f32_e32 v62, 0x3b000000, v61
	v_fmamk_f32 v67, v61, 0xbb000000, v68
	v_fmamk_f32 v61, v61, 0xbb000000, v69
	v_mul_f32_e32 v76, v61, v61
	v_pk_add_f32 v[68:69], v[70:71], v[62:63] op_sel_hi:[1,0] neg_lo:[0,1] neg_hi:[0,1]
	v_fmac_f32_e32 v76, v67, v67
	v_pk_mul_f32 v[70:71], v[68:69], v[68:69]
	s_nop 0
	v_add_f32_e32 v70, v70, v76
	v_add_f32_e32 v76, v71, v70
	v_pk_add_f32 v[70:71], v[72:73], v[62:63] op_sel_hi:[1,0] neg_lo:[0,1] neg_hi:[0,1]
	s_nop 0
	v_pk_mul_f32 v[72:73], v[70:71], v[70:71]
	s_nop 0
	v_add_f32_e32 v72, v72, v76
	v_add_f32_e32 v76, v73, v72
	v_pk_add_f32 v[72:73], v[74:75], v[62:63] op_sel_hi:[1,0] neg_lo:[0,1] neg_hi:[0,1]
	s_nop 0
	v_pk_mul_f32 v[74:75], v[72:73], v[72:73]
	s_nop 0
	v_add_f32_e32 v62, v74, v76
	v_add_f32_e32 v62, v75, v62
	s_nop 1
	v_add_f32_dpp v62, v62, v62 quad_perm:[1,0,3,2] row_mask:0xf bank_mask:0xf bound_ctrl:1
	s_nop 1
	v_add_f32_dpp v62, v62, v62 quad_perm:[2,3,0,1] row_mask:0xf bank_mask:0xf bound_ctrl:1
	s_nop 1
	v_add_f32_dpp v62, v62, v62 row_half_mirror row_mask:0xf bank_mask:0xf bound_ctrl:1
	s_nop 1
	v_add_f32_dpp v62, v62, v62 row_mirror row_mask:0xf bank_mask:0xf bound_ctrl:1
	s_nop 0
	v_readlane_b32 s6, v62, 16
	v_readlane_b32 s7, v62, 48
	v_readlane_b32 s4, v62, 0
	v_readlane_b32 s5, v62, 32
	v_mov_b32_e32 v74, s6
	v_mov_b32_e32 v75, s7
	v_pk_add_f32 v[74:75], s[4:5], v[74:75]
	s_nop 0
	v_add_f32_e32 v62, v74, v75
	v_fmamk_f32 v62, v62, 0x3b000000, v176
	v_rsq_f32_e32 v62, v62
	s_nop 0
	v_mul_f32_e32 v67, v67, v62
	v_fma_f32 v75, v4, v67, v12
	v_mul_f32_e32 v67, 0xbfb8aa3b, v75
	v_exp_f32_e32 v67, v67
	s_waitcnt vmcnt(1)
	v_lshlrev_b32_e32 v76, 16, v20
	v_mul_f32_e32 v61, v61, v62
	v_add_f32_e32 v67, 1.0, v67
	v_rcp_f32_e32 v77, v67
	v_mul_f32_e32 v67, 0xbfb8aa3b, v76
	v_exp_f32_e32 v67, v67
	s_nop 0
	v_add_f32_e32 v67, 1.0, v67
	v_rcp_f32_e32 v74, v67
	s_nop 0
	v_pk_mul_f32 v[74:75], v[74:75], v[76:77]
	s_nop 0
	v_mul_f32_e32 v67, v74, v75
	v_fma_f32 v75, v5, v61, v13
	v_and_b32_e32 v76, 0xffff0000, v20
	v_mul_f32_e32 v61, 0xbfb8aa3b, v75
	v_mul_f32_e32 v20, 0xbfb8aa3b, v76
	v_exp_f32_e32 v61, v61
	v_exp_f32_e32 v20, v20
	v_add_f32_e32 v61, 1.0, v61
	v_add_f32_e32 v20, 1.0, v20
	v_rcp_f32_e32 v77, v61
	v_rcp_f32_e32 v74, v20
	v_mul_f32_e32 v61, v68, v62
	v_pk_mul_f32 v[74:75], v[74:75], v[76:77]
	s_nop 0
	v_mul_f32_e32 v20, v74, v75
	v_fma_f32 v75, v6, v61, v14
	v_mul_f32_e32 v61, 0xbfb8aa3b, v75
	v_exp_f32_e32 v61, v61
	v_lshlrev_b32_e32 v76, 16, v21
	v_cvt_pk_bf16_f32 v20, v67, v20
	v_mul_f32_e32 v67, v69, v62
	v_add_f32_e32 v61, 1.0, v61
	v_rcp_f32_e32 v77, v61
	v_mul_f32_e32 v61, 0xbfb8aa3b, v76
	v_exp_f32_e32 v61, v61
	v_fma_f32 v69, v7, v67, v15
	v_mul_f32_e32 v67, 0xbfb8aa3b, v69
	v_exp_f32_e32 v67, v67
	v_add_f32_e32 v61, 1.0, v61
	v_rcp_f32_e32 v74, v61
	v_add_f32_e32 v67, 1.0, v67
	v_pk_mul_f32 v[74:75], v[74:75], v[76:77]
	s_nop 0
	v_mul_f32_e32 v61, v74, v75
	v_and_b32_e32 v74, 0xffff0000, v21
	v_mul_f32_e32 v21, 0xbfb8aa3b, v74
	v_exp_f32_e32 v21, v21
	v_rcp_f32_e32 v75, v67
	v_mul_f32_e32 v67, v71, v62
	v_add_f32_e32 v21, 1.0, v21
	v_rcp_f32_e32 v68, v21
	s_nop 0
	v_pk_mul_f32 v[68:69], v[68:69], v[74:75]
	s_nop 0
	v_mul_f32_e32 v21, v68, v69
	v_cvt_pk_bf16_f32 v21, v61, v21
	v_mul_f32_e32 v61, v70, v62
	v_fma_f32 v69, v0, v61, v8
	v_mul_f32_e32 v61, 0xbfb8aa3b, v69
	v_exp_f32_e32 v61, v61
	v_lshlrev_b32_e32 v74, 16, v22
	v_and_b32_e32 v70, 0xffff0000, v22
	v_mul_f32_e32 v22, 0xbfb8aa3b, v70
	v_add_f32_e32 v61, 1.0, v61
	v_rcp_f32_e32 v75, v61
	v_mul_f32_e32 v61, 0xbfb8aa3b, v74
	v_exp_f32_e32 v61, v61
	v_exp_f32_e32 v22, v22
	v_add_f32_e32 v61, 1.0, v61
	v_rcp_f32_e32 v68, v61
	v_add_f32_e32 v22, 1.0, v22
	v_pk_mul_f32 v[68:69], v[68:69], v[74:75]
	s_nop 0
	v_mul_f32_e32 v61, v68, v69
	v_fma_f32 v69, v1, v67, v9
	v_mul_f32_e32 v67, 0xbfb8aa3b, v69
	v_exp_f32_e32 v67, v67
	v_rcp_f32_e32 v68, v22
	v_add_f32_e32 v67, 1.0, v67
	v_rcp_f32_e32 v71, v67
	s_nop 0
	v_pk_mul_f32 v[68:69], v[68:69], v[70:71]
	s_nop 0
	v_mul_f32_e32 v22, v68, v69
	v_cvt_pk_bf16_f32 v22, v61, v22
	v_mul_f32_e32 v61, v72, v62
	v_fma_f32 v69, v2, v61, v10
	v_mul_f32_e32 v61, 0xbfb8aa3b, v69
	v_exp_f32_e32 v61, v61
	v_lshlrev_b32_e32 v70, 16, v23
	v_mul_f32_e32 v62, v73, v62
	v_add_f32_e32 v61, 1.0, v61
	v_rcp_f32_e32 v71, v61
	v_mul_f32_e32 v61, 0xbfb8aa3b, v70
	v_exp_f32_e32 v61, v61
	s_nop 0
	v_add_f32_e32 v61, 1.0, v61
	v_rcp_f32_e32 v68, v61
	s_nop 0
	v_pk_mul_f32 v[68:69], v[68:69], v[70:71]
	s_nop 0
	v_mul_f32_e32 v61, v68, v69
	v_fma_f32 v69, v3, v62, v11
	v_and_b32_e32 v70, 0xffff0000, v23
	v_mul_f32_e32 v62, 0xbfb8aa3b, v69
	v_mul_f32_e32 v23, 0xbfb8aa3b, v70
	v_exp_f32_e32 v62, v62
	v_exp_f32_e32 v23, v23
	v_add_f32_e32 v62, 1.0, v62
	v_add_f32_e32 v23, 1.0, v23
	v_rcp_f32_e32 v71, v62
	v_rcp_f32_e32 v68, v23
	s_nop 0
	v_pk_mul_f32 v[68:69], v[68:69], v[70:71]
	s_nop 0
	v_mul_f32_e32 v23, v68, v69
	v_add_u32_e32 v68, s83, v27
	v_ashrrev_i32_e32 v69, 31, v68
	v_lshlrev_b64 v[68:69], 12, v[68:69]
	v_lshl_add_u64 v[68:69], s[44:45], 0, v[68:69]
	v_lshl_add_u64 v[68:69], v[68:69], 0, v[144:145]
	v_add_co_u32_e32 v68, vcc, s89, v68
	v_cvt_pk_bf16_f32 v23, v61, v23
	s_nop 1
	v_addc_co_u32_e32 v69, vcc, 0, v69, vcc
	global_store_dwordx4 v[68:69], v[20:23], off offset:2048
	ds_read_b128 v[20:23], v32
	ds_read_b128 v[68:71], v32 offset:16
	s_waitcnt lgkmcnt(1)
	v_add_f32_e32 v61, 0, v20
	v_add_f32_e32 v61, v21, v61
	v_add_f32_e32 v61, v22, v61
	v_add_f32_e32 v61, v23, v61
	s_waitcnt lgkmcnt(0)
	v_add_f32_e32 v61, v68, v61
	v_add_f32_e32 v61, v69, v61
	v_add_f32_e32 v61, v70, v61
	v_add_f32_e32 v61, v71, v61
	s_nop 1
	v_add_f32_dpp v61, v61, v61 quad_perm:[1,0,3,2] row_mask:0xf bank_mask:0xf bound_ctrl:1
	s_nop 1
	v_add_f32_dpp v61, v61, v61 quad_perm:[2,3,0,1] row_mask:0xf bank_mask:0xf bound_ctrl:1
	s_nop 1
	v_add_f32_dpp v61, v61, v61 row_half_mirror row_mask:0xf bank_mask:0xf bound_ctrl:1
	s_nop 1
	v_add_f32_dpp v61, v61, v61 row_mirror row_mask:0xf bank_mask:0xf bound_ctrl:1
	s_nop 0
	v_readlane_b32 s6, v61, 16
	v_readlane_b32 s7, v61, 48
	v_readlane_b32 s4, v61, 0
	v_readlane_b32 s5, v61, 32
	v_mov_b32_e32 v72, s6
	v_mov_b32_e32 v73, s7
	v_pk_add_f32 v[72:73], s[4:5], v[72:73]
	s_nop 0
	v_add_f32_e32 v61, v72, v73
	v_mul_f32_e32 v62, 0x3b000000, v61
	v_fmamk_f32 v67, v61, 0xbb000000, v20
	v_fmamk_f32 v61, v61, 0xbb000000, v21
	v_mul_f32_e32 v72, v61, v61
	v_pk_add_f32 v[20:21], v[22:23], v[62:63] op_sel_hi:[1,0] neg_lo:[0,1] neg_hi:[0,1]
	v_fmac_f32_e32 v72, v67, v67
	v_pk_mul_f32 v[22:23], v[20:21], v[20:21]
	s_nop 0
	v_add_f32_e32 v22, v22, v72
	v_add_f32_e32 v72, v23, v22
	v_pk_add_f32 v[22:23], v[68:69], v[62:63] op_sel_hi:[1,0] neg_lo:[0,1] neg_hi:[0,1]
	s_nop 0
	v_pk_mul_f32 v[68:69], v[22:23], v[22:23]
	s_nop 0
	v_add_f32_e32 v68, v68, v72
	v_add_f32_e32 v72, v69, v68
	v_pk_add_f32 v[68:69], v[70:71], v[62:63] op_sel_hi:[1,0] neg_lo:[0,1] neg_hi:[0,1]
	s_nop 0
	v_pk_mul_f32 v[70:71], v[68:69], v[68:69]
	s_nop 0
	v_add_f32_e32 v62, v70, v72
	v_add_f32_e32 v62, v71, v62
	s_nop 1
	v_add_f32_dpp v62, v62, v62 quad_perm:[1,0,3,2] row_mask:0xf bank_mask:0xf bound_ctrl:1
	s_nop 1
	v_add_f32_dpp v62, v62, v62 quad_perm:[2,3,0,1] row_mask:0xf bank_mask:0xf bound_ctrl:1
	s_nop 1
	v_add_f32_dpp v62, v62, v62 row_half_mirror row_mask:0xf bank_mask:0xf bound_ctrl:1
	s_nop 1
	v_add_f32_dpp v62, v62, v62 row_mirror row_mask:0xf bank_mask:0xf bound_ctrl:1
	s_nop 0
	v_readlane_b32 s6, v62, 16
	v_readlane_b32 s7, v62, 48
	v_readlane_b32 s4, v62, 0
	v_readlane_b32 s5, v62, 32
	v_mov_b32_e32 v70, s6
	v_mov_b32_e32 v71, s7
	v_pk_add_f32 v[70:71], s[4:5], v[70:71]
	s_nop 0
	v_add_f32_e32 v62, v70, v71
	v_fmamk_f32 v62, v62, 0x3b000000, v176
	v_rsq_f32_e32 v62, v62
	s_nop 0
	v_mul_f32_e32 v67, v67, v62
	v_fma_f32 v71, v4, v67, v12
	v_mul_f32_e32 v67, 0xbfb8aa3b, v71
	v_exp_f32_e32 v67, v67
	s_waitcnt vmcnt(1)
	v_lshlrev_b32_e32 v72, 16, v16
	v_mul_f32_e32 v61, v61, v62
	v_mul_f32_e32 v20, v20, v62
	v_add_f32_e32 v67, 1.0, v67
	v_rcp_f32_e32 v73, v67
	v_mul_f32_e32 v67, 0xbfb8aa3b, v72
	v_exp_f32_e32 v67, v67
	s_nop 0
	v_add_f32_e32 v67, 1.0, v67
	v_rcp_f32_e32 v70, v67
	s_nop 0
	v_pk_mul_f32 v[70:71], v[70:71], v[72:73]
	s_nop 0
	v_mul_f32_e32 v67, v70, v71
	v_fma_f32 v71, v5, v61, v13
	v_and_b32_e32 v72, 0xffff0000, v16
	v_mul_f32_e32 v61, 0xbfb8aa3b, v71
	v_mul_f32_e32 v16, 0xbfb8aa3b, v72
	v_exp_f32_e32 v61, v61
	v_exp_f32_e32 v16, v16
	v_add_f32_e32 v61, 1.0, v61
	v_add_f32_e32 v16, 1.0, v16
	v_rcp_f32_e32 v73, v61
	v_rcp_f32_e32 v70, v16
	s_nop 0
	v_pk_mul_f32 v[70:71], v[70:71], v[72:73]
	s_nop 0
	v_mul_f32_e32 v16, v70, v71
	v_fma_f32 v71, v6, v20, v14
	v_mul_f32_e32 v20, 0xbfb8aa3b, v71
	v_exp_f32_e32 v20, v20
	v_lshlrev_b32_e32 v72, 16, v17
	v_cvt_pk_bf16_f32 v16, v67, v16
	v_add_f32_e32 v20, 1.0, v20
	v_rcp_f32_e32 v73, v20
	v_mul_f32_e32 v20, 0xbfb8aa3b, v72
	v_exp_f32_e32 v20, v20
	s_nop 0
	v_add_f32_e32 v20, 1.0, v20
	v_rcp_f32_e32 v70, v20
	v_mul_f32_e32 v20, v21, v62
	v_fma_f32 v21, v7, v20, v15
	v_mul_f32_e32 v20, 0xbfb8aa3b, v21
	v_pk_mul_f32 v[70:71], v[70:71], v[72:73]
	v_exp_f32_e32 v20, v20
	v_mul_f32_e32 v61, v70, v71
	v_and_b32_e32 v70, 0xffff0000, v17
	v_mul_f32_e32 v17, 0xbfb8aa3b, v70
	v_exp_f32_e32 v17, v17
	v_add_f32_e32 v20, 1.0, v20
	v_rcp_f32_e32 v71, v20
	v_add_f32_e32 v17, 1.0, v17
	v_rcp_f32_e32 v20, v17
	s_nop 0
	v_pk_mul_f32 v[20:21], v[20:21], v[70:71]
	s_nop 0
	v_mul_f32_e32 v17, v20, v21
	v_mul_f32_e32 v20, v22, v62
	v_fma_f32 v21, v0, v20, v8
	v_mul_f32_e32 v20, 0xbfb8aa3b, v21
	v_exp_f32_e32 v20, v20
	v_lshlrev_b32_e32 v70, 16, v18
	v_cvt_pk_bf16_f32 v17, v61, v17
	v_and_b32_e32 v22, 0xffff0000, v18
	v_add_f32_e32 v20, 1.0, v20
	v_rcp_f32_e32 v71, v20
	v_mul_f32_e32 v20, 0xbfb8aa3b, v70
	v_exp_f32_e32 v20, v20
	v_mul_f32_e32 v18, 0xbfb8aa3b, v22
	v_exp_f32_e32 v18, v18
	v_add_f32_e32 v20, 1.0, v20
	v_rcp_f32_e32 v20, v20
	v_add_f32_e32 v18, 1.0, v18
	v_pk_mul_f32 v[20:21], v[20:21], v[70:71]
	s_nop 0
	v_mul_f32_e32 v61, v20, v21
	v_mul_f32_e32 v20, v23, v62
	v_fma_f32 v21, v1, v20, v9
	v_mul_f32_e32 v20, 0xbfb8aa3b, v21
	v_exp_f32_e32 v20, v20
	s_nop 0
	v_add_f32_e32 v20, 1.0, v20
	v_rcp_f32_e32 v23, v20
	v_rcp_f32_e32 v20, v18
	s_nop 0
	v_pk_mul_f32 v[20:21], v[20:21], v[22:23]
	s_nop 0
	v_mul_f32_e32 v18, v20, v21
	v_mul_f32_e32 v20, v68, v62
	v_fma_f32 v21, v2, v20, v10
	v_mul_f32_e32 v20, 0xbfb8aa3b, v21
	v_exp_f32_e32 v20, v20
	v_lshlrev_b32_e32 v22, 16, v19
	v_cvt_pk_bf16_f32 v18, v61, v18
	v_add_f32_e32 v20, 1.0, v20
	v_rcp_f32_e32 v23, v20
	v_mul_f32_e32 v20, 0xbfb8aa3b, v22
	v_exp_f32_e32 v20, v20
	s_nop 0
	v_add_f32_e32 v20, 1.0, v20
	v_rcp_f32_e32 v20, v20
	s_nop 0
	v_pk_mul_f32 v[20:21], v[20:21], v[22:23]
	s_nop 0
	v_mul_f32_e32 v61, v20, v21
	v_mul_f32_e32 v20, v69, v62
	v_fma_f32 v21, v3, v20, v11
	v_and_b32_e32 v22, 0xffff0000, v19
	v_mul_f32_e32 v20, 0xbfb8aa3b, v21
	v_mul_f32_e32 v19, 0xbfb8aa3b, v22
	v_exp_f32_e32 v20, v20
	v_exp_f32_e32 v19, v19
	v_add_f32_e32 v20, 1.0, v20
	v_add_f32_e32 v19, 1.0, v19
	v_rcp_f32_e32 v23, v20
	v_rcp_f32_e32 v20, v19
	s_nop 0
	v_pk_mul_f32 v[20:21], v[20:21], v[22:23]
	s_nop 0
	v_mul_f32_e32 v19, v20, v21
	v_add_u32_e32 v20, s83, v30
	v_ashrrev_i32_e32 v21, 31, v20
	v_lshlrev_b64 v[20:21], 12, v[20:21]
	v_lshl_add_u64 v[20:21], s[44:45], 0, v[20:21]
	v_lshl_add_u64 v[20:21], v[20:21], 0, v[144:145]
	v_add_co_u32_e32 v20, vcc, s89, v20
	v_cvt_pk_bf16_f32 v19, v61, v19
	s_nop 1
	v_addc_co_u32_e32 v21, vcc, 0, v21, vcc
	global_store_dwordx4 v[20:21], v[16:19], off offset:2048
	s_barrier
	s_nop 0
	v_add_u32_e32 v16, 16, v66
	v_mad_i64_i32 v[16:17], s[4:5], v16, s62, v[24:25]
	v_lshl_add_u64 v[16:17], v[16:17], 0, v[144:145]
	v_add_co_u32_e32 v16, vcc, s74, v16
	s_nop 1
	v_addc_co_u32_e32 v17, vcc, 0, v17, vcc
	global_load_dwordx4 v[20:23], v[16:17], off offset:2048
	v_add_u32_e32 v16, 17, v66
	v_mad_i64_i32 v[16:17], s[4:5], v16, s62, v[24:25]
	v_lshl_add_u64 v[16:17], v[16:17], 0, v[144:145]
	v_add_co_u32_e32 v16, vcc, s74, v16
	v_fma_f32 v24, v125, v55, v140
	s_nop 0
	v_addc_co_u32_e32 v17, vcc, 0, v17, vcc
	global_load_dwordx4 v[16:19], v[16:17], off offset:2048
	ds_read_u16 v25, v63 offset:47104
	ds_read_u16 v55, v63 offset:48128
	v_fmac_f32_e32 v24, v126, v41
	v_fmac_f32_e32 v24, v109, v56
	v_fmac_f32_e32 v24, v127, v42
	s_waitcnt lgkmcnt(1)
	v_lshlrev_b32_e32 v62, 16, v25
	v_fma_f32 v25, v125, v41, v140
	v_fmac_f32_e32 v25, v126, v56
	v_fmac_f32_e32 v25, v109, v42
	v_fmac_f32_e32 v25, v127, v57
	v_fmac_f32_e32 v24, v110, v57
	v_fmac_f32_e32 v25, v110, v43
	v_fmac_f32_e32 v24, v111, v43
	v_fmac_f32_e32 v25, v111, v58
	v_fmac_f32_e32 v24, v112, v58
	v_fmac_f32_e32 v25, v112, v44
	v_fmac_f32_e32 v24, v128, v44
	v_fmac_f32_e32 v25, v128, v59
	v_fmac_f32_e32 v24, v113, v59
	v_fmac_f32_e32 v25, v113, v45
	v_fmac_f32_e32 v24, v114, v45
	v_fmac_f32_e32 v25, v114, v60
	v_fmac_f32_e32 v24, v115, v60
	v_fmac_f32_e32 v25, v115, v46
	v_fmac_f32_e32 v24, v129, v46
	v_fmac_f32_e32 v25, v129, v47
	v_fmac_f32_e32 v24, v116, v47
	v_fmac_f32_e32 v25, v116, v33
	v_fmac_f32_e32 v24, v117, v33
	v_fmac_f32_e32 v25, v117, v65
	v_fmac_f32_e32 v24, v118, v65
	v_fmac_f32_e32 v25, v118, v64
	v_fmac_f32_e32 v24, v130, v64
	v_fmac_f32_e32 v25, v130, v48
	v_fmac_f32_e32 v24, v119, v48
	v_fmac_f32_e32 v25, v119, v34
	v_fmac_f32_e32 v24, v120, v34
	v_fmac_f32_e32 v25, v120, v49
	v_fmac_f32_e32 v24, v121, v49
	v_fmac_f32_e32 v25, v121, v35
	v_fmac_f32_e32 v24, v131, v35
	v_fmac_f32_e32 v25, v131, v50
	v_fmac_f32_e32 v24, v122, v50
	v_fmac_f32_e32 v25, v122, v36
	v_fmac_f32_e32 v24, v123, v36
	v_fmac_f32_e32 v25, v123, v51
	v_fmac_f32_e32 v24, v124, v51
	v_fmac_f32_e32 v25, v124, v37
	v_fmac_f32_e32 v24, v132, v37
	v_fmac_f32_e32 v25, v132, v52
	v_fmac_f32_e32 v24, v133, v52
	v_fmac_f32_e32 v25, v133, v38
	v_fmac_f32_e32 v24, v134, v38
	v_fmac_f32_e32 v25, v134, v53
	v_fmac_f32_e32 v24, v135, v53
	v_fmac_f32_e32 v25, v135, v39
	v_fmac_f32_e32 v24, v138, v39
	v_fmac_f32_e32 v25, v138, v54
	v_fmac_f32_e32 v24, v136, v54
	v_fmac_f32_e32 v25, v136, v40
	v_fmac_f32_e32 v24, v137, v40
	s_waitcnt lgkmcnt(0)
	v_lshlrev_b32_e32 v61, 16, v55
	v_fmac_f32_e32 v25, v137, v62
	v_fmac_f32_e32 v24, v139, v62
	v_fmac_f32_e32 v25, v139, v61
	ds_write2st64_b32 v29, v24, v25 offset1:8
	ds_read_u16 v25, v63 offset:49152
	ds_read_u16 v41, v63 offset:50176
	v_fma_f32 v24, v125, v56, v140
	v_fmac_f32_e32 v24, v126, v42
	v_fmac_f32_e32 v24, v109, v57
	s_waitcnt lgkmcnt(1)
	v_lshlrev_b32_e32 v55, 16, v25
	v_fma_f32 v25, v125, v42, v140
	v_fmac_f32_e32 v25, v126, v57
	v_fmac_f32_e32 v25, v109, v43
	v_fmac_f32_e32 v24, v127, v43
	v_fmac_f32_e32 v25, v127, v58
	v_fmac_f32_e32 v24, v110, v58
	v_fmac_f32_e32 v25, v110, v44
	v_fmac_f32_e32 v24, v111, v44
	v_fmac_f32_e32 v25, v111, v59
	v_fmac_f32_e32 v24, v112, v59
	v_fmac_f32_e32 v25, v112, v45
	v_fmac_f32_e32 v24, v128, v45
	v_fmac_f32_e32 v25, v128, v60
	v_fmac_f32_e32 v24, v113, v60
	v_fmac_f32_e32 v25, v113, v46
	v_fmac_f32_e32 v24, v114, v46
	v_fmac_f32_e32 v25, v114, v47
	v_fmac_f32_e32 v24, v115, v47
	v_fmac_f32_e32 v25, v115, v33
	v_fmac_f32_e32 v24, v129, v33
	v_fmac_f32_e32 v25, v129, v65
	v_fmac_f32_e32 v24, v116, v65
	v_fmac_f32_e32 v25, v116, v64
	v_fmac_f32_e32 v24, v117, v64
	v_fmac_f32_e32 v25, v117, v48
	v_fmac_f32_e32 v24, v118, v48
	v_fmac_f32_e32 v25, v118, v34
	v_fmac_f32_e32 v24, v130, v34
	v_fmac_f32_e32 v25, v130, v49
	v_fmac_f32_e32 v24, v119, v49
	v_fmac_f32_e32 v25, v119, v35
	v_fmac_f32_e32 v24, v120, v35
	v_fmac_f32_e32 v25, v120, v50
	v_fmac_f32_e32 v24, v121, v50
	v_fmac_f32_e32 v25, v121, v36
	v_fmac_f32_e32 v24, v131, v36
	v_fmac_f32_e32 v25, v131, v51
	v_fmac_f32_e32 v24, v122, v51
	v_fmac_f32_e32 v25, v122, v37
	v_fmac_f32_e32 v24, v123, v37
	v_fmac_f32_e32 v25, v123, v52
	v_fmac_f32_e32 v24, v124, v52
	v_fmac_f32_e32 v25, v124, v38
	v_fmac_f32_e32 v24, v132, v38
	v_fmac_f32_e32 v25, v132, v53
	v_fmac_f32_e32 v24, v133, v53
	v_fmac_f32_e32 v25, v133, v39
	v_fmac_f32_e32 v24, v134, v39
	v_fmac_f32_e32 v25, v134, v54
	v_fmac_f32_e32 v24, v135, v54
	v_fmac_f32_e32 v25, v135, v40
	v_fmac_f32_e32 v24, v138, v40
	v_fmac_f32_e32 v25, v138, v62
	v_fmac_f32_e32 v24, v136, v62
	v_fmac_f32_e32 v25, v136, v61
	v_fmac_f32_e32 v24, v137, v61
	s_waitcnt lgkmcnt(0)
	v_lshlrev_b32_e32 v41, 16, v41
	v_fmac_f32_e32 v25, v137, v55
	v_fmac_f32_e32 v24, v139, v55
	v_fmac_f32_e32 v25, v139, v41
	ds_write2st64_b32 v29, v24, v25 offset0:16 offset1:24
	ds_read_u16 v25, v63 offset:51200
	ds_read_u16 v42, v63 offset:52224
	v_fma_f32 v24, v125, v57, v140
	v_fmac_f32_e32 v24, v126, v43
	v_fmac_f32_e32 v24, v109, v58
	s_waitcnt lgkmcnt(1)
	v_lshlrev_b32_e32 v56, 16, v25
	v_fma_f32 v25, v125, v43, v140
	v_fmac_f32_e32 v25, v126, v58
	v_fmac_f32_e32 v25, v109, v44
	v_fmac_f32_e32 v24, v127, v44
	v_fmac_f32_e32 v25, v127, v59
	v_fmac_f32_e32 v24, v110, v59
	v_fmac_f32_e32 v25, v110, v45
	v_fmac_f32_e32 v24, v111, v45
	v_fmac_f32_e32 v25, v111, v60
	v_fmac_f32_e32 v24, v112, v60
	v_fmac_f32_e32 v25, v112, v46
	v_fmac_f32_e32 v24, v128, v46
	v_fmac_f32_e32 v25, v128, v47
	v_fmac_f32_e32 v24, v113, v47
	v_fmac_f32_e32 v25, v113, v33
	v_fmac_f32_e32 v24, v114, v33
	v_fmac_f32_e32 v25, v114, v65
	v_fmac_f32_e32 v24, v115, v65
	v_fmac_f32_e32 v25, v115, v64
	v_fmac_f32_e32 v24, v129, v64
	v_fmac_f32_e32 v25, v129, v48
	v_fmac_f32_e32 v24, v116, v48
	v_fmac_f32_e32 v25, v116, v34
	v_fmac_f32_e32 v24, v117, v34
	v_fmac_f32_e32 v25, v117, v49
	v_fmac_f32_e32 v24, v118, v49
	v_fmac_f32_e32 v25, v118, v35
	v_fmac_f32_e32 v24, v130, v35
	v_fmac_f32_e32 v25, v130, v50
	v_fmac_f32_e32 v24, v119, v50
	v_fmac_f32_e32 v25, v119, v36
	v_fmac_f32_e32 v24, v120, v36
	v_fmac_f32_e32 v25, v120, v51
	v_fmac_f32_e32 v24, v121, v51
	v_fmac_f32_e32 v25, v121, v37
	v_fmac_f32_e32 v24, v131, v37
	v_fmac_f32_e32 v25, v131, v52
	v_fmac_f32_e32 v24, v122, v52
	v_fmac_f32_e32 v25, v122, v38
	v_fmac_f32_e32 v24, v123, v38
	v_fmac_f32_e32 v25, v123, v53
	v_fmac_f32_e32 v24, v124, v53
	v_fmac_f32_e32 v25, v124, v39
	v_fmac_f32_e32 v24, v132, v39
	v_fmac_f32_e32 v25, v132, v54
	v_fmac_f32_e32 v24, v133, v54
	v_fmac_f32_e32 v25, v133, v40
	v_fmac_f32_e32 v24, v134, v40
	v_fmac_f32_e32 v25, v134, v62
	v_fmac_f32_e32 v24, v135, v62
	v_fmac_f32_e32 v25, v135, v61
	v_fmac_f32_e32 v24, v138, v61
	v_fmac_f32_e32 v25, v138, v55
	v_fmac_f32_e32 v24, v136, v55
	v_fmac_f32_e32 v25, v136, v41
	v_fmac_f32_e32 v24, v137, v41
	s_waitcnt lgkmcnt(0)
	v_lshlrev_b32_e32 v42, 16, v42
	v_fmac_f32_e32 v25, v137, v56
	v_fmac_f32_e32 v24, v139, v56
	v_fmac_f32_e32 v25, v139, v42
	ds_write2st64_b32 v29, v24, v25 offset0:32 offset1:40
	ds_read_u16 v25, v63 offset:53248
	ds_read_u16 v43, v63 offset:54272
	v_fma_f32 v24, v125, v58, v140
	v_fmac_f32_e32 v24, v126, v44
	v_fmac_f32_e32 v24, v109, v59
	s_waitcnt lgkmcnt(1)
	v_lshlrev_b32_e32 v57, 16, v25
	v_fma_f32 v25, v125, v44, v140
	v_fmac_f32_e32 v25, v126, v59
	v_fmac_f32_e32 v25, v109, v45
	v_fmac_f32_e32 v24, v127, v45
	v_fmac_f32_e32 v25, v127, v60
	v_fmac_f32_e32 v24, v110, v60
	v_fmac_f32_e32 v25, v110, v46
	v_fmac_f32_e32 v24, v111, v46
	v_fmac_f32_e32 v25, v111, v47
	v_fmac_f32_e32 v24, v112, v47
	v_fmac_f32_e32 v25, v112, v33
	v_fmac_f32_e32 v24, v128, v33
	v_fmac_f32_e32 v25, v128, v65
	v_fmac_f32_e32 v24, v113, v65
	v_fmac_f32_e32 v25, v113, v64
	v_fmac_f32_e32 v24, v114, v64
	v_fmac_f32_e32 v25, v114, v48
	v_fmac_f32_e32 v24, v115, v48
	v_fmac_f32_e32 v25, v115, v34
	v_fmac_f32_e32 v24, v129, v34
	v_fmac_f32_e32 v25, v129, v49
	v_fmac_f32_e32 v24, v116, v49
	v_fmac_f32_e32 v25, v116, v35
	v_fmac_f32_e32 v24, v117, v35
	v_fmac_f32_e32 v25, v117, v50
	v_fmac_f32_e32 v24, v118, v50
	v_fmac_f32_e32 v25, v118, v36
	v_fmac_f32_e32 v24, v130, v36
	v_fmac_f32_e32 v25, v130, v51
	v_fmac_f32_e32 v24, v119, v51
	v_fmac_f32_e32 v25, v119, v37
	v_fmac_f32_e32 v24, v120, v37
	v_fmac_f32_e32 v25, v120, v52
	v_fmac_f32_e32 v24, v121, v52
	v_fmac_f32_e32 v25, v121, v38
	v_fmac_f32_e32 v24, v131, v38
	v_fmac_f32_e32 v25, v131, v53
	v_fmac_f32_e32 v24, v122, v53
	v_fmac_f32_e32 v25, v122, v39
	v_fmac_f32_e32 v24, v123, v39
	v_fmac_f32_e32 v25, v123, v54
	v_fmac_f32_e32 v24, v124, v54
	v_fmac_f32_e32 v25, v124, v40
	v_fmac_f32_e32 v24, v132, v40
	v_fmac_f32_e32 v25, v132, v62
	v_fmac_f32_e32 v24, v133, v62
	v_fmac_f32_e32 v25, v133, v61
	v_fmac_f32_e32 v24, v134, v61
	v_fmac_f32_e32 v25, v134, v55
	v_fmac_f32_e32 v24, v135, v55
	v_fmac_f32_e32 v25, v135, v41
	v_fmac_f32_e32 v24, v138, v41
	v_fmac_f32_e32 v25, v138, v56
	v_fmac_f32_e32 v24, v136, v56
	v_fmac_f32_e32 v25, v136, v42
	v_fmac_f32_e32 v24, v137, v42
	s_waitcnt lgkmcnt(0)
	v_lshlrev_b32_e32 v43, 16, v43
	v_fmac_f32_e32 v25, v137, v57
	v_fmac_f32_e32 v24, v139, v57
	v_fmac_f32_e32 v25, v139, v43
	ds_write2st64_b32 v29, v24, v25 offset0:48 offset1:56
	ds_read_u16 v25, v63 offset:55296
	ds_read_u16 v44, v63 offset:56320
	v_fma_f32 v24, v125, v59, v140
	v_fmac_f32_e32 v24, v126, v45
	v_fmac_f32_e32 v24, v109, v60
	s_waitcnt lgkmcnt(1)
	v_lshlrev_b32_e32 v58, 16, v25
	v_fma_f32 v25, v125, v45, v140
	v_fmac_f32_e32 v25, v126, v60
	v_fmac_f32_e32 v25, v109, v46
	v_fmac_f32_e32 v24, v127, v46
	v_fmac_f32_e32 v25, v127, v47
	v_fmac_f32_e32 v24, v110, v47
	v_fmac_f32_e32 v25, v110, v33
	v_fmac_f32_e32 v24, v111, v33
	v_fmac_f32_e32 v25, v111, v65
	v_fmac_f32_e32 v24, v112, v65
	v_fmac_f32_e32 v25, v112, v64
	v_fmac_f32_e32 v24, v128, v64
	v_fmac_f32_e32 v25, v128, v48
	v_fmac_f32_e32 v24, v113, v48
	v_fmac_f32_e32 v25, v113, v34
	v_fmac_f32_e32 v24, v114, v34
	v_fmac_f32_e32 v25, v114, v49
	v_fmac_f32_e32 v24, v115, v49
	v_fmac_f32_e32 v25, v115, v35
	v_fmac_f32_e32 v24, v129, v35
	v_fmac_f32_e32 v25, v129, v50
	v_fmac_f32_e32 v24, v116, v50
	v_fmac_f32_e32 v25, v116, v36
	v_fmac_f32_e32 v24, v117, v36
	v_fmac_f32_e32 v25, v117, v51
	v_fmac_f32_e32 v24, v118, v51
	v_fmac_f32_e32 v25, v118, v37
	v_fmac_f32_e32 v24, v130, v37
	v_fmac_f32_e32 v25, v130, v52
	v_fmac_f32_e32 v24, v119, v52
	v_fmac_f32_e32 v25, v119, v38
	v_fmac_f32_e32 v24, v120, v38
	v_fmac_f32_e32 v25, v120, v53
	v_fmac_f32_e32 v24, v121, v53
	v_fmac_f32_e32 v25, v121, v39
	v_fmac_f32_e32 v24, v131, v39
	v_fmac_f32_e32 v25, v131, v54
	v_fmac_f32_e32 v24, v122, v54
	v_fmac_f32_e32 v25, v122, v40
	v_fmac_f32_e32 v24, v123, v40
	v_fmac_f32_e32 v25, v123, v62
	v_fmac_f32_e32 v24, v124, v62
	v_fmac_f32_e32 v25, v124, v61
	v_fmac_f32_e32 v24, v132, v61
	v_fmac_f32_e32 v25, v132, v55
	v_fmac_f32_e32 v24, v133, v55
	v_fmac_f32_e32 v25, v133, v41
	v_fmac_f32_e32 v24, v134, v41
	v_fmac_f32_e32 v25, v134, v56
	v_fmac_f32_e32 v24, v135, v56
	v_fmac_f32_e32 v25, v135, v42
	v_fmac_f32_e32 v24, v138, v42
	v_fmac_f32_e32 v25, v138, v57
	v_fmac_f32_e32 v24, v136, v57
	v_fmac_f32_e32 v25, v136, v43
	v_fmac_f32_e32 v24, v137, v43
	s_waitcnt lgkmcnt(0)
	v_lshlrev_b32_e32 v44, 16, v44
	v_fmac_f32_e32 v25, v137, v58
	v_fmac_f32_e32 v24, v139, v58
	v_fmac_f32_e32 v25, v139, v44
	ds_write2st64_b32 v29, v24, v25 offset0:64 offset1:72
	ds_read_u16 v25, v63 offset:57344
	ds_read_u16 v45, v63 offset:58368
	v_fma_f32 v24, v125, v60, v140
	v_fmac_f32_e32 v24, v126, v46
	v_fmac_f32_e32 v24, v109, v47
	s_waitcnt lgkmcnt(1)
	v_lshlrev_b32_e32 v59, 16, v25
	v_fma_f32 v25, v125, v46, v140
	v_fmac_f32_e32 v25, v126, v47
	v_fmac_f32_e32 v25, v109, v33
	v_fmac_f32_e32 v24, v127, v33
	v_fmac_f32_e32 v25, v127, v65
	v_fmac_f32_e32 v24, v110, v65
	v_fmac_f32_e32 v25, v110, v64
	v_fmac_f32_e32 v24, v111, v64
	v_fmac_f32_e32 v25, v111, v48
	v_fmac_f32_e32 v24, v112, v48
	v_fmac_f32_e32 v25, v112, v34
	v_fmac_f32_e32 v24, v128, v34
	v_fmac_f32_e32 v25, v128, v49
	v_fmac_f32_e32 v24, v113, v49
	v_fmac_f32_e32 v25, v113, v35
	v_fmac_f32_e32 v24, v114, v35
	v_fmac_f32_e32 v25, v114, v50
	v_fmac_f32_e32 v24, v115, v50
	v_fmac_f32_e32 v25, v115, v36
	v_fmac_f32_e32 v24, v129, v36
	v_fmac_f32_e32 v25, v129, v51
	v_fmac_f32_e32 v24, v116, v51
	v_fmac_f32_e32 v25, v116, v37
	v_fmac_f32_e32 v24, v117, v37
	v_fmac_f32_e32 v25, v117, v52
	v_fmac_f32_e32 v24, v118, v52
	v_fmac_f32_e32 v25, v118, v38
	v_fmac_f32_e32 v24, v130, v38
	v_fmac_f32_e32 v25, v130, v53
	v_fmac_f32_e32 v24, v119, v53
	v_fmac_f32_e32 v25, v119, v39
	v_fmac_f32_e32 v24, v120, v39
	v_fmac_f32_e32 v25, v120, v54
	v_fmac_f32_e32 v24, v121, v54
	v_fmac_f32_e32 v25, v121, v40
	v_fmac_f32_e32 v24, v131, v40
	v_fmac_f32_e32 v25, v131, v62
	v_fmac_f32_e32 v24, v122, v62
	v_fmac_f32_e32 v25, v122, v61
	v_fmac_f32_e32 v24, v123, v61
	v_fmac_f32_e32 v25, v123, v55
	v_fmac_f32_e32 v24, v124, v55
	v_fmac_f32_e32 v25, v124, v41
	v_fmac_f32_e32 v24, v132, v41
	v_fmac_f32_e32 v25, v132, v56
	v_fmac_f32_e32 v24, v133, v56
	v_fmac_f32_e32 v25, v133, v42
	v_fmac_f32_e32 v24, v134, v42
	v_fmac_f32_e32 v25, v134, v57
	v_fmac_f32_e32 v24, v135, v57
	v_fmac_f32_e32 v25, v135, v43
	v_fmac_f32_e32 v24, v138, v43
	v_fmac_f32_e32 v25, v138, v58
	v_fmac_f32_e32 v24, v136, v58
	v_fmac_f32_e32 v25, v136, v44
	v_fmac_f32_e32 v24, v137, v44
	s_waitcnt lgkmcnt(0)
	v_lshlrev_b32_e32 v45, 16, v45
	v_fmac_f32_e32 v25, v137, v59
	v_fmac_f32_e32 v24, v139, v59
	v_fmac_f32_e32 v25, v139, v45
	ds_write2st64_b32 v29, v24, v25 offset0:80 offset1:88
	ds_read_u16 v25, v63 offset:59392
	ds_read_u16 v46, v63 offset:60416
	v_fma_f32 v24, v125, v47, v140
	v_fmac_f32_e32 v24, v126, v33
	v_fmac_f32_e32 v24, v109, v65
	s_waitcnt lgkmcnt(1)
	v_lshlrev_b32_e32 v60, 16, v25
	v_fma_f32 v25, v125, v33, v140
	v_fmac_f32_e32 v25, v126, v65
	v_fmac_f32_e32 v25, v109, v64
	v_fmac_f32_e32 v24, v127, v64
	v_fmac_f32_e32 v25, v127, v48
	v_fmac_f32_e32 v24, v110, v48
	v_fmac_f32_e32 v25, v110, v34
	v_fmac_f32_e32 v24, v111, v34
	v_fmac_f32_e32 v25, v111, v49
	v_fmac_f32_e32 v24, v112, v49
	v_fmac_f32_e32 v25, v112, v35
	v_fmac_f32_e32 v24, v128, v35
	v_fmac_f32_e32 v25, v128, v50
	v_fmac_f32_e32 v24, v113, v50
	v_fmac_f32_e32 v25, v113, v36
	v_fmac_f32_e32 v24, v114, v36
	v_fmac_f32_e32 v25, v114, v51
	v_fmac_f32_e32 v24, v115, v51
	v_fmac_f32_e32 v25, v115, v37
	v_fmac_f32_e32 v24, v129, v37
	v_fmac_f32_e32 v25, v129, v52
	v_fmac_f32_e32 v24, v116, v52
	v_fmac_f32_e32 v25, v116, v38
	v_fmac_f32_e32 v24, v117, v38
	v_fmac_f32_e32 v25, v117, v53
	v_fmac_f32_e32 v24, v118, v53
	v_fmac_f32_e32 v25, v118, v39
	v_fmac_f32_e32 v24, v130, v39
	v_fmac_f32_e32 v25, v130, v54
	v_fmac_f32_e32 v24, v119, v54
	v_fmac_f32_e32 v25, v119, v40
	v_fmac_f32_e32 v24, v120, v40
	v_fmac_f32_e32 v25, v120, v62
	v_fmac_f32_e32 v24, v121, v62
	v_fmac_f32_e32 v25, v121, v61
	v_fmac_f32_e32 v24, v131, v61
	v_fmac_f32_e32 v25, v131, v55
	v_fmac_f32_e32 v24, v122, v55
	v_fmac_f32_e32 v25, v122, v41
	v_fmac_f32_e32 v24, v123, v41
	v_fmac_f32_e32 v25, v123, v56
	v_fmac_f32_e32 v24, v124, v56
	v_fmac_f32_e32 v25, v124, v42
	v_fmac_f32_e32 v24, v132, v42
	v_fmac_f32_e32 v25, v132, v57
	v_fmac_f32_e32 v24, v133, v57
	v_fmac_f32_e32 v25, v133, v43
	v_fmac_f32_e32 v24, v134, v43
	v_fmac_f32_e32 v25, v134, v58
	v_fmac_f32_e32 v24, v135, v58
	v_fmac_f32_e32 v25, v135, v44
	v_fmac_f32_e32 v24, v138, v44
	v_fmac_f32_e32 v25, v138, v59
	v_fmac_f32_e32 v24, v136, v59
	v_fmac_f32_e32 v25, v136, v45
	v_fmac_f32_e32 v24, v137, v45
	s_waitcnt lgkmcnt(0)
	v_lshlrev_b32_e32 v46, 16, v46
	v_fmac_f32_e32 v25, v137, v60
	v_fmac_f32_e32 v24, v139, v60
	v_fmac_f32_e32 v25, v139, v46
	ds_write2st64_b32 v29, v24, v25 offset0:96 offset1:104
	ds_read_u16 v25, v63 offset:61440
	ds_read_u16 v33, v63 offset:62464
	v_fma_f32 v24, v125, v65, v140
	v_fmac_f32_e32 v24, v126, v64
	v_fmac_f32_e32 v24, v109, v48
	s_waitcnt lgkmcnt(1)
	v_lshlrev_b32_e32 v47, 16, v25
	v_fma_f32 v25, v125, v64, v140
	v_fmac_f32_e32 v25, v126, v48
	v_fmac_f32_e32 v25, v109, v34
	v_fmac_f32_e32 v24, v127, v34
	v_fmac_f32_e32 v25, v127, v49
	v_fmac_f32_e32 v24, v110, v49
	v_fmac_f32_e32 v25, v110, v35
	v_fmac_f32_e32 v24, v111, v35
	v_fmac_f32_e32 v25, v111, v50
	v_fmac_f32_e32 v24, v112, v50
	v_fmac_f32_e32 v25, v112, v36
	v_fmac_f32_e32 v24, v128, v36
	v_fmac_f32_e32 v25, v128, v51
	v_fmac_f32_e32 v24, v113, v51
	v_fmac_f32_e32 v25, v113, v37
	v_fmac_f32_e32 v24, v114, v37
	v_fmac_f32_e32 v25, v114, v52
	v_fmac_f32_e32 v24, v115, v52
	v_fmac_f32_e32 v25, v115, v38
	v_fmac_f32_e32 v24, v129, v38
	v_fmac_f32_e32 v25, v129, v53
	v_fmac_f32_e32 v24, v116, v53
	v_fmac_f32_e32 v25, v116, v39
	v_fmac_f32_e32 v24, v117, v39
	v_fmac_f32_e32 v25, v117, v54
	v_fmac_f32_e32 v24, v118, v54
	v_fmac_f32_e32 v25, v118, v40
	v_fmac_f32_e32 v24, v130, v40
	v_fmac_f32_e32 v25, v130, v62
	v_fmac_f32_e32 v24, v119, v62
	v_fmac_f32_e32 v25, v119, v61
	v_fmac_f32_e32 v24, v120, v61
	v_fmac_f32_e32 v25, v120, v55
	v_fmac_f32_e32 v24, v121, v55
	v_fmac_f32_e32 v25, v121, v41
	v_fmac_f32_e32 v24, v131, v41
	v_fmac_f32_e32 v25, v131, v56
	v_fmac_f32_e32 v24, v122, v56
	v_fmac_f32_e32 v25, v122, v42
	v_fmac_f32_e32 v24, v123, v42
	v_fmac_f32_e32 v25, v123, v57
	v_fmac_f32_e32 v24, v124, v57
	v_fmac_f32_e32 v25, v124, v43
	v_fmac_f32_e32 v24, v132, v43
	v_fmac_f32_e32 v25, v132, v58
	v_fmac_f32_e32 v24, v133, v58
	v_fmac_f32_e32 v25, v133, v44
	v_fmac_f32_e32 v24, v134, v44
	v_fmac_f32_e32 v25, v134, v59
	v_fmac_f32_e32 v24, v135, v59
	v_fmac_f32_e32 v25, v135, v45
	v_fmac_f32_e32 v24, v138, v45
	v_fmac_f32_e32 v25, v138, v60
	v_fmac_f32_e32 v24, v136, v60
	v_fmac_f32_e32 v25, v136, v46
	v_fmac_f32_e32 v24, v137, v46
	s_waitcnt lgkmcnt(0)
	v_lshlrev_b32_e32 v33, 16, v33
	v_fmac_f32_e32 v25, v137, v47
	v_fmac_f32_e32 v24, v139, v47
	v_fmac_f32_e32 v25, v139, v33
	ds_write2st64_b32 v29, v24, v25 offset0:112 offset1:120
	s_waitcnt lgkmcnt(0)
	s_barrier
	ds_read_b128 v[64:67], v31
	ds_read_b128 v[68:71], v31 offset:16
	s_or_b32 s4, s83, 16
	s_waitcnt lgkmcnt(1)
	v_add_f32_e32 v24, 0, v64
	v_add_f32_e32 v24, v65, v24
	v_add_f32_e32 v24, v66, v24
	v_add_f32_e32 v24, v67, v24
	s_waitcnt lgkmcnt(0)
	v_add_f32_e32 v24, v68, v24
	v_add_f32_e32 v24, v69, v24
	v_add_f32_e32 v24, v70, v24
	v_add_f32_e32 v24, v71, v24
	s_nop 1
	v_add_f32_dpp v24, v24, v24 quad_perm:[1,0,3,2] row_mask:0xf bank_mask:0xf bound_ctrl:1
	s_nop 1
	v_add_f32_dpp v24, v24, v24 quad_perm:[2,3,0,1] row_mask:0xf bank_mask:0xf bound_ctrl:1
	s_nop 1
	v_add_f32_dpp v24, v24, v24 row_half_mirror row_mask:0xf bank_mask:0xf bound_ctrl:1
	s_nop 1
	v_add_f32_dpp v24, v24, v24 row_mirror row_mask:0xf bank_mask:0xf bound_ctrl:1
	s_nop 0
	v_readlane_b32 s5, v24, 16
	v_readlane_b32 s8, v24, 48
	v_readlane_b32 s6, v24, 0
	v_readlane_b32 s7, v24, 32
	v_mov_b32_e32 v24, s5
	v_mov_b32_e32 v25, s8
	v_pk_add_f32 v[24:25], s[6:7], v[24:25]
	s_nop 0
	v_add_f32_e32 v25, v24, v25
	v_fmamk_f32 v72, v25, 0xbb000000, v65
	v_mul_f32_e32 v24, 0x3b000000, v25
	v_fmamk_f32 v63, v25, 0xbb000000, v64
	v_mul_f32_e32 v25, v72, v72
	v_fmac_f32_e32 v25, v63, v63
	v_pk_add_f32 v[64:65], v[66:67], v[24:25] op_sel_hi:[1,0] neg_lo:[0,1] neg_hi:[0,1]
	s_nop 0
	v_pk_mul_f32 v[66:67], v[64:65], v[64:65]
	s_nop 0
	v_add_f32_e32 v25, v66, v25
	v_add_f32_e32 v25, v67, v25
	v_pk_add_f32 v[66:67], v[68:69], v[24:25] op_sel_hi:[1,0] neg_lo:[0,1] neg_hi:[0,1]
	s_nop 0
	v_pk_mul_f32 v[68:69], v[66:67], v[66:67]
	s_nop 0
	v_add_f32_e32 v25, v68, v25
	v_add_f32_e32 v73, v69, v25
	v_pk_add_f32 v[24:25], v[70:71], v[24:25] op_sel_hi:[1,0] neg_lo:[0,1] neg_hi:[0,1]
	s_nop 0
	v_pk_mul_f32 v[68:69], v[24:25], v[24:25]
	s_nop 0
	v_add_f32_e32 v68, v68, v73
	v_add_f32_e32 v68, v69, v68
	s_nop 1
	v_add_f32_dpp v68, v68, v68 quad_perm:[1,0,3,2] row_mask:0xf bank_mask:0xf bound_ctrl:1
	s_nop 1
	v_add_f32_dpp v68, v68, v68 quad_perm:[2,3,0,1] row_mask:0xf bank_mask:0xf bound_ctrl:1
	s_nop 1
	v_add_f32_dpp v68, v68, v68 row_half_mirror row_mask:0xf bank_mask:0xf bound_ctrl:1
	s_nop 1
	v_add_f32_dpp v68, v68, v68 row_mirror row_mask:0xf bank_mask:0xf bound_ctrl:1
	s_nop 0
	v_readlane_b32 s5, v68, 16
	v_readlane_b32 s8, v68, 48
	v_readlane_b32 s6, v68, 0
	v_readlane_b32 s7, v68, 32
	v_mov_b32_e32 v68, s5
	v_mov_b32_e32 v69, s8
	v_pk_add_f32 v[68:69], s[6:7], v[68:69]
	s_nop 0
	v_add_f32_e32 v68, v68, v69
	v_fmamk_f32 v68, v68, 0x3b000000, v176
	v_rsq_f32_e32 v73, v68
	s_nop 0
	v_mul_f32_e32 v63, v63, v73
	v_fma_f32 v69, v4, v63, v12
	v_mul_f32_e32 v63, 0xbfb8aa3b, v69
	v_exp_f32_e32 v63, v63
	s_waitcnt vmcnt(1)
	v_lshlrev_b32_e32 v70, 16, v20
	v_mul_f32_e32 v24, v24, v73
	v_add_f32_e32 v63, 1.0, v63
	v_rcp_f32_e32 v71, v63
	v_mul_f32_e32 v63, 0xbfb8aa3b, v70
	v_exp_f32_e32 v63, v63
	s_nop 0
	v_add_f32_e32 v63, 1.0, v63
	v_rcp_f32_e32 v68, v63
	s_nop 0
	v_pk_mul_f32 v[68:69], v[68:69], v[70:71]
	s_nop 0
	v_mul_f32_e32 v63, v68, v69
	v_mul_f32_e32 v68, v72, v73
	v_fma_f32 v69, v5, v68, v13
	v_and_b32_e32 v70, 0xffff0000, v20
	v_mul_f32_e32 v68, 0xbfb8aa3b, v69
	v_mul_f32_e32 v20, 0xbfb8aa3b, v70
	v_exp_f32_e32 v68, v68
	v_exp_f32_e32 v20, v20
	v_add_f32_e32 v68, 1.0, v68
	v_add_f32_e32 v20, 1.0, v20
	v_rcp_f32_e32 v71, v68
	v_rcp_f32_e32 v68, v20
	s_nop 0
	v_pk_mul_f32 v[68:69], v[68:69], v[70:71]
	s_nop 0
	v_mul_f32_e32 v20, v68, v69
	v_cvt_pk_bf16_f32 v20, v63, v20
	v_mul_f32_e32 v63, v64, v73
	v_fma_f32 v69, v6, v63, v14
	v_mul_f32_e32 v63, 0xbfb8aa3b, v69
	v_exp_f32_e32 v63, v63
	v_lshlrev_b32_e32 v70, 16, v21
	v_mul_f32_e32 v64, v65, v73
	v_fma_f32 v65, v7, v64, v15
	v_add_f32_e32 v63, 1.0, v63
	v_rcp_f32_e32 v71, v63
	v_mul_f32_e32 v63, 0xbfb8aa3b, v70
	v_exp_f32_e32 v63, v63
	v_mul_f32_e32 v64, 0xbfb8aa3b, v65
	v_exp_f32_e32 v64, v64
	v_add_f32_e32 v63, 1.0, v63
	v_rcp_f32_e32 v68, v63
	v_add_f32_e32 v64, 1.0, v64
	v_pk_mul_f32 v[68:69], v[68:69], v[70:71]
	s_nop 0
	v_mul_f32_e32 v63, v68, v69
	v_and_b32_e32 v68, 0xffff0000, v21
	v_mul_f32_e32 v21, 0xbfb8aa3b, v68
	v_exp_f32_e32 v21, v21
	v_rcp_f32_e32 v69, v64
	v_add_f32_e32 v21, 1.0, v21
	v_rcp_f32_e32 v64, v21
	s_nop 0
	v_pk_mul_f32 v[64:65], v[64:65], v[68:69]
	s_nop 0
	v_mul_f32_e32 v21, v64, v65
	v_cvt_pk_bf16_f32 v21, v63, v21
	v_mul_f32_e32 v63, v66, v73
	v_fma_f32 v65, v0, v63, v8
	v_mul_f32_e32 v63, 0xbfb8aa3b, v65
	v_exp_f32_e32 v63, v63
	v_lshlrev_b32_e32 v68, 16, v22
	v_and_b32_e32 v66, 0xffff0000, v22
	v_mul_f32_e32 v22, 0xbfb8aa3b, v66
	v_add_f32_e32 v63, 1.0, v63
	v_rcp_f32_e32 v69, v63
	v_mul_f32_e32 v63, 0xbfb8aa3b, v68
	v_exp_f32_e32 v63, v63
	v_exp_f32_e32 v22, v22
	v_add_f32_e32 v63, 1.0, v63
	v_rcp_f32_e32 v64, v63
	v_add_f32_e32 v22, 1.0, v22
	v_pk_mul_f32 v[64:65], v[64:65], v[68:69]
	s_nop 0
	v_mul_f32_e32 v63, v64, v65
	v_mul_f32_e32 v64, v67, v73
	v_fma_f32 v65, v1, v64, v9
	v_mul_f32_e32 v64, 0xbfb8aa3b, v65
	v_exp_f32_e32 v64, v64
	s_nop 0
	v_add_f32_e32 v64, 1.0, v64
	v_rcp_f32_e32 v67, v64
	v_rcp_f32_e32 v64, v22
	s_nop 0
	v_pk_mul_f32 v[64:65], v[64:65], v[66:67]
	s_nop 0
	v_mul_f32_e32 v22, v64, v65
	v_fma_f32 v65, v2, v24, v10
	v_mul_f32_e32 v24, 0xbfb8aa3b, v65
	v_exp_f32_e32 v24, v24
	v_lshlrev_b32_e32 v66, 16, v23
	v_cvt_pk_bf16_f32 v22, v63, v22
	v_add_f32_e32 v24, 1.0, v24
	v_rcp_f32_e32 v67, v24
	v_mul_f32_e32 v24, 0xbfb8aa3b, v66
	v_exp_f32_e32 v24, v24
	s_nop 0
	v_add_f32_e32 v24, 1.0, v24
	v_rcp_f32_e32 v64, v24
	v_mul_f32_e32 v24, v25, v73
	v_fma_f32 v25, v3, v24, v11
	v_mul_f32_e32 v24, 0xbfb8aa3b, v25
	v_pk_mul_f32 v[64:65], v[64:65], v[66:67]
	v_exp_f32_e32 v24, v24
	v_mul_f32_e32 v63, v64, v65
	v_and_b32_e32 v64, 0xffff0000, v23
	v_mul_f32_e32 v23, 0xbfb8aa3b, v64
	v_exp_f32_e32 v23, v23
	v_add_f32_e32 v24, 1.0, v24
	v_rcp_f32_e32 v65, v24
	v_add_f32_e32 v23, 1.0, v23
	v_rcp_f32_e32 v24, v23
	s_nop 0
	v_pk_mul_f32 v[24:25], v[24:25], v[64:65]
	s_nop 0
	v_mul_f32_e32 v23, v24, v25
	v_add_u32_e32 v24, s4, v27
	v_ashrrev_i32_e32 v25, 31, v24
	v_lshlrev_b64 v[24:25], 12, v[24:25]
	v_lshl_add_u64 v[24:25], s[44:45], 0, v[24:25]
	v_lshl_add_u64 v[24:25], v[24:25], 0, v[144:145]
	v_add_co_u32_e32 v24, vcc, s89, v24
	v_cvt_pk_bf16_f32 v23, v63, v23
	s_nop 1
	v_addc_co_u32_e32 v25, vcc, 0, v25, vcc
	global_store_dwordx4 v[24:25], v[20:23], off offset:2048
	ds_read_b128 v[20:23], v32
	ds_read_b128 v[64:67], v32 offset:16
	s_waitcnt lgkmcnt(1)
	v_add_f32_e32 v24, 0, v20
	v_add_f32_e32 v24, v21, v24
	v_add_f32_e32 v24, v22, v24
	v_add_f32_e32 v24, v23, v24
	s_waitcnt lgkmcnt(0)
	v_add_f32_e32 v24, v64, v24
	v_add_f32_e32 v24, v65, v24
	v_add_f32_e32 v24, v66, v24
	v_add_f32_e32 v24, v67, v24
	s_nop 1
	v_add_f32_dpp v24, v24, v24 quad_perm:[1,0,3,2] row_mask:0xf bank_mask:0xf bound_ctrl:1
	s_nop 1
	v_add_f32_dpp v24, v24, v24 quad_perm:[2,3,0,1] row_mask:0xf bank_mask:0xf bound_ctrl:1
	s_nop 1
	v_add_f32_dpp v24, v24, v24 row_half_mirror row_mask:0xf bank_mask:0xf bound_ctrl:1
	s_nop 1
	v_add_f32_dpp v24, v24, v24 row_mirror row_mask:0xf bank_mask:0xf bound_ctrl:1
	s_nop 0
	v_readlane_b32 s5, v24, 16
	v_readlane_b32 s8, v24, 48
	v_readlane_b32 s6, v24, 0
	v_readlane_b32 s7, v24, 32
	v_mov_b32_e32 v24, s5
	v_mov_b32_e32 v25, s8
	v_pk_add_f32 v[24:25], s[6:7], v[24:25]
	s_nop 0
	v_add_f32_e32 v25, v24, v25
	v_fmamk_f32 v68, v25, 0xbb000000, v21
	v_mul_f32_e32 v24, 0x3b000000, v25
	v_fmamk_f32 v63, v25, 0xbb000000, v20
	v_mul_f32_e32 v25, v68, v68
	v_fmac_f32_e32 v25, v63, v63
	v_pk_add_f32 v[20:21], v[22:23], v[24:25] op_sel_hi:[1,0] neg_lo:[0,1] neg_hi:[0,1]
	s_nop 0
	v_pk_mul_f32 v[22:23], v[20:21], v[20:21]
	s_nop 0
	v_add_f32_e32 v22, v22, v25
	v_add_f32_e32 v25, v23, v22
	v_pk_add_f32 v[22:23], v[64:65], v[24:25] op_sel_hi:[1,0] neg_lo:[0,1] neg_hi:[0,1]
	s_nop 0
	v_pk_mul_f32 v[64:65], v[22:23], v[22:23]
	s_nop 0
	v_add_f32_e32 v25, v64, v25
	v_add_f32_e32 v69, v65, v25
	v_pk_add_f32 v[24:25], v[66:67], v[24:25] op_sel_hi:[1,0] neg_lo:[0,1] neg_hi:[0,1]
	s_nop 0
	v_pk_mul_f32 v[64:65], v[24:25], v[24:25]
	s_nop 0
	v_add_f32_e32 v64, v64, v69
	v_add_f32_e32 v64, v65, v64
	s_nop 1
	v_add_f32_dpp v64, v64, v64 quad_perm:[1,0,3,2] row_mask:0xf bank_mask:0xf bound_ctrl:1
	s_nop 1
	v_add_f32_dpp v64, v64, v64 quad_perm:[2,3,0,1] row_mask:0xf bank_mask:0xf bound_ctrl:1
	s_nop 1
	v_add_f32_dpp v64, v64, v64 row_half_mirror row_mask:0xf bank_mask:0xf bound_ctrl:1
	s_nop 1
	v_add_f32_dpp v64, v64, v64 row_mirror row_mask:0xf bank_mask:0xf bound_ctrl:1
	s_nop 0
	v_readlane_b32 s5, v64, 16
	v_readlane_b32 s8, v64, 48
	v_readlane_b32 s6, v64, 0
	v_readlane_b32 s7, v64, 32
	v_mov_b32_e32 v64, s5
	v_mov_b32_e32 v65, s8
	v_pk_add_f32 v[64:65], s[6:7], v[64:65]
	s_nop 0
	v_add_f32_e32 v64, v64, v65
	v_fmamk_f32 v64, v64, 0x3b000000, v176
	s_mov_b32 s42, 1
	v_rsq_f32_e32 v69, v64
	s_nop 0
	v_mul_f32_e32 v63, v63, v69
	v_fma_f32 v65, v4, v63, v12
	v_mul_f32_e32 v63, 0xbfb8aa3b, v65
	v_exp_f32_e32 v63, v63
	s_waitcnt vmcnt(1)
	v_lshlrev_b32_e32 v66, 16, v16
	v_mul_f32_e32 v20, v20, v69
	v_add_f32_e32 v63, 1.0, v63
	v_rcp_f32_e32 v67, v63
	v_mul_f32_e32 v63, 0xbfb8aa3b, v66
	v_exp_f32_e32 v63, v63
	s_nop 0
	v_add_f32_e32 v63, 1.0, v63
	v_rcp_f32_e32 v64, v63
	s_nop 0
	v_pk_mul_f32 v[64:65], v[64:65], v[66:67]
	s_nop 0
	v_mul_f32_e32 v63, v64, v65
	v_mul_f32_e32 v64, v68, v69
	v_fma_f32 v65, v5, v64, v13
	v_and_b32_e32 v66, 0xffff0000, v16
	v_mul_f32_e32 v64, 0xbfb8aa3b, v65
	v_mul_f32_e32 v16, 0xbfb8aa3b, v66
	v_exp_f32_e32 v64, v64
	v_exp_f32_e32 v16, v16
	v_add_f32_e32 v64, 1.0, v64
	v_add_f32_e32 v16, 1.0, v16
	v_rcp_f32_e32 v67, v64
	v_rcp_f32_e32 v64, v16
	s_nop 0
	v_pk_mul_f32 v[64:65], v[64:65], v[66:67]
	s_nop 0
	v_mul_f32_e32 v16, v64, v65
	v_fma_f32 v65, v6, v20, v14
	v_mul_f32_e32 v20, 0xbfb8aa3b, v65
	v_exp_f32_e32 v20, v20
	v_lshlrev_b32_e32 v66, 16, v17
	v_cvt_pk_bf16_f32 v16, v63, v16
	v_add_f32_e32 v20, 1.0, v20
	v_rcp_f32_e32 v67, v20
	v_mul_f32_e32 v20, 0xbfb8aa3b, v66
	v_exp_f32_e32 v20, v20
	s_nop 0
	v_add_f32_e32 v20, 1.0, v20
	v_rcp_f32_e32 v64, v20
	v_mul_f32_e32 v20, v21, v69
	v_fma_f32 v21, v7, v20, v15
	v_mul_f32_e32 v20, 0xbfb8aa3b, v21
	v_pk_mul_f32 v[64:65], v[64:65], v[66:67]
	v_exp_f32_e32 v20, v20
	v_mul_f32_e32 v63, v64, v65
	v_and_b32_e32 v64, 0xffff0000, v17
	v_mul_f32_e32 v17, 0xbfb8aa3b, v64
	v_exp_f32_e32 v17, v17
	v_add_f32_e32 v20, 1.0, v20
	v_rcp_f32_e32 v65, v20
	v_add_f32_e32 v17, 1.0, v17
	v_rcp_f32_e32 v20, v17
	s_nop 0
	v_pk_mul_f32 v[20:21], v[20:21], v[64:65]
	s_nop 0
	v_mul_f32_e32 v17, v20, v21
	v_mul_f32_e32 v20, v22, v69
	v_fma_f32 v21, v0, v20, v8
	v_mul_f32_e32 v20, 0xbfb8aa3b, v21
	v_exp_f32_e32 v20, v20
	v_lshlrev_b32_e32 v64, 16, v18
	v_cvt_pk_bf16_f32 v17, v63, v17
	v_and_b32_e32 v22, 0xffff0000, v18
	v_add_f32_e32 v20, 1.0, v20
	v_rcp_f32_e32 v65, v20
	v_mul_f32_e32 v20, 0xbfb8aa3b, v64
	v_exp_f32_e32 v20, v20
	v_mul_f32_e32 v18, 0xbfb8aa3b, v22
	v_exp_f32_e32 v18, v18
	v_add_f32_e32 v20, 1.0, v20
	v_rcp_f32_e32 v20, v20
	v_add_f32_e32 v18, 1.0, v18
	v_pk_mul_f32 v[20:21], v[20:21], v[64:65]
	s_nop 0
	v_mul_f32_e32 v63, v20, v21
	v_mul_f32_e32 v20, v23, v69
	v_fma_f32 v21, v1, v20, v9
	v_mul_f32_e32 v20, 0xbfb8aa3b, v21
	v_exp_f32_e32 v20, v20
	s_nop 0
	v_add_f32_e32 v20, 1.0, v20
	v_rcp_f32_e32 v23, v20
	v_rcp_f32_e32 v20, v18
	s_nop 0
	v_pk_mul_f32 v[20:21], v[20:21], v[22:23]
	s_nop 0
	v_mul_f32_e32 v18, v20, v21
	v_mul_f32_e32 v20, v24, v69
	v_fma_f32 v21, v2, v20, v10
	v_mul_f32_e32 v20, 0xbfb8aa3b, v21
	v_exp_f32_e32 v20, v20
	v_lshlrev_b32_e32 v22, 16, v19
	v_cvt_pk_bf16_f32 v18, v63, v18
	v_add_f32_e32 v20, 1.0, v20
	v_rcp_f32_e32 v23, v20
	v_mul_f32_e32 v20, 0xbfb8aa3b, v22
	v_exp_f32_e32 v20, v20
	s_nop 0
	v_add_f32_e32 v20, 1.0, v20
	v_rcp_f32_e32 v20, v20
	s_nop 0
	v_pk_mul_f32 v[20:21], v[20:21], v[22:23]
	s_nop 0
	v_mul_f32_e32 v24, v20, v21
	v_mul_f32_e32 v20, v25, v69
	v_fma_f32 v21, v3, v20, v11
	v_and_b32_e32 v22, 0xffff0000, v19
	v_mul_f32_e32 v20, 0xbfb8aa3b, v21
	v_mul_f32_e32 v19, 0xbfb8aa3b, v22
	v_exp_f32_e32 v20, v20
	v_exp_f32_e32 v19, v19
	v_add_f32_e32 v20, 1.0, v20
	v_add_f32_e32 v19, 1.0, v19
	v_rcp_f32_e32 v23, v20
	v_rcp_f32_e32 v20, v19
	s_nop 0
	v_pk_mul_f32 v[20:21], v[20:21], v[22:23]
	s_nop 0
	v_mul_f32_e32 v19, v20, v21
	v_add_u32_e32 v20, s4, v30
	v_ashrrev_i32_e32 v21, 31, v20
	v_lshlrev_b64 v[20:21], 12, v[20:21]
	v_lshl_add_u64 v[20:21], s[44:45], 0, v[20:21]
	v_lshl_add_u64 v[20:21], v[20:21], 0, v[144:145]
	v_add_co_u32_e32 v20, vcc, 0x11b80000, v20
	v_cvt_pk_bf16_f32 v19, v24, v19
	s_nop 1
	v_addc_co_u32_e32 v21, vcc, 0, v21, vcc
	s_and_b64 vcc, exec, s[76:77]
	s_mov_b64 s[76:77], 0
	global_store_dwordx4 v[20:21], v[16:19], off offset:2048
	s_barrier
	s_cbranch_vccnz .LBB0_395
	s_mov_b64 s[42:43], 0
.LBB0_397:
	s_and_b64 vcc, exec, s[42:43]
	s_cbranch_vccz .LBB0_363
	s_add_i32 s4, s92, s87
	s_waitcnt vmcnt(1)
	v_mov_b32_e32 v32, v175
	s_mov_b64 s[48:49], s[68:69]
	s_add_u32 s76, s48, 0x7900000
	v_ashrrev_i32_e32 v4, 6, v32
	s_addc_u32 s77, s49, 0
	s_lshl_b32 s4, s4, 6
	s_and_b32 s4, s4, 0xffffff80
	v_lshlrev_b32_e32 v120, 4, v4
	v_and_b32_e32 v127, 63, v32
	v_add_u32_e32 v31, s4, v120
	v_mov_b64_e32 v[0:1], s[76:77]
	v_mad_i64_i32 v[2:3], s[6:7], v31, s62, v[0:1]
	v_lshlrev_b32_e32 v144, 4, v127
	v_lshl_add_u64 v[2:3], v[2:3], 0, v[144:145]
	v_add_co_u32_e32 v2, vcc, s3, v2
	s_nop 1
	v_addc_co_u32_e32 v3, vcc, 0, v3, vcc
	s_barrier
	global_load_dwordx4 v[34:37], v[2:3], off
	v_or_b32_e32 v2, 1, v31
	v_mad_i64_i32 v[2:3], s[6:7], v2, s62, v[0:1]
	v_lshlrev_b32_e32 v30, 7, v4
	v_or_b32_e32 v4, 2, v31
	v_lshl_add_u64 v[2:3], v[2:3], 0, v[144:145]
	v_mad_i64_i32 v[4:5], s[6:7], v4, s62, v[0:1]
	v_add_co_u32_e32 v2, vcc, s3, v2
	v_or_b32_e32 v6, 3, v31
	v_lshl_add_u64 v[4:5], v[4:5], 0, v[144:145]
	v_addc_co_u32_e32 v3, vcc, 0, v3, vcc
	v_mad_i64_i32 v[6:7], s[6:7], v6, s62, v[0:1]
	v_add_co_u32_e32 v4, vcc, s3, v4
	v_or_b32_e32 v8, 4, v31
	v_lshl_add_u64 v[6:7], v[6:7], 0, v[144:145]
	v_addc_co_u32_e32 v5, vcc, 0, v5, vcc
	v_mad_i64_i32 v[8:9], s[6:7], v8, s62, v[0:1]
	v_add_co_u32_e32 v6, vcc, s3, v6
	v_or_b32_e32 v10, 5, v31
	v_lshl_add_u64 v[8:9], v[8:9], 0, v[144:145]
	v_addc_co_u32_e32 v7, vcc, 0, v7, vcc
	v_mad_i64_i32 v[10:11], s[6:7], v10, s62, v[0:1]
	v_add_co_u32_e32 v8, vcc, s3, v8
	v_or_b32_e32 v12, 6, v31
	v_lshl_add_u64 v[10:11], v[10:11], 0, v[144:145]
	v_addc_co_u32_e32 v9, vcc, 0, v9, vcc
	v_mad_i64_i32 v[12:13], s[6:7], v12, s62, v[0:1]
	v_add_co_u32_e32 v10, vcc, s3, v10
	v_lshl_add_u64 v[12:13], v[12:13], 0, v[144:145]
	s_nop 0
	v_addc_co_u32_e32 v11, vcc, 0, v11, vcc
	v_or_b32_e32 v14, 7, v31
	v_add_co_u32_e32 v28, vcc, s3, v12
	v_mad_i64_i32 v[0:1], s[6:7], v14, s62, v[0:1]
	s_nop 0
	v_addc_co_u32_e32 v29, vcc, 0, v13, vcc
	global_load_dwordx4 v[24:27], v[2:3], off
	global_load_dwordx4 v[20:23], v[4:5], off
	global_load_dwordx4 v[16:19], v[6:7], off
	global_load_dwordx4 v[12:15], v[8:9], off
	s_nop 0
	global_load_dwordx4 v[8:11], v[10:11], off
	v_lshl_add_u64 v[0:1], v[0:1], 0, v[144:145]
	v_add_co_u32_e32 v0, vcc, s3, v0
	v_cmp_eq_u32_e64 s[42:43], 0, v127
	s_nop 0
	v_addc_co_u32_e32 v1, vcc, 0, v1, vcc
	v_add_u32_e32 v30, 0, v30
	s_waitcnt vmcnt(5)
	v_lshlrev_b32_e32 v33, 16, v34
	v_mul_f32_e32 v2, v33, v33
	v_fmamk_f32 v2, v2, 0xbdd2d3e8, v245
	v_mul_f32_e32 v2, v2, v33
	v_and_b32_e32 v34, 0xffff0000, v34
	v_exp_f32_e32 v38, v2
	v_mul_f32_e32 v2, v34, v34
	v_fmamk_f32 v2, v2, 0xbdd2d3e8, v245
	v_mul_f32_e32 v2, v2, v34
	v_exp_f32_e32 v39, v2
	global_load_dwordx4 v[4:7], v[28:29], off
	s_nop 0
	global_load_dwordx4 v[0:3], v[0:1], off
	v_add_f32_e32 v28, 1.0, v38
	v_lshlrev_b32_e32 v38, 16, v35
	v_rcp_f32_e32 v29, v28
	v_add_f32_e32 v28, 1.0, v39
	v_mul_f32_e32 v39, v38, v38
	v_and_b32_e32 v35, 0xffff0000, v35
	v_fmamk_f32 v39, v39, 0xbdd2d3e8, v245
	v_mul_f32_e32 v40, v35, v35
	v_mul_f32_e32 v39, v39, v38
	v_fmamk_f32 v40, v40, 0xbdd2d3e8, v245
	v_mul_f32_e32 v40, v40, v35
	v_exp_f32_e32 v39, v39
	v_exp_f32_e32 v40, v40
	v_rcp_f32_e32 v41, v28
	v_add_f32_e32 v28, 1.0, v39
	v_rcp_f32_e32 v39, v28
	v_add_f32_e32 v28, 1.0, v40
	v_lshlrev_b32_e32 v40, 16, v36
	v_mul_f32_e32 v42, v40, v40
	v_and_b32_e32 v36, 0xffff0000, v36
	v_fmamk_f32 v42, v42, 0xbdd2d3e8, v245
	v_mul_f32_e32 v43, v36, v36
	v_mul_f32_e32 v42, v42, v40
	v_fmamk_f32 v43, v43, 0xbdd2d3e8, v245
	v_mul_f32_e32 v43, v43, v36
	v_exp_f32_e32 v42, v42
	v_exp_f32_e32 v43, v43
	v_rcp_f32_e32 v44, v28
	v_add_f32_e32 v28, 1.0, v42
	v_rcp_f32_e32 v42, v28
	v_add_f32_e32 v28, 1.0, v43
	v_lshlrev_b32_e32 v43, 16, v37
	v_mul_f32_e32 v45, v43, v43
	v_and_b32_e32 v37, 0xffff0000, v37
	v_fmamk_f32 v45, v45, 0xbdd2d3e8, v245
	v_mul_f32_e32 v46, v37, v37
	v_mul_f32_e32 v45, v45, v43
	v_fmamk_f32 v46, v46, 0xbdd2d3e8, v245
	v_mul_f32_e32 v46, v46, v37
	v_exp_f32_e32 v45, v45
	v_exp_f32_e32 v46, v46
	v_rcp_f32_e32 v47, v28
	v_add_f32_e32 v28, 1.0, v45
	v_rcp_f32_e32 v45, v28
	v_add_f32_e32 v28, 1.0, v46
	v_rcp_f32_e32 v46, v28
	v_fma_f32 v28, v29, v33, 0
	v_fmac_f32_e32 v28, v41, v34
	v_fmac_f32_e32 v28, v39, v38
	v_fmac_f32_e32 v28, v44, v35
	v_fmac_f32_e32 v28, v42, v40
	v_fmac_f32_e32 v28, v47, v36
	v_fmac_f32_e32 v28, v45, v43
	v_fmac_f32_e32 v28, v46, v37
	s_nop 1
	v_add_f32_dpp v28, v28, v28 quad_perm:[1,0,3,2] row_mask:0xf bank_mask:0xf bound_ctrl:1
	s_nop 1
	v_add_f32_dpp v28, v28, v28 quad_perm:[2,3,0,1] row_mask:0xf bank_mask:0xf bound_ctrl:1
	s_nop 1
	v_add_f32_dpp v28, v28, v28 row_half_mirror row_mask:0xf bank_mask:0xf bound_ctrl:1
	s_nop 1
	v_add_f32_dpp v28, v28, v28 row_mirror row_mask:0xf bank_mask:0xf bound_ctrl:1
	s_nop 0
	v_readlane_b32 s6, v28, 16
	v_readlane_b32 s5, v28, 0
	s_nop 0
	v_mov_b32_e32 v48, s6
	v_readlane_b32 s6, v28, 48
	v_add_f32_e32 v48, s5, v48
	v_readlane_b32 s5, v28, 32
	v_mov_b32_e32 v28, s6
	s_nop 0
	v_add_f32_e32 v28, s5, v28
	v_add_f32_e32 v28, v48, v28
	v_mul_f32_e32 v28, 0x3b000000, v28
	v_fma_f32 v29, v29, v33, -v28
	v_fma_f32 v33, v41, v34, -v28
	v_mul_f32_e32 v33, v33, v33
	v_fmac_f32_e32 v33, v29, v29
	v_fma_f32 v29, v39, v38, -v28
	v_fmac_f32_e32 v33, v29, v29
	v_fma_f32 v29, v44, v35, -v28
	v_fmac_f32_e32 v33, v29, v29
	v_fma_f32 v29, v42, v40, -v28
	v_fmac_f32_e32 v33, v29, v29
	v_fma_f32 v29, v47, v36, -v28
	v_fmac_f32_e32 v33, v29, v29
	v_fma_f32 v29, v45, v43, -v28
	v_fmac_f32_e32 v33, v29, v29
	v_fma_f32 v29, v46, v37, -v28
	v_fmac_f32_e32 v33, v29, v29
	s_nop 1
	v_add_f32_dpp v29, v33, v33 quad_perm:[1,0,3,2] row_mask:0xf bank_mask:0xf bound_ctrl:1
	s_nop 1
	v_add_f32_dpp v29, v29, v29 quad_perm:[2,3,0,1] row_mask:0xf bank_mask:0xf bound_ctrl:1
	s_nop 1
	v_add_f32_dpp v29, v29, v29 row_half_mirror row_mask:0xf bank_mask:0xf bound_ctrl:1
	s_nop 1
	v_add_f32_dpp v29, v29, v29 row_mirror row_mask:0xf bank_mask:0xf bound_ctrl:1
	s_nop 0
	v_readlane_b32 s44, v29, 0
	v_readlane_b32 s5, v29, 16
	v_readlane_b32 s45, v29, 32
	v_readlane_b32 s6, v29, 48
	s_and_saveexec_b64 s[82:83], s[42:43]
	s_cbranch_execz .LBB0_400
	v_mov_b32_e32 v34, s5
	v_mov_b32_e32 v35, s6
	v_pk_add_f32 v[34:35], s[44:45], v[34:35]
	s_nop 0
	v_add_f32_e32 v29, v34, v35
	v_fmamk_f32 v29, v29, 0x3b000000, v176
	v_rsq_f32_e32 v29, v29
	ds_write_b64 v30, v[28:29]
.LBB0_400:
	s_or_b64 exec, exec, s[82:83]
	s_waitcnt vmcnt(6)
	v_and_b32_e32 v33, 0xffff0000, v24
	v_lshlrev_b32_e32 v28, 16, v24
	v_mul_f32_e32 v24, v33, v33
	v_lshlrev_b32_e32 v34, 16, v25
	v_fmamk_f32 v24, v24, 0xbdd2d3e8, v245
	v_mul_f32_e32 v35, v34, v34
	v_and_b32_e32 v25, 0xffff0000, v25
	v_mul_f32_e32 v24, v24, v33
	v_fmamk_f32 v35, v35, 0xbdd2d3e8, v245
	v_mul_f32_e32 v36, v25, v25
	v_mul_f32_e32 v35, v35, v34
	v_fmamk_f32 v36, v36, 0xbdd2d3e8, v245
	v_mul_f32_e32 v36, v36, v25
	v_exp_f32_e32 v24, v24
	v_exp_f32_e32 v35, v35
	v_exp_f32_e32 v36, v36
	v_add_f32_e32 v24, 1.0, v24
	v_rcp_f32_e32 v37, v24
	v_add_f32_e32 v24, 1.0, v35
	v_rcp_f32_e32 v35, v24
	v_add_f32_e32 v24, 1.0, v36
	v_lshlrev_b32_e32 v36, 16, v26
	v_mul_f32_e32 v38, v36, v36
	v_and_b32_e32 v26, 0xffff0000, v26
	v_fmamk_f32 v38, v38, 0xbdd2d3e8, v245
	v_mul_f32_e32 v39, v26, v26
	v_mul_f32_e32 v38, v38, v36
	v_fmamk_f32 v39, v39, 0xbdd2d3e8, v245
	v_mul_f32_e32 v39, v39, v26
	v_exp_f32_e32 v38, v38
	v_exp_f32_e32 v39, v39
	v_mul_f32_e32 v29, v28, v28
	v_fmamk_f32 v29, v29, 0xbdd2d3e8, v245
	v_rcp_f32_e32 v40, v24
	v_add_f32_e32 v24, 1.0, v38
	v_mul_f32_e32 v29, v29, v28
	v_rcp_f32_e32 v38, v24
	v_add_f32_e32 v24, 1.0, v39
	v_lshlrev_b32_e32 v39, 16, v27
	v_mul_f32_e32 v41, v39, v39
	v_and_b32_e32 v27, 0xffff0000, v27
	v_fmamk_f32 v41, v41, 0xbdd2d3e8, v245
	v_mul_f32_e32 v42, v27, v27
	v_exp_f32_e32 v29, v29
	v_mul_f32_e32 v41, v41, v39
	v_fmamk_f32 v42, v42, 0xbdd2d3e8, v245
	v_mul_f32_e32 v42, v42, v27
	v_exp_f32_e32 v41, v41
	v_add_f32_e32 v29, 1.0, v29
	v_exp_f32_e32 v42, v42
	v_rcp_f32_e32 v29, v29
	v_rcp_f32_e32 v43, v24
	v_add_f32_e32 v24, 1.0, v41
	v_rcp_f32_e32 v41, v24
	v_add_f32_e32 v24, 1.0, v42
	v_rcp_f32_e32 v42, v24
	v_fma_f32 v24, v29, v28, 0
	v_fmac_f32_e32 v24, v37, v33
	v_fmac_f32_e32 v24, v35, v34
	v_fmac_f32_e32 v24, v40, v25
	v_fmac_f32_e32 v24, v38, v36
	v_fmac_f32_e32 v24, v43, v26
	v_fmac_f32_e32 v24, v41, v39
	v_fmac_f32_e32 v24, v42, v27
	s_nop 1
	v_add_f32_dpp v24, v24, v24 quad_perm:[1,0,3,2] row_mask:0xf bank_mask:0xf bound_ctrl:1
	s_nop 1
	v_add_f32_dpp v24, v24, v24 quad_perm:[2,3,0,1] row_mask:0xf bank_mask:0xf bound_ctrl:1
	s_nop 1
	v_add_f32_dpp v24, v24, v24 row_half_mirror row_mask:0xf bank_mask:0xf bound_ctrl:1
	s_nop 1
	v_add_f32_dpp v24, v24, v24 row_mirror row_mask:0xf bank_mask:0xf bound_ctrl:1
	s_nop 0
	v_readlane_b32 s6, v24, 16
	v_readlane_b32 s5, v24, 0
	s_nop 0
	v_mov_b32_e32 v44, s6
	v_readlane_b32 s6, v24, 48
	v_add_f32_e32 v44, s5, v44
	v_readlane_b32 s5, v24, 32
	v_mov_b32_e32 v24, s6
	s_nop 0
	v_add_f32_e32 v24, s5, v24
	v_add_f32_e32 v24, v44, v24
	v_mul_f32_e32 v24, 0x3b000000, v24
	v_fma_f32 v28, v29, v28, -v24
	v_fma_f32 v29, v37, v33, -v24
	v_mul_f32_e32 v29, v29, v29
	v_fmac_f32_e32 v29, v28, v28
	v_fma_f32 v28, v35, v34, -v24
	v_fmac_f32_e32 v29, v28, v28
	v_fma_f32 v25, v40, v25, -v24
	v_fmac_f32_e32 v29, v25, v25
	v_fma_f32 v25, v38, v36, -v24
	v_fmac_f32_e32 v29, v25, v25
	v_fma_f32 v25, v43, v26, -v24
	v_fmac_f32_e32 v29, v25, v25
	v_fma_f32 v25, v41, v39, -v24
	v_fmac_f32_e32 v29, v25, v25
	v_fma_f32 v25, v42, v27, -v24
	v_fmac_f32_e32 v29, v25, v25
	s_nop 1
	v_add_f32_dpp v25, v29, v29 quad_perm:[1,0,3,2] row_mask:0xf bank_mask:0xf bound_ctrl:1
	s_nop 1
	v_add_f32_dpp v25, v25, v25 quad_perm:[2,3,0,1] row_mask:0xf bank_mask:0xf bound_ctrl:1
	s_nop 1
	v_add_f32_dpp v25, v25, v25 row_half_mirror row_mask:0xf bank_mask:0xf bound_ctrl:1
	s_nop 1
	v_add_f32_dpp v25, v25, v25 row_mirror row_mask:0xf bank_mask:0xf bound_ctrl:1
	s_nop 0
	v_readlane_b32 s44, v25, 0
	v_readlane_b32 s5, v25, 16
	v_readlane_b32 s45, v25, 32
	v_readlane_b32 s6, v25, 48
	s_and_saveexec_b64 s[82:83], s[42:43]
	s_cbranch_execz .LBB0_402
	v_mov_b32_e32 v26, s5
	v_mov_b32_e32 v27, s6
	v_pk_add_f32 v[26:27], s[44:45], v[26:27]
	s_nop 0
	v_add_f32_e32 v25, v26, v27
	v_fmamk_f32 v25, v25, 0x3b000000, v176
	v_rsq_f32_e32 v25, v25
	ds_write_b64 v30, v[24:25] offset:8
.LBB0_402:
	s_or_b64 exec, exec, s[82:83]
	s_waitcnt vmcnt(5)
	v_and_b32_e32 v26, 0xffff0000, v20
	v_lshlrev_b32_e32 v24, 16, v20
	v_mul_f32_e32 v20, v26, v26
	v_lshlrev_b32_e32 v27, 16, v21
	v_fmamk_f32 v20, v20, 0xbdd2d3e8, v245
	v_mul_f32_e32 v28, v27, v27
	v_and_b32_e32 v21, 0xffff0000, v21
	v_mul_f32_e32 v20, v20, v26
	v_fmamk_f32 v28, v28, 0xbdd2d3e8, v245
	v_mul_f32_e32 v29, v21, v21
	v_mul_f32_e32 v28, v28, v27
	v_fmamk_f32 v29, v29, 0xbdd2d3e8, v245
	v_mul_f32_e32 v29, v29, v21
	v_exp_f32_e32 v20, v20
	v_exp_f32_e32 v28, v28
	v_exp_f32_e32 v29, v29
	v_add_f32_e32 v20, 1.0, v20
	v_rcp_f32_e32 v33, v20
	v_add_f32_e32 v20, 1.0, v28
	v_rcp_f32_e32 v28, v20
	v_add_f32_e32 v20, 1.0, v29
	v_lshlrev_b32_e32 v29, 16, v22
	v_mul_f32_e32 v34, v29, v29
	v_and_b32_e32 v22, 0xffff0000, v22
	v_fmamk_f32 v34, v34, 0xbdd2d3e8, v245
	v_mul_f32_e32 v35, v22, v22
	v_mul_f32_e32 v34, v34, v29
	v_fmamk_f32 v35, v35, 0xbdd2d3e8, v245
	v_mul_f32_e32 v35, v35, v22
	v_exp_f32_e32 v34, v34
	v_exp_f32_e32 v35, v35
	v_mul_f32_e32 v25, v24, v24
	v_fmamk_f32 v25, v25, 0xbdd2d3e8, v245
	v_rcp_f32_e32 v36, v20
	v_add_f32_e32 v20, 1.0, v34
	v_mul_f32_e32 v25, v25, v24
	v_rcp_f32_e32 v34, v20
	v_add_f32_e32 v20, 1.0, v35
	v_lshlrev_b32_e32 v35, 16, v23
	v_mul_f32_e32 v37, v35, v35
	v_and_b32_e32 v23, 0xffff0000, v23
	v_fmamk_f32 v37, v37, 0xbdd2d3e8, v245
	v_mul_f32_e32 v38, v23, v23
	v_exp_f32_e32 v25, v25
	v_mul_f32_e32 v37, v37, v35
	v_fmamk_f32 v38, v38, 0xbdd2d3e8, v245
	v_mul_f32_e32 v38, v38, v23
	v_exp_f32_e32 v37, v37
	v_add_f32_e32 v25, 1.0, v25
	v_exp_f32_e32 v38, v38
	v_rcp_f32_e32 v25, v25
	v_rcp_f32_e32 v39, v20
	v_add_f32_e32 v20, 1.0, v37
	v_rcp_f32_e32 v37, v20
	v_add_f32_e32 v20, 1.0, v38
	v_rcp_f32_e32 v38, v20
	v_fma_f32 v20, v25, v24, 0
	v_fmac_f32_e32 v20, v33, v26
	v_fmac_f32_e32 v20, v28, v27
	v_fmac_f32_e32 v20, v36, v21
	v_fmac_f32_e32 v20, v34, v29
	v_fmac_f32_e32 v20, v39, v22
	v_fmac_f32_e32 v20, v37, v35
	v_fmac_f32_e32 v20, v38, v23
	s_nop 1
	v_add_f32_dpp v20, v20, v20 quad_perm:[1,0,3,2] row_mask:0xf bank_mask:0xf bound_ctrl:1
	s_nop 1
	v_add_f32_dpp v20, v20, v20 quad_perm:[2,3,0,1] row_mask:0xf bank_mask:0xf bound_ctrl:1
	s_nop 1
	v_add_f32_dpp v20, v20, v20 row_half_mirror row_mask:0xf bank_mask:0xf bound_ctrl:1
	s_nop 1
	v_add_f32_dpp v20, v20, v20 row_mirror row_mask:0xf bank_mask:0xf bound_ctrl:1
	s_nop 0
	v_readlane_b32 s6, v20, 16
	v_readlane_b32 s5, v20, 0
	s_nop 0
	v_mov_b32_e32 v40, s6
	v_readlane_b32 s6, v20, 48
	v_add_f32_e32 v40, s5, v40
	v_readlane_b32 s5, v20, 32
	v_mov_b32_e32 v20, s6
	s_nop 0
	v_add_f32_e32 v20, s5, v20
	v_add_f32_e32 v20, v40, v20
	v_mul_f32_e32 v20, 0x3b000000, v20
	v_fma_f32 v24, v25, v24, -v20
	v_fma_f32 v25, v33, v26, -v20
	v_mul_f32_e32 v25, v25, v25
	v_fmac_f32_e32 v25, v24, v24
	v_fma_f32 v24, v28, v27, -v20
	v_fmac_f32_e32 v25, v24, v24
	v_fma_f32 v21, v36, v21, -v20
	v_fmac_f32_e32 v25, v21, v21
	v_fma_f32 v21, v34, v29, -v20
	v_fmac_f32_e32 v25, v21, v21
	v_fma_f32 v21, v39, v22, -v20
	v_fmac_f32_e32 v25, v21, v21
	v_fma_f32 v21, v37, v35, -v20
	v_fmac_f32_e32 v25, v21, v21
	v_fma_f32 v21, v38, v23, -v20
	v_fmac_f32_e32 v25, v21, v21
	s_nop 1
	v_add_f32_dpp v21, v25, v25 quad_perm:[1,0,3,2] row_mask:0xf bank_mask:0xf bound_ctrl:1
	s_nop 1
	v_add_f32_dpp v21, v21, v21 quad_perm:[2,3,0,1] row_mask:0xf bank_mask:0xf bound_ctrl:1
	s_nop 1
	v_add_f32_dpp v21, v21, v21 row_half_mirror row_mask:0xf bank_mask:0xf bound_ctrl:1
	s_nop 1
	v_add_f32_dpp v21, v21, v21 row_mirror row_mask:0xf bank_mask:0xf bound_ctrl:1
	s_nop 0
	v_readlane_b32 s44, v21, 0
	v_readlane_b32 s5, v21, 16
	v_readlane_b32 s45, v21, 32
	v_readlane_b32 s6, v21, 48
	s_and_saveexec_b64 s[82:83], s[42:43]
	s_cbranch_execz .LBB0_404
	v_mov_b32_e32 v22, s5
	v_mov_b32_e32 v23, s6
	v_pk_add_f32 v[22:23], s[44:45], v[22:23]
	s_nop 0
	v_add_f32_e32 v21, v22, v23
	v_fmamk_f32 v21, v21, 0x3b000000, v176
	v_rsq_f32_e32 v21, v21
	ds_write_b64 v30, v[20:21] offset:16
.LBB0_404:
	s_or_b64 exec, exec, s[82:83]
	s_waitcnt vmcnt(4)
	v_and_b32_e32 v22, 0xffff0000, v16
	v_lshlrev_b32_e32 v20, 16, v16
	v_mul_f32_e32 v16, v22, v22
	v_lshlrev_b32_e32 v23, 16, v17
	v_fmamk_f32 v16, v16, 0xbdd2d3e8, v245
	v_mul_f32_e32 v24, v23, v23
	v_and_b32_e32 v17, 0xffff0000, v17
	v_mul_f32_e32 v16, v16, v22
	v_fmamk_f32 v24, v24, 0xbdd2d3e8, v245
	v_mul_f32_e32 v25, v17, v17
	v_mul_f32_e32 v24, v24, v23
	v_fmamk_f32 v25, v25, 0xbdd2d3e8, v245
	v_mul_f32_e32 v25, v25, v17
	v_exp_f32_e32 v16, v16
	v_exp_f32_e32 v24, v24
	v_exp_f32_e32 v25, v25
	v_add_f32_e32 v16, 1.0, v16
	v_rcp_f32_e32 v26, v16
	v_add_f32_e32 v16, 1.0, v24
	v_rcp_f32_e32 v24, v16
	v_add_f32_e32 v16, 1.0, v25
	v_lshlrev_b32_e32 v25, 16, v18
	v_mul_f32_e32 v27, v25, v25
	v_and_b32_e32 v18, 0xffff0000, v18
	v_fmamk_f32 v27, v27, 0xbdd2d3e8, v245
	v_mul_f32_e32 v28, v18, v18
	v_mul_f32_e32 v27, v27, v25
	v_fmamk_f32 v28, v28, 0xbdd2d3e8, v245
	v_mul_f32_e32 v28, v28, v18
	v_exp_f32_e32 v27, v27
	v_exp_f32_e32 v28, v28
	v_mul_f32_e32 v21, v20, v20
	v_fmamk_f32 v21, v21, 0xbdd2d3e8, v245
	v_rcp_f32_e32 v29, v16
	v_add_f32_e32 v16, 1.0, v27
	v_mul_f32_e32 v21, v21, v20
	v_rcp_f32_e32 v27, v16
	v_add_f32_e32 v16, 1.0, v28
	v_lshlrev_b32_e32 v28, 16, v19
	v_mul_f32_e32 v33, v28, v28
	v_and_b32_e32 v19, 0xffff0000, v19
	v_fmamk_f32 v33, v33, 0xbdd2d3e8, v245
	v_mul_f32_e32 v34, v19, v19
	v_exp_f32_e32 v21, v21
	v_mul_f32_e32 v33, v33, v28
	v_fmamk_f32 v34, v34, 0xbdd2d3e8, v245
	v_mul_f32_e32 v34, v34, v19
	v_exp_f32_e32 v33, v33
	v_add_f32_e32 v21, 1.0, v21
	v_exp_f32_e32 v34, v34
	v_rcp_f32_e32 v21, v21
	v_rcp_f32_e32 v35, v16
	v_add_f32_e32 v16, 1.0, v33
	v_rcp_f32_e32 v33, v16
	v_add_f32_e32 v16, 1.0, v34
	v_rcp_f32_e32 v34, v16
	v_fma_f32 v16, v21, v20, 0
	v_fmac_f32_e32 v16, v26, v22
	v_fmac_f32_e32 v16, v24, v23
	v_fmac_f32_e32 v16, v29, v17
	v_fmac_f32_e32 v16, v27, v25
	v_fmac_f32_e32 v16, v35, v18
	v_fmac_f32_e32 v16, v33, v28
	v_fmac_f32_e32 v16, v34, v19
	s_nop 1
	v_add_f32_dpp v16, v16, v16 quad_perm:[1,0,3,2] row_mask:0xf bank_mask:0xf bound_ctrl:1
	s_nop 1
	v_add_f32_dpp v16, v16, v16 quad_perm:[2,3,0,1] row_mask:0xf bank_mask:0xf bound_ctrl:1
	s_nop 1
	v_add_f32_dpp v16, v16, v16 row_half_mirror row_mask:0xf bank_mask:0xf bound_ctrl:1
	s_nop 1
	v_add_f32_dpp v16, v16, v16 row_mirror row_mask:0xf bank_mask:0xf bound_ctrl:1
	s_nop 0
	v_readlane_b32 s6, v16, 16
	v_readlane_b32 s5, v16, 0
	s_nop 0
	v_mov_b32_e32 v36, s6
	v_readlane_b32 s6, v16, 48
	v_add_f32_e32 v36, s5, v36
	v_readlane_b32 s5, v16, 32
	v_mov_b32_e32 v16, s6
	s_nop 0
	v_add_f32_e32 v16, s5, v16
	v_add_f32_e32 v16, v36, v16
	v_mul_f32_e32 v16, 0x3b000000, v16
	v_fma_f32 v20, v21, v20, -v16
	v_fma_f32 v21, v26, v22, -v16
	v_mul_f32_e32 v21, v21, v21
	v_fmac_f32_e32 v21, v20, v20
	v_fma_f32 v20, v24, v23, -v16
	v_fmac_f32_e32 v21, v20, v20
	v_fma_f32 v17, v29, v17, -v16
	v_fmac_f32_e32 v21, v17, v17
	v_fma_f32 v17, v27, v25, -v16
	v_fmac_f32_e32 v21, v17, v17
	v_fma_f32 v17, v35, v18, -v16
	v_fmac_f32_e32 v21, v17, v17
	v_fma_f32 v17, v33, v28, -v16
	v_fmac_f32_e32 v21, v17, v17
	v_fma_f32 v17, v34, v19, -v16
	v_fmac_f32_e32 v21, v17, v17
	s_nop 1
	v_add_f32_dpp v17, v21, v21 quad_perm:[1,0,3,2] row_mask:0xf bank_mask:0xf bound_ctrl:1
	s_nop 1
	v_add_f32_dpp v17, v17, v17 quad_perm:[2,3,0,1] row_mask:0xf bank_mask:0xf bound_ctrl:1
	s_nop 1
	v_add_f32_dpp v17, v17, v17 row_half_mirror row_mask:0xf bank_mask:0xf bound_ctrl:1
	s_nop 1
	v_add_f32_dpp v17, v17, v17 row_mirror row_mask:0xf bank_mask:0xf bound_ctrl:1
	s_nop 0
	v_readlane_b32 s44, v17, 0
	v_readlane_b32 s5, v17, 16
	v_readlane_b32 s45, v17, 32
	v_readlane_b32 s6, v17, 48
	s_and_saveexec_b64 s[82:83], s[42:43]
	s_cbranch_execz .LBB0_406
	v_mov_b32_e32 v18, s5
	v_mov_b32_e32 v19, s6
	v_pk_add_f32 v[18:19], s[44:45], v[18:19]
	s_nop 0
	v_add_f32_e32 v17, v18, v19
	v_fmamk_f32 v17, v17, 0x3b000000, v176
	v_rsq_f32_e32 v17, v17
	ds_write_b64 v30, v[16:17] offset:24
.LBB0_406:
	s_or_b64 exec, exec, s[82:83]
	s_waitcnt vmcnt(3)
	v_and_b32_e32 v18, 0xffff0000, v12
	v_lshlrev_b32_e32 v16, 16, v12
	v_mul_f32_e32 v12, v18, v18
	v_lshlrev_b32_e32 v19, 16, v13
	v_fmamk_f32 v12, v12, 0xbdd2d3e8, v245
	v_mul_f32_e32 v20, v19, v19
	v_and_b32_e32 v13, 0xffff0000, v13
	v_mul_f32_e32 v12, v12, v18
	v_fmamk_f32 v20, v20, 0xbdd2d3e8, v245
	v_mul_f32_e32 v21, v13, v13
	v_mul_f32_e32 v20, v20, v19
	v_fmamk_f32 v21, v21, 0xbdd2d3e8, v245
	v_mul_f32_e32 v21, v21, v13
	v_exp_f32_e32 v12, v12
	v_exp_f32_e32 v20, v20
	v_exp_f32_e32 v21, v21
	v_add_f32_e32 v12, 1.0, v12
	v_rcp_f32_e32 v22, v12
	v_add_f32_e32 v12, 1.0, v20
	v_rcp_f32_e32 v20, v12
	v_add_f32_e32 v12, 1.0, v21
	v_lshlrev_b32_e32 v21, 16, v14
	v_mul_f32_e32 v23, v21, v21
	v_and_b32_e32 v14, 0xffff0000, v14
	v_fmamk_f32 v23, v23, 0xbdd2d3e8, v245
	v_mul_f32_e32 v24, v14, v14
	v_mul_f32_e32 v23, v23, v21
	v_fmamk_f32 v24, v24, 0xbdd2d3e8, v245
	v_mul_f32_e32 v24, v24, v14
	v_exp_f32_e32 v23, v23
	v_exp_f32_e32 v24, v24
	v_mul_f32_e32 v17, v16, v16
	v_fmamk_f32 v17, v17, 0xbdd2d3e8, v245
	v_rcp_f32_e32 v25, v12
	v_add_f32_e32 v12, 1.0, v23
	v_mul_f32_e32 v17, v17, v16
	v_rcp_f32_e32 v23, v12
	v_add_f32_e32 v12, 1.0, v24
	v_lshlrev_b32_e32 v24, 16, v15
	v_mul_f32_e32 v26, v24, v24
	v_and_b32_e32 v15, 0xffff0000, v15
	v_fmamk_f32 v26, v26, 0xbdd2d3e8, v245
	v_mul_f32_e32 v27, v15, v15
	v_exp_f32_e32 v17, v17
	v_mul_f32_e32 v26, v26, v24
	v_fmamk_f32 v27, v27, 0xbdd2d3e8, v245
	v_mul_f32_e32 v27, v27, v15
	v_exp_f32_e32 v26, v26
	v_add_f32_e32 v17, 1.0, v17
	v_exp_f32_e32 v27, v27
	v_rcp_f32_e32 v17, v17
	v_rcp_f32_e32 v28, v12
	v_add_f32_e32 v12, 1.0, v26
	v_rcp_f32_e32 v26, v12
	v_add_f32_e32 v12, 1.0, v27
	v_rcp_f32_e32 v27, v12
	v_fma_f32 v12, v17, v16, 0
	v_fmac_f32_e32 v12, v22, v18
	v_fmac_f32_e32 v12, v20, v19
	v_fmac_f32_e32 v12, v25, v13
	v_fmac_f32_e32 v12, v23, v21
	v_fmac_f32_e32 v12, v28, v14
	v_fmac_f32_e32 v12, v26, v24
	v_fmac_f32_e32 v12, v27, v15
	s_nop 1
	v_add_f32_dpp v12, v12, v12 quad_perm:[1,0,3,2] row_mask:0xf bank_mask:0xf bound_ctrl:1
	s_nop 1
	v_add_f32_dpp v12, v12, v12 quad_perm:[2,3,0,1] row_mask:0xf bank_mask:0xf bound_ctrl:1
	s_nop 1
	v_add_f32_dpp v12, v12, v12 row_half_mirror row_mask:0xf bank_mask:0xf bound_ctrl:1
	s_nop 1
	v_add_f32_dpp v12, v12, v12 row_mirror row_mask:0xf bank_mask:0xf bound_ctrl:1
	s_nop 0
	v_readlane_b32 s6, v12, 16
	v_readlane_b32 s5, v12, 0
	s_nop 0
	v_mov_b32_e32 v29, s6
	v_readlane_b32 s6, v12, 48
	v_add_f32_e32 v29, s5, v29
	v_readlane_b32 s5, v12, 32
	v_mov_b32_e32 v12, s6
	s_nop 0
	v_add_f32_e32 v12, s5, v12
	v_add_f32_e32 v12, v29, v12
	v_mul_f32_e32 v12, 0x3b000000, v12
	v_fma_f32 v16, v17, v16, -v12
	v_fma_f32 v17, v22, v18, -v12
	v_mul_f32_e32 v17, v17, v17
	v_fmac_f32_e32 v17, v16, v16
	v_fma_f32 v16, v20, v19, -v12
	v_fmac_f32_e32 v17, v16, v16
	v_fma_f32 v13, v25, v13, -v12
	v_fmac_f32_e32 v17, v13, v13
	v_fma_f32 v13, v23, v21, -v12
	v_fmac_f32_e32 v17, v13, v13
	v_fma_f32 v13, v28, v14, -v12
	v_fmac_f32_e32 v17, v13, v13
	v_fma_f32 v13, v26, v24, -v12
	v_fmac_f32_e32 v17, v13, v13
	v_fma_f32 v13, v27, v15, -v12
	v_fmac_f32_e32 v17, v13, v13
	s_nop 1
	v_add_f32_dpp v13, v17, v17 quad_perm:[1,0,3,2] row_mask:0xf bank_mask:0xf bound_ctrl:1
	s_nop 1
	v_add_f32_dpp v13, v13, v13 quad_perm:[2,3,0,1] row_mask:0xf bank_mask:0xf bound_ctrl:1
	s_nop 1
	v_add_f32_dpp v13, v13, v13 row_half_mirror row_mask:0xf bank_mask:0xf bound_ctrl:1
	s_nop 1
	v_add_f32_dpp v13, v13, v13 row_mirror row_mask:0xf bank_mask:0xf bound_ctrl:1
	s_nop 0
	v_readlane_b32 s44, v13, 0
	v_readlane_b32 s5, v13, 16
	v_readlane_b32 s45, v13, 32
	v_readlane_b32 s6, v13, 48
	s_and_saveexec_b64 s[82:83], s[42:43]
	s_cbranch_execz .LBB0_408
	v_mov_b32_e32 v14, s5
	v_mov_b32_e32 v15, s6
	v_pk_add_f32 v[14:15], s[44:45], v[14:15]
	s_nop 0
	v_add_f32_e32 v13, v14, v15
	v_fmamk_f32 v13, v13, 0x3b000000, v176
	v_rsq_f32_e32 v13, v13
	ds_write_b64 v30, v[12:13] offset:32
.LBB0_408:
	s_or_b64 exec, exec, s[82:83]
	s_waitcnt vmcnt(2)
	v_and_b32_e32 v14, 0xffff0000, v8
	v_lshlrev_b32_e32 v12, 16, v8
	v_mul_f32_e32 v8, v14, v14
	v_lshlrev_b32_e32 v15, 16, v9
	v_fmamk_f32 v8, v8, 0xbdd2d3e8, v245
	v_mul_f32_e32 v16, v15, v15
	v_and_b32_e32 v9, 0xffff0000, v9
	v_mul_f32_e32 v8, v8, v14
	v_fmamk_f32 v16, v16, 0xbdd2d3e8, v245
	v_mul_f32_e32 v17, v9, v9
	v_mul_f32_e32 v16, v16, v15
	v_fmamk_f32 v17, v17, 0xbdd2d3e8, v245
	v_mul_f32_e32 v17, v17, v9
	v_exp_f32_e32 v8, v8
	v_exp_f32_e32 v16, v16
	v_exp_f32_e32 v17, v17
	v_add_f32_e32 v8, 1.0, v8
	v_rcp_f32_e32 v18, v8
	v_add_f32_e32 v8, 1.0, v16
	v_rcp_f32_e32 v16, v8
	v_add_f32_e32 v8, 1.0, v17
	v_lshlrev_b32_e32 v17, 16, v10
	v_mul_f32_e32 v19, v17, v17
	v_and_b32_e32 v10, 0xffff0000, v10
	v_fmamk_f32 v19, v19, 0xbdd2d3e8, v245
	v_mul_f32_e32 v20, v10, v10
	v_mul_f32_e32 v19, v19, v17
	v_fmamk_f32 v20, v20, 0xbdd2d3e8, v245
	v_mul_f32_e32 v20, v20, v10
	v_exp_f32_e32 v19, v19
	v_exp_f32_e32 v20, v20
	v_mul_f32_e32 v13, v12, v12
	v_fmamk_f32 v13, v13, 0xbdd2d3e8, v245
	v_rcp_f32_e32 v21, v8
	v_add_f32_e32 v8, 1.0, v19
	v_mul_f32_e32 v13, v13, v12
	v_rcp_f32_e32 v19, v8
	v_add_f32_e32 v8, 1.0, v20
	v_lshlrev_b32_e32 v20, 16, v11
	v_mul_f32_e32 v22, v20, v20
	v_and_b32_e32 v11, 0xffff0000, v11
	v_fmamk_f32 v22, v22, 0xbdd2d3e8, v245
	v_mul_f32_e32 v23, v11, v11
	v_exp_f32_e32 v13, v13
	v_mul_f32_e32 v22, v22, v20
	v_fmamk_f32 v23, v23, 0xbdd2d3e8, v245
	v_mul_f32_e32 v23, v23, v11
	v_exp_f32_e32 v22, v22
	v_add_f32_e32 v13, 1.0, v13
	v_exp_f32_e32 v23, v23
	v_rcp_f32_e32 v13, v13
	v_rcp_f32_e32 v24, v8
	v_add_f32_e32 v8, 1.0, v22
	v_rcp_f32_e32 v22, v8
	v_add_f32_e32 v8, 1.0, v23
	v_rcp_f32_e32 v23, v8
	v_fma_f32 v8, v13, v12, 0
	v_fmac_f32_e32 v8, v18, v14
	v_fmac_f32_e32 v8, v16, v15
	v_fmac_f32_e32 v8, v21, v9
	v_fmac_f32_e32 v8, v19, v17
	v_fmac_f32_e32 v8, v24, v10
	v_fmac_f32_e32 v8, v22, v20
	v_fmac_f32_e32 v8, v23, v11
	s_nop 1
	v_add_f32_dpp v8, v8, v8 quad_perm:[1,0,3,2] row_mask:0xf bank_mask:0xf bound_ctrl:1
	s_nop 1
	v_add_f32_dpp v8, v8, v8 quad_perm:[2,3,0,1] row_mask:0xf bank_mask:0xf bound_ctrl:1
	s_nop 1
	v_add_f32_dpp v8, v8, v8 row_half_mirror row_mask:0xf bank_mask:0xf bound_ctrl:1
	s_nop 1
	v_add_f32_dpp v8, v8, v8 row_mirror row_mask:0xf bank_mask:0xf bound_ctrl:1
	s_nop 0
	v_readlane_b32 s6, v8, 16
	v_readlane_b32 s5, v8, 0
	s_nop 0
	v_mov_b32_e32 v25, s6
	v_readlane_b32 s6, v8, 48
	v_add_f32_e32 v25, s5, v25
	v_readlane_b32 s5, v8, 32
	v_mov_b32_e32 v8, s6
	s_nop 0
	v_add_f32_e32 v8, s5, v8
	v_add_f32_e32 v8, v25, v8
	v_mul_f32_e32 v8, 0x3b000000, v8
	v_fma_f32 v12, v13, v12, -v8
	v_fma_f32 v13, v18, v14, -v8
	v_mul_f32_e32 v13, v13, v13
	v_fmac_f32_e32 v13, v12, v12
	v_fma_f32 v12, v16, v15, -v8
	v_fmac_f32_e32 v13, v12, v12
	v_fma_f32 v9, v21, v9, -v8
	v_fmac_f32_e32 v13, v9, v9
	v_fma_f32 v9, v19, v17, -v8
	v_fmac_f32_e32 v13, v9, v9
	v_fma_f32 v9, v24, v10, -v8
	v_fmac_f32_e32 v13, v9, v9
	v_fma_f32 v9, v22, v20, -v8
	v_fmac_f32_e32 v13, v9, v9
	v_fma_f32 v9, v23, v11, -v8
	v_fmac_f32_e32 v13, v9, v9
	s_nop 1
	v_add_f32_dpp v9, v13, v13 quad_perm:[1,0,3,2] row_mask:0xf bank_mask:0xf bound_ctrl:1
	s_nop 1
	v_add_f32_dpp v9, v9, v9 quad_perm:[2,3,0,1] row_mask:0xf bank_mask:0xf bound_ctrl:1
	s_nop 1
	v_add_f32_dpp v9, v9, v9 row_half_mirror row_mask:0xf bank_mask:0xf bound_ctrl:1
	s_nop 1
	v_add_f32_dpp v9, v9, v9 row_mirror row_mask:0xf bank_mask:0xf bound_ctrl:1
	s_nop 0
	v_readlane_b32 s44, v9, 0
	v_readlane_b32 s5, v9, 16
	v_readlane_b32 s45, v9, 32
	v_readlane_b32 s6, v9, 48
	s_and_saveexec_b64 s[82:83], s[42:43]
	s_cbranch_execz .LBB0_410
	v_mov_b32_e32 v10, s5
	v_mov_b32_e32 v11, s6
	v_pk_add_f32 v[10:11], s[44:45], v[10:11]
	s_nop 0
	v_add_f32_e32 v9, v10, v11
	v_fmamk_f32 v9, v9, 0x3b000000, v176
	v_rsq_f32_e32 v9, v9
	ds_write_b64 v30, v[8:9] offset:40
.LBB0_410:
	s_or_b64 exec, exec, s[82:83]
	s_waitcnt vmcnt(1)
	v_and_b32_e32 v10, 0xffff0000, v4
	v_lshlrev_b32_e32 v8, 16, v4
	v_mul_f32_e32 v4, v10, v10
	v_lshlrev_b32_e32 v11, 16, v5
	v_fmamk_f32 v4, v4, 0xbdd2d3e8, v245
	v_mul_f32_e32 v12, v11, v11
	v_and_b32_e32 v5, 0xffff0000, v5
	v_mul_f32_e32 v4, v4, v10
	v_fmamk_f32 v12, v12, 0xbdd2d3e8, v245
	v_mul_f32_e32 v13, v5, v5
	v_mul_f32_e32 v12, v12, v11
	v_fmamk_f32 v13, v13, 0xbdd2d3e8, v245
	v_mul_f32_e32 v13, v13, v5
	v_exp_f32_e32 v4, v4
	v_exp_f32_e32 v12, v12
	v_exp_f32_e32 v13, v13
	v_add_f32_e32 v4, 1.0, v4
	v_rcp_f32_e32 v14, v4
	v_add_f32_e32 v4, 1.0, v12
	v_rcp_f32_e32 v12, v4
	v_add_f32_e32 v4, 1.0, v13
	v_lshlrev_b32_e32 v13, 16, v6
	v_mul_f32_e32 v15, v13, v13
	v_and_b32_e32 v6, 0xffff0000, v6
	v_fmamk_f32 v15, v15, 0xbdd2d3e8, v245
	v_mul_f32_e32 v16, v6, v6
	v_mul_f32_e32 v15, v15, v13
	v_fmamk_f32 v16, v16, 0xbdd2d3e8, v245
	v_mul_f32_e32 v16, v16, v6
	v_exp_f32_e32 v15, v15
	v_exp_f32_e32 v16, v16
	v_mul_f32_e32 v9, v8, v8
	v_fmamk_f32 v9, v9, 0xbdd2d3e8, v245
	v_rcp_f32_e32 v17, v4
	v_add_f32_e32 v4, 1.0, v15
	v_mul_f32_e32 v9, v9, v8
	v_rcp_f32_e32 v15, v4
	v_add_f32_e32 v4, 1.0, v16
	v_lshlrev_b32_e32 v16, 16, v7
	v_mul_f32_e32 v18, v16, v16
	v_and_b32_e32 v7, 0xffff0000, v7
	v_fmamk_f32 v18, v18, 0xbdd2d3e8, v245
	v_mul_f32_e32 v19, v7, v7
	v_exp_f32_e32 v9, v9
	v_mul_f32_e32 v18, v18, v16
	v_fmamk_f32 v19, v19, 0xbdd2d3e8, v245
	v_mul_f32_e32 v19, v19, v7
	v_exp_f32_e32 v18, v18
	v_add_f32_e32 v9, 1.0, v9
	v_exp_f32_e32 v19, v19
	v_rcp_f32_e32 v9, v9
	v_rcp_f32_e32 v20, v4
	v_add_f32_e32 v4, 1.0, v18
	v_rcp_f32_e32 v18, v4
	v_add_f32_e32 v4, 1.0, v19
	v_rcp_f32_e32 v19, v4
	v_fma_f32 v4, v9, v8, 0
	v_fmac_f32_e32 v4, v14, v10
	v_fmac_f32_e32 v4, v12, v11
	v_fmac_f32_e32 v4, v17, v5
	v_fmac_f32_e32 v4, v15, v13
	v_fmac_f32_e32 v4, v20, v6
	v_fmac_f32_e32 v4, v18, v16
	v_fmac_f32_e32 v4, v19, v7
	s_nop 1
	v_add_f32_dpp v4, v4, v4 quad_perm:[1,0,3,2] row_mask:0xf bank_mask:0xf bound_ctrl:1
	s_nop 1
	v_add_f32_dpp v4, v4, v4 quad_perm:[2,3,0,1] row_mask:0xf bank_mask:0xf bound_ctrl:1
	s_nop 1
	v_add_f32_dpp v4, v4, v4 row_half_mirror row_mask:0xf bank_mask:0xf bound_ctrl:1
	s_nop 1
	v_add_f32_dpp v4, v4, v4 row_mirror row_mask:0xf bank_mask:0xf bound_ctrl:1
	s_nop 0
	v_readlane_b32 s6, v4, 16
	v_readlane_b32 s5, v4, 0
	s_nop 0
	v_mov_b32_e32 v21, s6
	v_readlane_b32 s6, v4, 48
	v_add_f32_e32 v21, s5, v21
	v_readlane_b32 s5, v4, 32
	v_mov_b32_e32 v4, s6
	s_nop 0
	v_add_f32_e32 v4, s5, v4
	v_add_f32_e32 v4, v21, v4
	v_mul_f32_e32 v4, 0x3b000000, v4
	v_fma_f32 v8, v9, v8, -v4
	v_fma_f32 v9, v14, v10, -v4
	v_mul_f32_e32 v9, v9, v9
	v_fmac_f32_e32 v9, v8, v8
	v_fma_f32 v8, v12, v11, -v4
	v_fmac_f32_e32 v9, v8, v8
	v_fma_f32 v5, v17, v5, -v4
	v_fmac_f32_e32 v9, v5, v5
	v_fma_f32 v5, v15, v13, -v4
	v_fmac_f32_e32 v9, v5, v5
	v_fma_f32 v5, v20, v6, -v4
	v_fmac_f32_e32 v9, v5, v5
	v_fma_f32 v5, v18, v16, -v4
	v_fmac_f32_e32 v9, v5, v5
	v_fma_f32 v5, v19, v7, -v4
	v_fmac_f32_e32 v9, v5, v5
	s_nop 1
	v_add_f32_dpp v5, v9, v9 quad_perm:[1,0,3,2] row_mask:0xf bank_mask:0xf bound_ctrl:1
	s_nop 1
	v_add_f32_dpp v5, v5, v5 quad_perm:[2,3,0,1] row_mask:0xf bank_mask:0xf bound_ctrl:1
	s_nop 1
	v_add_f32_dpp v5, v5, v5 row_half_mirror row_mask:0xf bank_mask:0xf bound_ctrl:1
	s_nop 1
	v_add_f32_dpp v5, v5, v5 row_mirror row_mask:0xf bank_mask:0xf bound_ctrl:1
	s_nop 0
	v_readlane_b32 s44, v5, 0
	v_readlane_b32 s5, v5, 16
	v_readlane_b32 s45, v5, 32
	v_readlane_b32 s6, v5, 48
	s_and_saveexec_b64 s[82:83], s[42:43]
	s_cbranch_execz .LBB0_412
	v_mov_b32_e32 v6, s5
	v_mov_b32_e32 v7, s6
	v_pk_add_f32 v[6:7], s[44:45], v[6:7]
	s_nop 0
	v_add_f32_e32 v5, v6, v7
	v_fmamk_f32 v5, v5, 0x3b000000, v176
	v_rsq_f32_e32 v5, v5
	ds_write_b64 v30, v[4:5] offset:48
.LBB0_412:
	s_or_b64 exec, exec, s[82:83]
	s_waitcnt vmcnt(0)
	v_and_b32_e32 v6, 0xffff0000, v0
	v_lshlrev_b32_e32 v4, 16, v0
	v_mul_f32_e32 v0, v6, v6
	v_lshlrev_b32_e32 v7, 16, v1
	v_fmamk_f32 v0, v0, 0xbdd2d3e8, v245
	v_mul_f32_e32 v8, v7, v7
	v_and_b32_e32 v1, 0xffff0000, v1
	v_mul_f32_e32 v0, v0, v6
	v_fmamk_f32 v8, v8, 0xbdd2d3e8, v245
	v_mul_f32_e32 v9, v1, v1
	v_mul_f32_e32 v8, v8, v7
	v_fmamk_f32 v9, v9, 0xbdd2d3e8, v245
	v_mul_f32_e32 v9, v9, v1
	v_exp_f32_e32 v0, v0
	v_exp_f32_e32 v8, v8
	v_exp_f32_e32 v9, v9
	v_add_f32_e32 v0, 1.0, v0
	v_rcp_f32_e32 v10, v0
	v_add_f32_e32 v0, 1.0, v8
	v_rcp_f32_e32 v8, v0
	v_add_f32_e32 v0, 1.0, v9
	v_lshlrev_b32_e32 v9, 16, v2
	v_mul_f32_e32 v11, v9, v9
	v_and_b32_e32 v2, 0xffff0000, v2
	v_fmamk_f32 v11, v11, 0xbdd2d3e8, v245
	v_mul_f32_e32 v12, v2, v2
	v_mul_f32_e32 v11, v11, v9
	v_fmamk_f32 v12, v12, 0xbdd2d3e8, v245
	v_mul_f32_e32 v12, v12, v2
	v_exp_f32_e32 v11, v11
	v_exp_f32_e32 v12, v12
	v_mul_f32_e32 v5, v4, v4
	v_fmamk_f32 v5, v5, 0xbdd2d3e8, v245
	v_rcp_f32_e32 v13, v0
	v_add_f32_e32 v0, 1.0, v11
	v_mul_f32_e32 v5, v5, v4
	v_rcp_f32_e32 v11, v0
	v_add_f32_e32 v0, 1.0, v12
	v_lshlrev_b32_e32 v12, 16, v3
	v_mul_f32_e32 v14, v12, v12
	v_and_b32_e32 v3, 0xffff0000, v3
	v_fmamk_f32 v14, v14, 0xbdd2d3e8, v245
	v_mul_f32_e32 v15, v3, v3
	v_exp_f32_e32 v5, v5
	v_mul_f32_e32 v14, v14, v12
	v_fmamk_f32 v15, v15, 0xbdd2d3e8, v245
	v_mul_f32_e32 v15, v15, v3
	v_exp_f32_e32 v14, v14
	v_add_f32_e32 v5, 1.0, v5
	v_exp_f32_e32 v15, v15
	v_rcp_f32_e32 v5, v5
	v_rcp_f32_e32 v16, v0
	v_add_f32_e32 v0, 1.0, v14
	v_rcp_f32_e32 v14, v0
	v_add_f32_e32 v0, 1.0, v15
	v_rcp_f32_e32 v15, v0
	v_fma_f32 v0, v5, v4, 0
	v_fmac_f32_e32 v0, v10, v6
	v_fmac_f32_e32 v0, v8, v7
	v_fmac_f32_e32 v0, v13, v1
	v_fmac_f32_e32 v0, v11, v9
	v_fmac_f32_e32 v0, v16, v2
	v_fmac_f32_e32 v0, v14, v12
	v_fmac_f32_e32 v0, v15, v3
	s_nop 1
	v_add_f32_dpp v0, v0, v0 quad_perm:[1,0,3,2] row_mask:0xf bank_mask:0xf bound_ctrl:1
	s_nop 1
	v_add_f32_dpp v0, v0, v0 quad_perm:[2,3,0,1] row_mask:0xf bank_mask:0xf bound_ctrl:1
	s_nop 1
	v_add_f32_dpp v0, v0, v0 row_half_mirror row_mask:0xf bank_mask:0xf bound_ctrl:1
	s_nop 1
	v_add_f32_dpp v0, v0, v0 row_mirror row_mask:0xf bank_mask:0xf bound_ctrl:1
	s_nop 0
	v_readlane_b32 s6, v0, 16
	v_readlane_b32 s5, v0, 0
	s_nop 0
	v_mov_b32_e32 v17, s6
	v_readlane_b32 s6, v0, 48
	v_add_f32_e32 v17, s5, v17
	v_readlane_b32 s5, v0, 32
	v_mov_b32_e32 v0, s6
	s_nop 0
	v_add_f32_e32 v0, s5, v0
	v_add_f32_e32 v0, v17, v0
	v_mul_f32_e32 v0, 0x3b000000, v0
	v_fma_f32 v4, v5, v4, -v0
	v_fma_f32 v5, v10, v6, -v0
	v_mul_f32_e32 v5, v5, v5
	v_fmac_f32_e32 v5, v4, v4
	v_fma_f32 v4, v8, v7, -v0
	v_fmac_f32_e32 v5, v4, v4
	v_fma_f32 v1, v13, v1, -v0
	v_fmac_f32_e32 v5, v1, v1
	v_fma_f32 v1, v11, v9, -v0
	v_fmac_f32_e32 v5, v1, v1
	v_fma_f32 v1, v16, v2, -v0
	v_fmac_f32_e32 v5, v1, v1
	v_fma_f32 v1, v14, v12, -v0
	v_fmac_f32_e32 v5, v1, v1
	v_fma_f32 v1, v15, v3, -v0
	v_fmac_f32_e32 v5, v1, v1
	s_nop 1
	v_add_f32_dpp v1, v5, v5 quad_perm:[1,0,3,2] row_mask:0xf bank_mask:0xf bound_ctrl:1
	s_nop 1
	v_add_f32_dpp v1, v1, v1 quad_perm:[2,3,0,1] row_mask:0xf bank_mask:0xf bound_ctrl:1
	s_nop 1
	v_add_f32_dpp v1, v1, v1 row_half_mirror row_mask:0xf bank_mask:0xf bound_ctrl:1
	s_nop 1
	v_add_f32_dpp v1, v1, v1 row_mirror row_mask:0xf bank_mask:0xf bound_ctrl:1
	s_nop 0
	v_readlane_b32 s44, v1, 0
	v_readlane_b32 s5, v1, 16
	v_readlane_b32 s45, v1, 32
	v_readlane_b32 s6, v1, 48
	s_and_saveexec_b64 s[82:83], s[42:43]
	s_cbranch_execz .LBB0_414
	v_mov_b32_e32 v2, s5
	v_mov_b32_e32 v3, s6
	v_pk_add_f32 v[2:3], s[44:45], v[2:3]
	s_nop 0
	v_add_f32_e32 v1, v2, v3
	v_fmamk_f32 v1, v1, 0x3b000000, v176
	v_rsq_f32_e32 v1, v1
	ds_write_b64 v30, v[0:1] offset:56
.LBB0_414:
	s_or_b64 exec, exec, s[82:83]
	v_lshlrev_b32_e32 v4, 3, v127
	v_or_b32_e32 v2, 8, v31
	v_mov_b64_e32 v[0:1], s[76:77]
	v_mad_i64_i32 v[2:3], s[6:7], v2, s62, v[0:1]
	v_lshlrev_b32_e32 v144, 1, v4
	v_lshl_add_u64 v[2:3], v[2:3], 0, v[144:145]
	v_add_co_u32_e32 v2, vcc, 0x2000, v2
	v_or_b32_e32 v4, 10, v31
	s_nop 0
	v_addc_co_u32_e32 v3, vcc, 0, v3, vcc
	global_load_dwordx4 v[34:37], v[2:3], off
	v_or_b32_e32 v2, 9, v31
	v_mad_i64_i32 v[2:3], s[6:7], v2, s62, v[0:1]
	v_lshl_add_u64 v[2:3], v[2:3], 0, v[144:145]
	v_mad_i64_i32 v[4:5], s[6:7], v4, s62, v[0:1]
	v_add_co_u32_e32 v2, vcc, 0x2000, v2
	v_or_b32_e32 v6, 11, v31
	v_lshl_add_u64 v[4:5], v[4:5], 0, v[144:145]
	v_addc_co_u32_e32 v3, vcc, 0, v3, vcc
	v_mad_i64_i32 v[6:7], s[6:7], v6, s62, v[0:1]
	v_add_co_u32_e32 v4, vcc, 0x2000, v4
	v_or_b32_e32 v8, 12, v31
	v_lshl_add_u64 v[6:7], v[6:7], 0, v[144:145]
	v_addc_co_u32_e32 v5, vcc, 0, v5, vcc
	v_mad_i64_i32 v[8:9], s[6:7], v8, s62, v[0:1]
	global_load_dwordx4 v[24:27], v[2:3], off
	v_add_co_u32_e32 v2, vcc, 0x2000, v6
	v_or_b32_e32 v10, 13, v31
	v_lshl_add_u64 v[8:9], v[8:9], 0, v[144:145]
	v_addc_co_u32_e32 v3, vcc, 0, v7, vcc
	v_mad_i64_i32 v[10:11], s[6:7], v10, s62, v[0:1]
	v_add_co_u32_e32 v6, vcc, 0x2000, v8
	v_or_b32_e32 v12, 14, v31
	v_lshl_add_u64 v[10:11], v[10:11], 0, v[144:145]
	v_addc_co_u32_e32 v7, vcc, 0, v9, vcc
	v_mad_i64_i32 v[12:13], s[6:7], v12, s62, v[0:1]
	global_load_dwordx4 v[20:23], v[4:5], off
	global_load_dwordx4 v[16:19], v[2:3], off
	v_add_co_u32_e32 v2, vcc, 0x2000, v10
	v_lshl_add_u64 v[28:29], v[12:13], 0, v[144:145]
	s_nop 0
	v_addc_co_u32_e32 v3, vcc, 0, v11, vcc
	v_add_co_u32_e32 v4, vcc, 0x2000, v28
	v_or_b32_e32 v14, 15, v31
	s_nop 0
	v_addc_co_u32_e32 v5, vcc, 0, v29, vcc
	v_mad_i64_i32 v[0:1], s[6:7], v14, s62, v[0:1]
	global_load_dwordx4 v[12:15], v[6:7], off
	global_load_dwordx4 v[8:11], v[2:3], off
	v_lshl_add_u64 v[0:1], v[0:1], 0, v[144:145]
	v_add_co_u32_e32 v0, vcc, 0x2000, v0
	s_waitcnt vmcnt(5)
	v_lshlrev_b32_e32 v29, 16, v34
	v_mul_f32_e32 v2, v29, v29
	v_and_b32_e32 v31, 0xffff0000, v34
	v_fmamk_f32 v2, v2, 0xbdd2d3e8, v245
	v_mul_f32_e32 v3, 0x3d372713, v31
	v_mul_f32_e32 v2, v2, v29
	v_mul_f32_e32 v3, v3, v31
	v_fma_f32 v3, v3, v31, v31
	v_exp_f32_e32 v28, v2
	v_mul_f32_e32 v2, 0x3fcc422a, v3
	v_addc_co_u32_e32 v1, vcc, 0, v1, vcc
	v_mul_f32_e32 v2, 0xbfb8aa3b, v2
	v_exp_f32_e32 v33, v2
	global_load_dwordx4 v[4:7], v[4:5], off
	s_nop 0
	global_load_dwordx4 v[0:3], v[0:1], off
	v_add_f32_e32 v28, 1.0, v28
	v_rcp_f32_e32 v34, v28
	v_add_f32_e32 v28, 1.0, v33
	v_lshlrev_b32_e32 v33, 16, v35
	v_mul_f32_e32 v38, v33, v33
	v_and_b32_e32 v35, 0xffff0000, v35
	v_fmamk_f32 v38, v38, 0xbdd2d3e8, v245
	v_mul_f32_e32 v39, v35, v35
	v_mul_f32_e32 v38, v38, v33
	v_fmamk_f32 v39, v39, 0xbdd2d3e8, v245
	v_mul_f32_e32 v39, v39, v35
	v_exp_f32_e32 v38, v38
	v_exp_f32_e32 v39, v39
	v_rcp_f32_e32 v40, v28
	v_add_f32_e32 v28, 1.0, v38
	v_rcp_f32_e32 v38, v28
	v_add_f32_e32 v28, 1.0, v39
	v_lshlrev_b32_e32 v39, 16, v36
	v_mul_f32_e32 v41, v39, v39
	v_and_b32_e32 v36, 0xffff0000, v36
	v_fmamk_f32 v41, v41, 0xbdd2d3e8, v245
	v_mul_f32_e32 v42, v36, v36
	v_mul_f32_e32 v41, v41, v39
	v_fmamk_f32 v42, v42, 0xbdd2d3e8, v245
	v_mul_f32_e32 v42, v42, v36
	v_exp_f32_e32 v41, v41
	v_exp_f32_e32 v42, v42
	v_rcp_f32_e32 v43, v28
	v_add_f32_e32 v28, 1.0, v41
	v_rcp_f32_e32 v41, v28
	v_add_f32_e32 v28, 1.0, v42
	v_lshlrev_b32_e32 v42, 16, v37
	v_mul_f32_e32 v44, v42, v42
	v_and_b32_e32 v37, 0xffff0000, v37
	v_fmamk_f32 v44, v44, 0xbdd2d3e8, v245
	v_mul_f32_e32 v45, v37, v37
	v_mul_f32_e32 v44, v44, v42
	v_fmamk_f32 v45, v45, 0xbdd2d3e8, v245
	v_mul_f32_e32 v45, v45, v37
	v_exp_f32_e32 v44, v44
	v_exp_f32_e32 v45, v45
	v_rcp_f32_e32 v46, v28
	v_add_f32_e32 v28, 1.0, v44
	v_rcp_f32_e32 v44, v28
	v_add_f32_e32 v28, 1.0, v45
	v_rcp_f32_e32 v45, v28
	v_fma_f32 v28, v34, v29, 0
	v_fmac_f32_e32 v28, v40, v31
	v_fmac_f32_e32 v28, v38, v33
	v_fmac_f32_e32 v28, v43, v35
	v_fmac_f32_e32 v28, v41, v39
	v_fmac_f32_e32 v28, v46, v36
	v_fmac_f32_e32 v28, v44, v42
	v_fmac_f32_e32 v28, v45, v37
	s_nop 1
	v_add_f32_dpp v28, v28, v28 quad_perm:[1,0,3,2] row_mask:0xf bank_mask:0xf bound_ctrl:1
	s_nop 1
	v_add_f32_dpp v28, v28, v28 quad_perm:[2,3,0,1] row_mask:0xf bank_mask:0xf bound_ctrl:1
	s_nop 1
	v_add_f32_dpp v28, v28, v28 row_half_mirror row_mask:0xf bank_mask:0xf bound_ctrl:1
	s_nop 1
	v_add_f32_dpp v28, v28, v28 row_mirror row_mask:0xf bank_mask:0xf bound_ctrl:1
	s_nop 0
	v_readlane_b32 s6, v28, 16
	v_readlane_b32 s5, v28, 0
	s_nop 0
	v_mov_b32_e32 v47, s6
	v_readlane_b32 s6, v28, 48
	v_add_f32_e32 v47, s5, v47
	v_readlane_b32 s5, v28, 32
	v_mov_b32_e32 v28, s6
	s_nop 0
	v_add_f32_e32 v28, s5, v28
	v_add_f32_e32 v28, v47, v28
	v_mul_f32_e32 v28, 0x3b000000, v28
	v_fma_f32 v31, v40, v31, -v28
	v_fma_f32 v29, v34, v29, -v28
	v_mul_f32_e32 v31, v31, v31
	v_fmac_f32_e32 v31, v29, v29
	v_fma_f32 v29, v38, v33, -v28
	v_fmac_f32_e32 v31, v29, v29
	v_fma_f32 v29, v43, v35, -v28
	v_fmac_f32_e32 v31, v29, v29
	v_fma_f32 v29, v41, v39, -v28
	v_fmac_f32_e32 v31, v29, v29
	v_fma_f32 v29, v46, v36, -v28
	v_fmac_f32_e32 v31, v29, v29
	v_fma_f32 v29, v44, v42, -v28
	v_fmac_f32_e32 v31, v29, v29
	v_fma_f32 v29, v45, v37, -v28
	v_fmac_f32_e32 v31, v29, v29
	s_nop 1
	v_add_f32_dpp v29, v31, v31 quad_perm:[1,0,3,2] row_mask:0xf bank_mask:0xf bound_ctrl:1
	s_nop 1
	v_add_f32_dpp v29, v29, v29 quad_perm:[2,3,0,1] row_mask:0xf bank_mask:0xf bound_ctrl:1
	s_nop 1
	v_add_f32_dpp v29, v29, v29 row_half_mirror row_mask:0xf bank_mask:0xf bound_ctrl:1
	s_nop 1
	v_add_f32_dpp v29, v29, v29 row_mirror row_mask:0xf bank_mask:0xf bound_ctrl:1
	s_nop 0
	v_readlane_b32 s44, v29, 0
	v_readlane_b32 s5, v29, 16
	v_readlane_b32 s45, v29, 32
	v_readlane_b32 s6, v29, 48
	s_and_saveexec_b64 s[82:83], s[42:43]
	s_cbranch_execz .LBB0_416
	v_mov_b32_e32 v34, s5
	v_mov_b32_e32 v35, s6
	v_pk_add_f32 v[34:35], s[44:45], v[34:35]
	s_nop 0
	v_add_f32_e32 v29, v34, v35
	v_fmamk_f32 v29, v29, 0x3b000000, v176
	v_rsq_f32_e32 v29, v29
	ds_write_b64 v30, v[28:29] offset:64
.LBB0_416:
	s_or_b64 exec, exec, s[82:83]
	s_waitcnt vmcnt(6)
	v_and_b32_e32 v31, 0xffff0000, v24
	v_lshlrev_b32_e32 v28, 16, v24
	v_mul_f32_e32 v24, v31, v31
	v_lshlrev_b32_e32 v33, 16, v25
	v_fmamk_f32 v24, v24, 0xbdd2d3e8, v245
	v_mul_f32_e32 v34, v33, v33
	v_and_b32_e32 v25, 0xffff0000, v25
	v_mul_f32_e32 v24, v24, v31
	v_fmamk_f32 v34, v34, 0xbdd2d3e8, v245
	v_mul_f32_e32 v35, v25, v25
	v_mul_f32_e32 v34, v34, v33
	v_fmamk_f32 v35, v35, 0xbdd2d3e8, v245
	v_mul_f32_e32 v35, v35, v25
	v_exp_f32_e32 v24, v24
	v_exp_f32_e32 v34, v34
	v_exp_f32_e32 v35, v35
	v_add_f32_e32 v24, 1.0, v24
	v_rcp_f32_e32 v36, v24
	v_add_f32_e32 v24, 1.0, v34
	v_rcp_f32_e32 v34, v24
	v_add_f32_e32 v24, 1.0, v35
	v_lshlrev_b32_e32 v35, 16, v26
	v_mul_f32_e32 v37, v35, v35
	v_and_b32_e32 v26, 0xffff0000, v26
	v_fmamk_f32 v37, v37, 0xbdd2d3e8, v245
	v_mul_f32_e32 v38, v26, v26
	v_mul_f32_e32 v37, v37, v35
	v_fmamk_f32 v38, v38, 0xbdd2d3e8, v245
	v_mul_f32_e32 v38, v38, v26
	v_exp_f32_e32 v37, v37
	v_exp_f32_e32 v38, v38
	v_mul_f32_e32 v29, v28, v28
	v_fmamk_f32 v29, v29, 0xbdd2d3e8, v245
	v_rcp_f32_e32 v39, v24
	v_add_f32_e32 v24, 1.0, v37
	v_mul_f32_e32 v29, v29, v28
	v_rcp_f32_e32 v37, v24
	v_add_f32_e32 v24, 1.0, v38
	v_lshlrev_b32_e32 v38, 16, v27
	v_mul_f32_e32 v40, v38, v38
	v_and_b32_e32 v27, 0xffff0000, v27
	v_fmamk_f32 v40, v40, 0xbdd2d3e8, v245
	v_mul_f32_e32 v41, v27, v27
	v_exp_f32_e32 v29, v29
	v_mul_f32_e32 v40, v40, v38
	v_fmamk_f32 v41, v41, 0xbdd2d3e8, v245
	v_mul_f32_e32 v41, v41, v27
	v_exp_f32_e32 v40, v40
	v_add_f32_e32 v29, 1.0, v29
	v_exp_f32_e32 v41, v41
	v_rcp_f32_e32 v29, v29
	v_rcp_f32_e32 v42, v24
	v_add_f32_e32 v24, 1.0, v40
	v_rcp_f32_e32 v40, v24
	v_add_f32_e32 v24, 1.0, v41
	v_rcp_f32_e32 v41, v24
	v_fma_f32 v24, v29, v28, 0
	v_fmac_f32_e32 v24, v36, v31
	v_fmac_f32_e32 v24, v34, v33
	v_fmac_f32_e32 v24, v39, v25
	v_fmac_f32_e32 v24, v37, v35
	v_fmac_f32_e32 v24, v42, v26
	v_fmac_f32_e32 v24, v40, v38
	v_fmac_f32_e32 v24, v41, v27
	s_nop 1
	v_add_f32_dpp v24, v24, v24 quad_perm:[1,0,3,2] row_mask:0xf bank_mask:0xf bound_ctrl:1
	s_nop 1
	v_add_f32_dpp v24, v24, v24 quad_perm:[2,3,0,1] row_mask:0xf bank_mask:0xf bound_ctrl:1
	s_nop 1
	v_add_f32_dpp v24, v24, v24 row_half_mirror row_mask:0xf bank_mask:0xf bound_ctrl:1
	s_nop 1
	v_add_f32_dpp v24, v24, v24 row_mirror row_mask:0xf bank_mask:0xf bound_ctrl:1
	s_nop 0
	v_readlane_b32 s6, v24, 16
	v_readlane_b32 s5, v24, 0
	s_nop 0
	v_mov_b32_e32 v43, s6
	v_readlane_b32 s6, v24, 48
	v_add_f32_e32 v43, s5, v43
	v_readlane_b32 s5, v24, 32
	v_mov_b32_e32 v24, s6
	s_nop 0
	v_add_f32_e32 v24, s5, v24
	v_add_f32_e32 v24, v43, v24
	v_mul_f32_e32 v24, 0x3b000000, v24
	v_fma_f32 v28, v29, v28, -v24
	v_fma_f32 v29, v36, v31, -v24
	v_mul_f32_e32 v29, v29, v29
	v_fmac_f32_e32 v29, v28, v28
	v_fma_f32 v28, v34, v33, -v24
	v_fmac_f32_e32 v29, v28, v28
	v_fma_f32 v25, v39, v25, -v24
	v_fmac_f32_e32 v29, v25, v25
	v_fma_f32 v25, v37, v35, -v24
	v_fmac_f32_e32 v29, v25, v25
	v_fma_f32 v25, v42, v26, -v24
	v_fmac_f32_e32 v29, v25, v25
	v_fma_f32 v25, v40, v38, -v24
	v_fmac_f32_e32 v29, v25, v25
	v_fma_f32 v25, v41, v27, -v24
	v_fmac_f32_e32 v29, v25, v25
	s_nop 1
	v_add_f32_dpp v25, v29, v29 quad_perm:[1,0,3,2] row_mask:0xf bank_mask:0xf bound_ctrl:1
	s_nop 1
	v_add_f32_dpp v25, v25, v25 quad_perm:[2,3,0,1] row_mask:0xf bank_mask:0xf bound_ctrl:1
	s_nop 1
	v_add_f32_dpp v25, v25, v25 row_half_mirror row_mask:0xf bank_mask:0xf bound_ctrl:1
	s_nop 1
	v_add_f32_dpp v25, v25, v25 row_mirror row_mask:0xf bank_mask:0xf bound_ctrl:1
	s_nop 0
	v_readlane_b32 s44, v25, 0
	v_readlane_b32 s5, v25, 16
	v_readlane_b32 s45, v25, 32
	v_readlane_b32 s6, v25, 48
	s_and_saveexec_b64 s[82:83], s[42:43]
	s_cbranch_execz .LBB0_418
	v_mov_b32_e32 v26, s5
	v_mov_b32_e32 v27, s6
	v_pk_add_f32 v[26:27], s[44:45], v[26:27]
	s_nop 0
	v_add_f32_e32 v25, v26, v27
	v_fmamk_f32 v25, v25, 0x3b000000, v176
	v_rsq_f32_e32 v25, v25
	ds_write_b64 v30, v[24:25] offset:72
.LBB0_418:
	s_or_b64 exec, exec, s[82:83]
	s_waitcnt vmcnt(5)
	v_and_b32_e32 v26, 0xffff0000, v20
	v_lshlrev_b32_e32 v24, 16, v20
	v_mul_f32_e32 v20, v26, v26
	v_lshlrev_b32_e32 v27, 16, v21
	v_fmamk_f32 v20, v20, 0xbdd2d3e8, v245
	v_mul_f32_e32 v28, v27, v27
	v_and_b32_e32 v21, 0xffff0000, v21
	v_mul_f32_e32 v20, v20, v26
	v_fmamk_f32 v28, v28, 0xbdd2d3e8, v245
	v_mul_f32_e32 v29, v21, v21
	v_mul_f32_e32 v28, v28, v27
	v_fmamk_f32 v29, v29, 0xbdd2d3e8, v245
	v_mul_f32_e32 v29, v29, v21
	v_exp_f32_e32 v20, v20
	v_exp_f32_e32 v28, v28
	v_exp_f32_e32 v29, v29
	v_add_f32_e32 v20, 1.0, v20
	v_rcp_f32_e32 v31, v20
	v_add_f32_e32 v20, 1.0, v28
	v_rcp_f32_e32 v28, v20
	v_add_f32_e32 v20, 1.0, v29
	v_lshlrev_b32_e32 v29, 16, v22
	v_mul_f32_e32 v33, v29, v29
	v_and_b32_e32 v22, 0xffff0000, v22
	v_fmamk_f32 v33, v33, 0xbdd2d3e8, v245
	v_mul_f32_e32 v34, v22, v22
	v_mul_f32_e32 v33, v33, v29
	v_fmamk_f32 v34, v34, 0xbdd2d3e8, v245
	v_mul_f32_e32 v34, v34, v22
	v_exp_f32_e32 v33, v33
	v_exp_f32_e32 v34, v34
	v_mul_f32_e32 v25, v24, v24
	v_fmamk_f32 v25, v25, 0xbdd2d3e8, v245
	v_rcp_f32_e32 v35, v20
	v_add_f32_e32 v20, 1.0, v33
	v_mul_f32_e32 v25, v25, v24
	v_rcp_f32_e32 v33, v20
	v_add_f32_e32 v20, 1.0, v34
	v_lshlrev_b32_e32 v34, 16, v23
	v_mul_f32_e32 v36, v34, v34
	v_and_b32_e32 v23, 0xffff0000, v23
	v_fmamk_f32 v36, v36, 0xbdd2d3e8, v245
	v_mul_f32_e32 v37, v23, v23
	v_exp_f32_e32 v25, v25
	v_mul_f32_e32 v36, v36, v34
	v_fmamk_f32 v37, v37, 0xbdd2d3e8, v245
	v_mul_f32_e32 v37, v37, v23
	v_exp_f32_e32 v36, v36
	v_add_f32_e32 v25, 1.0, v25
	v_exp_f32_e32 v37, v37
	v_rcp_f32_e32 v25, v25
	v_rcp_f32_e32 v38, v20
	v_add_f32_e32 v20, 1.0, v36
	v_rcp_f32_e32 v36, v20
	v_add_f32_e32 v20, 1.0, v37
	v_rcp_f32_e32 v37, v20
	v_fma_f32 v20, v25, v24, 0
	v_fmac_f32_e32 v20, v31, v26
	v_fmac_f32_e32 v20, v28, v27
	v_fmac_f32_e32 v20, v35, v21
	v_fmac_f32_e32 v20, v33, v29
	v_fmac_f32_e32 v20, v38, v22
	v_fmac_f32_e32 v20, v36, v34
	v_fmac_f32_e32 v20, v37, v23
	s_nop 1
	v_add_f32_dpp v20, v20, v20 quad_perm:[1,0,3,2] row_mask:0xf bank_mask:0xf bound_ctrl:1
	s_nop 1
	v_add_f32_dpp v20, v20, v20 quad_perm:[2,3,0,1] row_mask:0xf bank_mask:0xf bound_ctrl:1
	s_nop 1
	v_add_f32_dpp v20, v20, v20 row_half_mirror row_mask:0xf bank_mask:0xf bound_ctrl:1
	s_nop 1
	v_add_f32_dpp v20, v20, v20 row_mirror row_mask:0xf bank_mask:0xf bound_ctrl:1
	s_nop 0
	v_readlane_b32 s6, v20, 16
	v_readlane_b32 s5, v20, 0
	s_nop 0
	v_mov_b32_e32 v39, s6
	v_readlane_b32 s6, v20, 48
	v_add_f32_e32 v39, s5, v39
	v_readlane_b32 s5, v20, 32
	v_mov_b32_e32 v20, s6
	s_nop 0
	v_add_f32_e32 v20, s5, v20
	v_add_f32_e32 v20, v39, v20
	v_mul_f32_e32 v20, 0x3b000000, v20
	v_fma_f32 v24, v25, v24, -v20
	v_fma_f32 v25, v31, v26, -v20
	v_mul_f32_e32 v25, v25, v25
	v_fmac_f32_e32 v25, v24, v24
	v_fma_f32 v24, v28, v27, -v20
	v_fmac_f32_e32 v25, v24, v24
	v_fma_f32 v21, v35, v21, -v20
	v_fmac_f32_e32 v25, v21, v21
	v_fma_f32 v21, v33, v29, -v20
	v_fmac_f32_e32 v25, v21, v21
	v_fma_f32 v21, v38, v22, -v20
	v_fmac_f32_e32 v25, v21, v21
	v_fma_f32 v21, v36, v34, -v20
	v_fmac_f32_e32 v25, v21, v21
	v_fma_f32 v21, v37, v23, -v20
	v_fmac_f32_e32 v25, v21, v21
	s_nop 1
	v_add_f32_dpp v21, v25, v25 quad_perm:[1,0,3,2] row_mask:0xf bank_mask:0xf bound_ctrl:1
	s_nop 1
	v_add_f32_dpp v21, v21, v21 quad_perm:[2,3,0,1] row_mask:0xf bank_mask:0xf bound_ctrl:1
	s_nop 1
	v_add_f32_dpp v21, v21, v21 row_half_mirror row_mask:0xf bank_mask:0xf bound_ctrl:1
	s_nop 1
	v_add_f32_dpp v21, v21, v21 row_mirror row_mask:0xf bank_mask:0xf bound_ctrl:1
	s_nop 0
	v_readlane_b32 s44, v21, 0
	v_readlane_b32 s5, v21, 16
	v_readlane_b32 s45, v21, 32
	v_readlane_b32 s6, v21, 48
	s_and_saveexec_b64 s[82:83], s[42:43]
	s_cbranch_execz .LBB0_420
	v_mov_b32_e32 v22, s5
	v_mov_b32_e32 v23, s6
	v_pk_add_f32 v[22:23], s[44:45], v[22:23]
	s_nop 0
	v_add_f32_e32 v21, v22, v23
	v_fmamk_f32 v21, v21, 0x3b000000, v176
	v_rsq_f32_e32 v21, v21
	ds_write_b64 v30, v[20:21] offset:80
.LBB0_420:
	s_or_b64 exec, exec, s[82:83]
	s_waitcnt vmcnt(4)
	v_and_b32_e32 v22, 0xffff0000, v16
	v_lshlrev_b32_e32 v20, 16, v16
	v_mul_f32_e32 v16, v22, v22
	v_lshlrev_b32_e32 v23, 16, v17
	v_fmamk_f32 v16, v16, 0xbdd2d3e8, v245
	v_mul_f32_e32 v24, v23, v23
	v_and_b32_e32 v17, 0xffff0000, v17
	v_mul_f32_e32 v16, v16, v22
	v_fmamk_f32 v24, v24, 0xbdd2d3e8, v245
	v_mul_f32_e32 v25, v17, v17
	v_mul_f32_e32 v24, v24, v23
	v_fmamk_f32 v25, v25, 0xbdd2d3e8, v245
	v_mul_f32_e32 v25, v25, v17
	v_exp_f32_e32 v16, v16
	v_exp_f32_e32 v24, v24
	v_exp_f32_e32 v25, v25
	v_add_f32_e32 v16, 1.0, v16
	v_rcp_f32_e32 v26, v16
	v_add_f32_e32 v16, 1.0, v24
	v_rcp_f32_e32 v24, v16
	v_add_f32_e32 v16, 1.0, v25
	v_lshlrev_b32_e32 v25, 16, v18
	v_mul_f32_e32 v27, v25, v25
	v_and_b32_e32 v18, 0xffff0000, v18
	v_fmamk_f32 v27, v27, 0xbdd2d3e8, v245
	v_mul_f32_e32 v28, v18, v18
	v_mul_f32_e32 v27, v27, v25
	v_fmamk_f32 v28, v28, 0xbdd2d3e8, v245
	v_mul_f32_e32 v28, v28, v18
	v_exp_f32_e32 v27, v27
	v_exp_f32_e32 v28, v28
	v_mul_f32_e32 v21, v20, v20
	v_fmamk_f32 v21, v21, 0xbdd2d3e8, v245
	v_rcp_f32_e32 v29, v16
	v_add_f32_e32 v16, 1.0, v27
	v_mul_f32_e32 v21, v21, v20
	v_rcp_f32_e32 v27, v16
	v_add_f32_e32 v16, 1.0, v28
	v_lshlrev_b32_e32 v28, 16, v19
	v_mul_f32_e32 v31, v28, v28
	v_and_b32_e32 v19, 0xffff0000, v19
	v_fmamk_f32 v31, v31, 0xbdd2d3e8, v245
	v_mul_f32_e32 v33, v19, v19
	v_exp_f32_e32 v21, v21
	v_mul_f32_e32 v31, v31, v28
	v_fmamk_f32 v33, v33, 0xbdd2d3e8, v245
	v_mul_f32_e32 v33, v33, v19
	v_exp_f32_e32 v31, v31
	v_add_f32_e32 v21, 1.0, v21
	v_exp_f32_e32 v33, v33
	v_rcp_f32_e32 v21, v21
	v_rcp_f32_e32 v34, v16
	v_add_f32_e32 v16, 1.0, v31
	v_rcp_f32_e32 v31, v16
	v_add_f32_e32 v16, 1.0, v33
	v_rcp_f32_e32 v33, v16
	v_fma_f32 v16, v21, v20, 0
	v_fmac_f32_e32 v16, v26, v22
	v_fmac_f32_e32 v16, v24, v23
	v_fmac_f32_e32 v16, v29, v17
	v_fmac_f32_e32 v16, v27, v25
	v_fmac_f32_e32 v16, v34, v18
	v_fmac_f32_e32 v16, v31, v28
	v_fmac_f32_e32 v16, v33, v19
	s_nop 1
	v_add_f32_dpp v16, v16, v16 quad_perm:[1,0,3,2] row_mask:0xf bank_mask:0xf bound_ctrl:1
	s_nop 1
	v_add_f32_dpp v16, v16, v16 quad_perm:[2,3,0,1] row_mask:0xf bank_mask:0xf bound_ctrl:1
	s_nop 1
	v_add_f32_dpp v16, v16, v16 row_half_mirror row_mask:0xf bank_mask:0xf bound_ctrl:1
	s_nop 1
	v_add_f32_dpp v16, v16, v16 row_mirror row_mask:0xf bank_mask:0xf bound_ctrl:1
	s_nop 0
	v_readlane_b32 s6, v16, 16
	v_readlane_b32 s5, v16, 0
	s_nop 0
	v_mov_b32_e32 v35, s6
	v_readlane_b32 s6, v16, 48
	v_add_f32_e32 v35, s5, v35
	v_readlane_b32 s5, v16, 32
	v_mov_b32_e32 v16, s6
	s_nop 0
	v_add_f32_e32 v16, s5, v16
	v_add_f32_e32 v16, v35, v16
	v_mul_f32_e32 v16, 0x3b000000, v16
	v_fma_f32 v20, v21, v20, -v16
	v_fma_f32 v21, v26, v22, -v16
	v_mul_f32_e32 v21, v21, v21
	v_fmac_f32_e32 v21, v20, v20
	v_fma_f32 v20, v24, v23, -v16
	v_fmac_f32_e32 v21, v20, v20
	v_fma_f32 v17, v29, v17, -v16
	v_fmac_f32_e32 v21, v17, v17
	v_fma_f32 v17, v27, v25, -v16
	v_fmac_f32_e32 v21, v17, v17
	v_fma_f32 v17, v34, v18, -v16
	v_fmac_f32_e32 v21, v17, v17
	v_fma_f32 v17, v31, v28, -v16
	v_fmac_f32_e32 v21, v17, v17
	v_fma_f32 v17, v33, v19, -v16
	v_fmac_f32_e32 v21, v17, v17
	s_nop 1
	v_add_f32_dpp v17, v21, v21 quad_perm:[1,0,3,2] row_mask:0xf bank_mask:0xf bound_ctrl:1
	s_nop 1
	v_add_f32_dpp v17, v17, v17 quad_perm:[2,3,0,1] row_mask:0xf bank_mask:0xf bound_ctrl:1
	s_nop 1
	v_add_f32_dpp v17, v17, v17 row_half_mirror row_mask:0xf bank_mask:0xf bound_ctrl:1
	s_nop 1
	v_add_f32_dpp v17, v17, v17 row_mirror row_mask:0xf bank_mask:0xf bound_ctrl:1
	s_nop 0
	v_readlane_b32 s44, v17, 0
	v_readlane_b32 s5, v17, 16
	v_readlane_b32 s45, v17, 32
	v_readlane_b32 s6, v17, 48
	s_and_saveexec_b64 s[82:83], s[42:43]
	s_cbranch_execz .LBB0_422
	v_mov_b32_e32 v18, s5
	v_mov_b32_e32 v19, s6
	v_pk_add_f32 v[18:19], s[44:45], v[18:19]
	s_nop 0
	v_add_f32_e32 v17, v18, v19
	v_fmamk_f32 v17, v17, 0x3b000000, v176
	v_rsq_f32_e32 v17, v17
	ds_write_b64 v30, v[16:17] offset:88
.LBB0_422:
	s_or_b64 exec, exec, s[82:83]
	s_waitcnt vmcnt(3)
	v_and_b32_e32 v18, 0xffff0000, v12
	v_lshlrev_b32_e32 v16, 16, v12
	v_mul_f32_e32 v12, v18, v18
	v_lshlrev_b32_e32 v19, 16, v13
	v_fmamk_f32 v12, v12, 0xbdd2d3e8, v245
	v_mul_f32_e32 v20, v19, v19
	v_and_b32_e32 v13, 0xffff0000, v13
	v_mul_f32_e32 v12, v12, v18
	v_fmamk_f32 v20, v20, 0xbdd2d3e8, v245
	v_mul_f32_e32 v21, v13, v13
	v_mul_f32_e32 v20, v20, v19
	v_fmamk_f32 v21, v21, 0xbdd2d3e8, v245
	v_mul_f32_e32 v21, v21, v13
	v_exp_f32_e32 v12, v12
	v_exp_f32_e32 v20, v20
	v_exp_f32_e32 v21, v21
	v_add_f32_e32 v12, 1.0, v12
	v_rcp_f32_e32 v22, v12
	v_add_f32_e32 v12, 1.0, v20
	v_rcp_f32_e32 v20, v12
	v_add_f32_e32 v12, 1.0, v21
	v_lshlrev_b32_e32 v21, 16, v14
	v_mul_f32_e32 v23, v21, v21
	v_and_b32_e32 v14, 0xffff0000, v14
	v_fmamk_f32 v23, v23, 0xbdd2d3e8, v245
	v_mul_f32_e32 v24, v14, v14
	v_mul_f32_e32 v23, v23, v21
	v_fmamk_f32 v24, v24, 0xbdd2d3e8, v245
	v_mul_f32_e32 v24, v24, v14
	v_exp_f32_e32 v23, v23
	v_exp_f32_e32 v24, v24
	v_mul_f32_e32 v17, v16, v16
	v_fmamk_f32 v17, v17, 0xbdd2d3e8, v245
	v_rcp_f32_e32 v25, v12
	v_add_f32_e32 v12, 1.0, v23
	v_mul_f32_e32 v17, v17, v16
	v_rcp_f32_e32 v23, v12
	v_add_f32_e32 v12, 1.0, v24
	v_lshlrev_b32_e32 v24, 16, v15
	v_mul_f32_e32 v26, v24, v24
	v_and_b32_e32 v15, 0xffff0000, v15
	v_fmamk_f32 v26, v26, 0xbdd2d3e8, v245
	v_mul_f32_e32 v27, v15, v15
	v_exp_f32_e32 v17, v17
	v_mul_f32_e32 v26, v26, v24
	v_fmamk_f32 v27, v27, 0xbdd2d3e8, v245
	v_mul_f32_e32 v27, v27, v15
	v_exp_f32_e32 v26, v26
	v_add_f32_e32 v17, 1.0, v17
	v_exp_f32_e32 v27, v27
	v_rcp_f32_e32 v17, v17
	v_rcp_f32_e32 v28, v12
	v_add_f32_e32 v12, 1.0, v26
	v_rcp_f32_e32 v26, v12
	v_add_f32_e32 v12, 1.0, v27
	v_rcp_f32_e32 v27, v12
	v_fma_f32 v12, v17, v16, 0
	v_fmac_f32_e32 v12, v22, v18
	v_fmac_f32_e32 v12, v20, v19
	v_fmac_f32_e32 v12, v25, v13
	v_fmac_f32_e32 v12, v23, v21
	v_fmac_f32_e32 v12, v28, v14
	v_fmac_f32_e32 v12, v26, v24
	v_fmac_f32_e32 v12, v27, v15
	s_nop 1
	v_add_f32_dpp v12, v12, v12 quad_perm:[1,0,3,2] row_mask:0xf bank_mask:0xf bound_ctrl:1
	s_nop 1
	v_add_f32_dpp v12, v12, v12 quad_perm:[2,3,0,1] row_mask:0xf bank_mask:0xf bound_ctrl:1
	s_nop 1
	v_add_f32_dpp v12, v12, v12 row_half_mirror row_mask:0xf bank_mask:0xf bound_ctrl:1
	s_nop 1
	v_add_f32_dpp v12, v12, v12 row_mirror row_mask:0xf bank_mask:0xf bound_ctrl:1
	s_nop 0
	v_readlane_b32 s6, v12, 16
	v_readlane_b32 s5, v12, 0
	s_nop 0
	v_mov_b32_e32 v29, s6
	v_readlane_b32 s6, v12, 48
	v_add_f32_e32 v29, s5, v29
	v_readlane_b32 s5, v12, 32
	v_mov_b32_e32 v12, s6
	s_nop 0
	v_add_f32_e32 v12, s5, v12
	v_add_f32_e32 v12, v29, v12
	v_mul_f32_e32 v12, 0x3b000000, v12
	v_fma_f32 v16, v17, v16, -v12
	v_fma_f32 v17, v22, v18, -v12
	v_mul_f32_e32 v17, v17, v17
	v_fmac_f32_e32 v17, v16, v16
	v_fma_f32 v16, v20, v19, -v12
	v_fmac_f32_e32 v17, v16, v16
	v_fma_f32 v13, v25, v13, -v12
	v_fmac_f32_e32 v17, v13, v13
	v_fma_f32 v13, v23, v21, -v12
	v_fmac_f32_e32 v17, v13, v13
	v_fma_f32 v13, v28, v14, -v12
	v_fmac_f32_e32 v17, v13, v13
	v_fma_f32 v13, v26, v24, -v12
	v_fmac_f32_e32 v17, v13, v13
	v_fma_f32 v13, v27, v15, -v12
	v_fmac_f32_e32 v17, v13, v13
	s_nop 1
	v_add_f32_dpp v13, v17, v17 quad_perm:[1,0,3,2] row_mask:0xf bank_mask:0xf bound_ctrl:1
	s_nop 1
	v_add_f32_dpp v13, v13, v13 quad_perm:[2,3,0,1] row_mask:0xf bank_mask:0xf bound_ctrl:1
	s_nop 1
	v_add_f32_dpp v13, v13, v13 row_half_mirror row_mask:0xf bank_mask:0xf bound_ctrl:1
	s_nop 1
	v_add_f32_dpp v13, v13, v13 row_mirror row_mask:0xf bank_mask:0xf bound_ctrl:1
	s_nop 0
	v_readlane_b32 s44, v13, 0
	v_readlane_b32 s5, v13, 16
	v_readlane_b32 s45, v13, 32
	v_readlane_b32 s6, v13, 48
	s_and_saveexec_b64 s[82:83], s[42:43]
	s_cbranch_execz .LBB0_424
	v_mov_b32_e32 v14, s5
	v_mov_b32_e32 v15, s6
	v_pk_add_f32 v[14:15], s[44:45], v[14:15]
	s_nop 0
	v_add_f32_e32 v13, v14, v15
	v_fmamk_f32 v13, v13, 0x3b000000, v176
	v_rsq_f32_e32 v13, v13
	ds_write_b64 v30, v[12:13] offset:96
.LBB0_424:
	s_or_b64 exec, exec, s[82:83]
	s_waitcnt vmcnt(2)
	v_and_b32_e32 v14, 0xffff0000, v8
	v_lshlrev_b32_e32 v12, 16, v8
	v_mul_f32_e32 v8, v14, v14
	v_lshlrev_b32_e32 v15, 16, v9
	v_fmamk_f32 v8, v8, 0xbdd2d3e8, v245
	v_mul_f32_e32 v16, v15, v15
	v_and_b32_e32 v9, 0xffff0000, v9
	v_mul_f32_e32 v8, v8, v14
	v_fmamk_f32 v16, v16, 0xbdd2d3e8, v245
	v_mul_f32_e32 v17, v9, v9
	v_mul_f32_e32 v16, v16, v15
	v_fmamk_f32 v17, v17, 0xbdd2d3e8, v245
	v_mul_f32_e32 v17, v17, v9
	v_exp_f32_e32 v8, v8
	v_exp_f32_e32 v16, v16
	v_exp_f32_e32 v17, v17
	v_add_f32_e32 v8, 1.0, v8
	v_rcp_f32_e32 v18, v8
	v_add_f32_e32 v8, 1.0, v16
	v_rcp_f32_e32 v16, v8
	v_add_f32_e32 v8, 1.0, v17
	v_lshlrev_b32_e32 v17, 16, v10
	v_mul_f32_e32 v19, v17, v17
	v_and_b32_e32 v10, 0xffff0000, v10
	v_fmamk_f32 v19, v19, 0xbdd2d3e8, v245
	v_mul_f32_e32 v20, v10, v10
	v_mul_f32_e32 v19, v19, v17
	v_fmamk_f32 v20, v20, 0xbdd2d3e8, v245
	v_mul_f32_e32 v20, v20, v10
	v_exp_f32_e32 v19, v19
	v_exp_f32_e32 v20, v20
	v_mul_f32_e32 v13, v12, v12
	v_fmamk_f32 v13, v13, 0xbdd2d3e8, v245
	v_rcp_f32_e32 v21, v8
	v_add_f32_e32 v8, 1.0, v19
	v_mul_f32_e32 v13, v13, v12
	v_rcp_f32_e32 v19, v8
	v_add_f32_e32 v8, 1.0, v20
	v_lshlrev_b32_e32 v20, 16, v11
	v_mul_f32_e32 v22, v20, v20
	v_and_b32_e32 v11, 0xffff0000, v11
	v_fmamk_f32 v22, v22, 0xbdd2d3e8, v245
	v_mul_f32_e32 v23, v11, v11
	v_exp_f32_e32 v13, v13
	v_mul_f32_e32 v22, v22, v20
	v_fmamk_f32 v23, v23, 0xbdd2d3e8, v245
	v_mul_f32_e32 v23, v23, v11
	v_exp_f32_e32 v22, v22
	v_add_f32_e32 v13, 1.0, v13
	v_exp_f32_e32 v23, v23
	v_rcp_f32_e32 v13, v13
	v_rcp_f32_e32 v24, v8
	v_add_f32_e32 v8, 1.0, v22
	v_rcp_f32_e32 v22, v8
	v_add_f32_e32 v8, 1.0, v23
	v_rcp_f32_e32 v23, v8
	v_fma_f32 v8, v13, v12, 0
	v_fmac_f32_e32 v8, v18, v14
	v_fmac_f32_e32 v8, v16, v15
	v_fmac_f32_e32 v8, v21, v9
	v_fmac_f32_e32 v8, v19, v17
	v_fmac_f32_e32 v8, v24, v10
	v_fmac_f32_e32 v8, v22, v20
	v_fmac_f32_e32 v8, v23, v11
	s_nop 1
	v_add_f32_dpp v8, v8, v8 quad_perm:[1,0,3,2] row_mask:0xf bank_mask:0xf bound_ctrl:1
	s_nop 1
	v_add_f32_dpp v8, v8, v8 quad_perm:[2,3,0,1] row_mask:0xf bank_mask:0xf bound_ctrl:1
	s_nop 1
	v_add_f32_dpp v8, v8, v8 row_half_mirror row_mask:0xf bank_mask:0xf bound_ctrl:1
	s_nop 1
	v_add_f32_dpp v8, v8, v8 row_mirror row_mask:0xf bank_mask:0xf bound_ctrl:1
	s_nop 0
	v_readlane_b32 s6, v8, 16
	v_readlane_b32 s5, v8, 0
	s_nop 0
	v_mov_b32_e32 v25, s6
	v_readlane_b32 s6, v8, 48
	v_add_f32_e32 v25, s5, v25
	v_readlane_b32 s5, v8, 32
	v_mov_b32_e32 v8, s6
	s_nop 0
	v_add_f32_e32 v8, s5, v8
	v_add_f32_e32 v8, v25, v8
	v_mul_f32_e32 v8, 0x3b000000, v8
	v_fma_f32 v12, v13, v12, -v8
	v_fma_f32 v13, v18, v14, -v8
	v_mul_f32_e32 v13, v13, v13
	v_fmac_f32_e32 v13, v12, v12
	v_fma_f32 v12, v16, v15, -v8
	v_fmac_f32_e32 v13, v12, v12
	v_fma_f32 v9, v21, v9, -v8
	v_fmac_f32_e32 v13, v9, v9
	v_fma_f32 v9, v19, v17, -v8
	v_fmac_f32_e32 v13, v9, v9
	v_fma_f32 v9, v24, v10, -v8
	v_fmac_f32_e32 v13, v9, v9
	v_fma_f32 v9, v22, v20, -v8
	v_fmac_f32_e32 v13, v9, v9
	v_fma_f32 v9, v23, v11, -v8
	v_fmac_f32_e32 v13, v9, v9
	s_nop 1
	v_add_f32_dpp v9, v13, v13 quad_perm:[1,0,3,2] row_mask:0xf bank_mask:0xf bound_ctrl:1
	s_nop 1
	v_add_f32_dpp v9, v9, v9 quad_perm:[2,3,0,1] row_mask:0xf bank_mask:0xf bound_ctrl:1
	s_nop 1
	v_add_f32_dpp v9, v9, v9 row_half_mirror row_mask:0xf bank_mask:0xf bound_ctrl:1
	s_nop 1
	v_add_f32_dpp v9, v9, v9 row_mirror row_mask:0xf bank_mask:0xf bound_ctrl:1
	s_nop 0
	v_readlane_b32 s44, v9, 0
	v_readlane_b32 s5, v9, 16
	v_readlane_b32 s45, v9, 32
	v_readlane_b32 s6, v9, 48
	s_and_saveexec_b64 s[82:83], s[42:43]
	s_cbranch_execz .LBB0_426
	v_mov_b32_e32 v10, s5
	v_mov_b32_e32 v11, s6
	v_pk_add_f32 v[10:11], s[44:45], v[10:11]
	s_nop 0
	v_add_f32_e32 v9, v10, v11
	v_fmamk_f32 v9, v9, 0x3b000000, v176
	v_rsq_f32_e32 v9, v9
	ds_write_b64 v30, v[8:9] offset:104
.LBB0_426:
	s_or_b64 exec, exec, s[82:83]
	s_waitcnt vmcnt(1)
	v_and_b32_e32 v10, 0xffff0000, v4
	v_lshlrev_b32_e32 v8, 16, v4
	v_mul_f32_e32 v4, v10, v10
	v_lshlrev_b32_e32 v11, 16, v5
	v_fmamk_f32 v4, v4, 0xbdd2d3e8, v245
	v_mul_f32_e32 v12, v11, v11
	v_and_b32_e32 v5, 0xffff0000, v5
	v_mul_f32_e32 v4, v4, v10
	v_fmamk_f32 v12, v12, 0xbdd2d3e8, v245
	v_mul_f32_e32 v13, v5, v5
	v_mul_f32_e32 v12, v12, v11
	v_fmamk_f32 v13, v13, 0xbdd2d3e8, v245
	v_mul_f32_e32 v13, v13, v5
	v_exp_f32_e32 v4, v4
	v_exp_f32_e32 v12, v12
	v_exp_f32_e32 v13, v13
	v_add_f32_e32 v4, 1.0, v4
	v_rcp_f32_e32 v14, v4
	v_add_f32_e32 v4, 1.0, v12
	v_rcp_f32_e32 v12, v4
	v_add_f32_e32 v4, 1.0, v13
	v_lshlrev_b32_e32 v13, 16, v6
	v_mul_f32_e32 v15, v13, v13
	v_and_b32_e32 v6, 0xffff0000, v6
	v_fmamk_f32 v15, v15, 0xbdd2d3e8, v245
	v_mul_f32_e32 v16, v6, v6
	v_mul_f32_e32 v15, v15, v13
	v_fmamk_f32 v16, v16, 0xbdd2d3e8, v245
	v_mul_f32_e32 v16, v16, v6
	v_exp_f32_e32 v15, v15
	v_exp_f32_e32 v16, v16
	v_mul_f32_e32 v9, v8, v8
	v_fmamk_f32 v9, v9, 0xbdd2d3e8, v245
	v_rcp_f32_e32 v17, v4
	v_add_f32_e32 v4, 1.0, v15
	v_mul_f32_e32 v9, v9, v8
	v_rcp_f32_e32 v15, v4
	v_add_f32_e32 v4, 1.0, v16
	v_lshlrev_b32_e32 v16, 16, v7
	v_mul_f32_e32 v18, v16, v16
	v_and_b32_e32 v7, 0xffff0000, v7
	v_fmamk_f32 v18, v18, 0xbdd2d3e8, v245
	v_mul_f32_e32 v19, v7, v7
	v_exp_f32_e32 v9, v9
	v_mul_f32_e32 v18, v18, v16
	v_fmamk_f32 v19, v19, 0xbdd2d3e8, v245
	v_mul_f32_e32 v19, v19, v7
	v_exp_f32_e32 v18, v18
	v_add_f32_e32 v9, 1.0, v9
	v_exp_f32_e32 v19, v19
	v_rcp_f32_e32 v9, v9
	v_rcp_f32_e32 v20, v4
	v_add_f32_e32 v4, 1.0, v18
	v_rcp_f32_e32 v18, v4
	v_add_f32_e32 v4, 1.0, v19
	v_rcp_f32_e32 v19, v4
	v_fma_f32 v4, v9, v8, 0
	v_fmac_f32_e32 v4, v14, v10
	v_fmac_f32_e32 v4, v12, v11
	v_fmac_f32_e32 v4, v17, v5
	v_fmac_f32_e32 v4, v15, v13
	v_fmac_f32_e32 v4, v20, v6
	v_fmac_f32_e32 v4, v18, v16
	v_fmac_f32_e32 v4, v19, v7
	s_nop 1
	v_add_f32_dpp v4, v4, v4 quad_perm:[1,0,3,2] row_mask:0xf bank_mask:0xf bound_ctrl:1
	s_nop 1
	v_add_f32_dpp v4, v4, v4 quad_perm:[2,3,0,1] row_mask:0xf bank_mask:0xf bound_ctrl:1
	s_nop 1
	v_add_f32_dpp v4, v4, v4 row_half_mirror row_mask:0xf bank_mask:0xf bound_ctrl:1
	s_nop 1
	v_add_f32_dpp v4, v4, v4 row_mirror row_mask:0xf bank_mask:0xf bound_ctrl:1
	s_nop 0
	v_readlane_b32 s6, v4, 16
	v_readlane_b32 s5, v4, 0
	s_nop 0
	v_mov_b32_e32 v21, s6
	v_readlane_b32 s6, v4, 48
	v_add_f32_e32 v21, s5, v21
	v_readlane_b32 s5, v4, 32
	v_mov_b32_e32 v4, s6
	s_nop 0
	v_add_f32_e32 v4, s5, v4
	v_add_f32_e32 v4, v21, v4
	v_mul_f32_e32 v4, 0x3b000000, v4
	v_fma_f32 v8, v9, v8, -v4
	v_fma_f32 v9, v14, v10, -v4
	v_mul_f32_e32 v9, v9, v9
	v_fmac_f32_e32 v9, v8, v8
	v_fma_f32 v8, v12, v11, -v4
	v_fmac_f32_e32 v9, v8, v8
	v_fma_f32 v5, v17, v5, -v4
	v_fmac_f32_e32 v9, v5, v5
	v_fma_f32 v5, v15, v13, -v4
	v_fmac_f32_e32 v9, v5, v5
	v_fma_f32 v5, v20, v6, -v4
	v_fmac_f32_e32 v9, v5, v5
	v_fma_f32 v5, v18, v16, -v4
	v_fmac_f32_e32 v9, v5, v5
	v_fma_f32 v5, v19, v7, -v4
	v_fmac_f32_e32 v9, v5, v5
	s_nop 1
	v_add_f32_dpp v5, v9, v9 quad_perm:[1,0,3,2] row_mask:0xf bank_mask:0xf bound_ctrl:1
	s_nop 1
	v_add_f32_dpp v5, v5, v5 quad_perm:[2,3,0,1] row_mask:0xf bank_mask:0xf bound_ctrl:1
	s_nop 1
	v_add_f32_dpp v5, v5, v5 row_half_mirror row_mask:0xf bank_mask:0xf bound_ctrl:1
	s_nop 1
	v_add_f32_dpp v5, v5, v5 row_mirror row_mask:0xf bank_mask:0xf bound_ctrl:1
	s_nop 0
	v_readlane_b32 s44, v5, 0
	v_readlane_b32 s5, v5, 16
	v_readlane_b32 s45, v5, 32
	v_readlane_b32 s6, v5, 48
	s_and_saveexec_b64 s[82:83], s[42:43]
	s_cbranch_execz .LBB0_428
	v_mov_b32_e32 v6, s5
	v_mov_b32_e32 v7, s6
	v_pk_add_f32 v[6:7], s[44:45], v[6:7]
	s_nop 0
	v_add_f32_e32 v5, v6, v7
	v_fmamk_f32 v5, v5, 0x3b000000, v176
	v_rsq_f32_e32 v5, v5
	ds_write_b64 v30, v[4:5] offset:112
.LBB0_428:
	s_or_b64 exec, exec, s[82:83]
	s_waitcnt vmcnt(0)
	v_and_b32_e32 v6, 0xffff0000, v0
	v_lshlrev_b32_e32 v4, 16, v0
	v_mul_f32_e32 v0, v6, v6
	v_lshlrev_b32_e32 v7, 16, v1
	v_fmamk_f32 v0, v0, 0xbdd2d3e8, v245
	v_mul_f32_e32 v8, v7, v7
	v_and_b32_e32 v1, 0xffff0000, v1
	v_mul_f32_e32 v0, v0, v6
	v_fmamk_f32 v8, v8, 0xbdd2d3e8, v245
	v_mul_f32_e32 v9, v1, v1
	v_mul_f32_e32 v8, v8, v7
	v_fmamk_f32 v9, v9, 0xbdd2d3e8, v245
	v_mul_f32_e32 v9, v9, v1
	v_exp_f32_e32 v0, v0
	v_exp_f32_e32 v8, v8
	v_exp_f32_e32 v9, v9
	v_add_f32_e32 v0, 1.0, v0
	v_rcp_f32_e32 v10, v0
	v_add_f32_e32 v0, 1.0, v8
	v_rcp_f32_e32 v8, v0
	v_add_f32_e32 v0, 1.0, v9
	v_lshlrev_b32_e32 v9, 16, v2
	v_mul_f32_e32 v11, v9, v9
	v_and_b32_e32 v2, 0xffff0000, v2
	v_fmamk_f32 v11, v11, 0xbdd2d3e8, v245
	v_mul_f32_e32 v12, v2, v2
	v_mul_f32_e32 v11, v11, v9
	v_fmamk_f32 v12, v12, 0xbdd2d3e8, v245
	v_mul_f32_e32 v12, v12, v2
	v_exp_f32_e32 v11, v11
	v_exp_f32_e32 v12, v12
	v_mul_f32_e32 v5, v4, v4
	v_fmamk_f32 v5, v5, 0xbdd2d3e8, v245
	v_rcp_f32_e32 v13, v0
	v_add_f32_e32 v0, 1.0, v11
	v_mul_f32_e32 v5, v5, v4
	v_rcp_f32_e32 v11, v0
	v_add_f32_e32 v0, 1.0, v12
	v_lshlrev_b32_e32 v12, 16, v3
	v_mul_f32_e32 v14, v12, v12
	v_and_b32_e32 v3, 0xffff0000, v3
	v_fmamk_f32 v14, v14, 0xbdd2d3e8, v245
	v_mul_f32_e32 v15, v3, v3
	v_exp_f32_e32 v5, v5
	v_mul_f32_e32 v14, v14, v12
	v_fmamk_f32 v15, v15, 0xbdd2d3e8, v245
	v_mul_f32_e32 v15, v15, v3
	v_exp_f32_e32 v14, v14
	v_add_f32_e32 v5, 1.0, v5
	v_exp_f32_e32 v15, v15
	v_rcp_f32_e32 v5, v5
	v_rcp_f32_e32 v16, v0
	v_add_f32_e32 v0, 1.0, v14
	v_rcp_f32_e32 v14, v0
	v_add_f32_e32 v0, 1.0, v15
	v_rcp_f32_e32 v15, v0
	v_fma_f32 v0, v5, v4, 0
	v_fmac_f32_e32 v0, v10, v6
	v_fmac_f32_e32 v0, v8, v7
	v_fmac_f32_e32 v0, v13, v1
	v_fmac_f32_e32 v0, v11, v9
	v_fmac_f32_e32 v0, v16, v2
	v_fmac_f32_e32 v0, v14, v12
	v_fmac_f32_e32 v0, v15, v3
	s_nop 1
	v_add_f32_dpp v0, v0, v0 quad_perm:[1,0,3,2] row_mask:0xf bank_mask:0xf bound_ctrl:1
	s_nop 1
	v_add_f32_dpp v0, v0, v0 quad_perm:[2,3,0,1] row_mask:0xf bank_mask:0xf bound_ctrl:1
	s_nop 1
	v_add_f32_dpp v0, v0, v0 row_half_mirror row_mask:0xf bank_mask:0xf bound_ctrl:1
	s_nop 1
	v_add_f32_dpp v0, v0, v0 row_mirror row_mask:0xf bank_mask:0xf bound_ctrl:1
	s_nop 0
	v_readlane_b32 s6, v0, 16
	v_readlane_b32 s5, v0, 0
	s_nop 0
	v_mov_b32_e32 v17, s6
	v_readlane_b32 s6, v0, 48
	v_add_f32_e32 v17, s5, v17
	v_readlane_b32 s5, v0, 32
	v_mov_b32_e32 v0, s6
	s_nop 0
	v_add_f32_e32 v0, s5, v0
	v_add_f32_e32 v0, v17, v0
	v_mul_f32_e32 v0, 0x3b000000, v0
	v_fma_f32 v4, v5, v4, -v0
	v_fma_f32 v5, v10, v6, -v0
	v_mul_f32_e32 v5, v5, v5
	v_fmac_f32_e32 v5, v4, v4
	v_fma_f32 v4, v8, v7, -v0
	v_fmac_f32_e32 v5, v4, v4
	v_fma_f32 v1, v13, v1, -v0
	v_fmac_f32_e32 v5, v1, v1
	v_fma_f32 v1, v11, v9, -v0
	v_fmac_f32_e32 v5, v1, v1
	v_fma_f32 v1, v16, v2, -v0
	v_fmac_f32_e32 v5, v1, v1
	v_fma_f32 v1, v14, v12, -v0
	v_fmac_f32_e32 v5, v1, v1
	v_fma_f32 v1, v15, v3, -v0
	v_fmac_f32_e32 v5, v1, v1
	s_nop 1
	v_add_f32_dpp v1, v5, v5 quad_perm:[1,0,3,2] row_mask:0xf bank_mask:0xf bound_ctrl:1
	s_nop 1
	v_add_f32_dpp v1, v1, v1 quad_perm:[2,3,0,1] row_mask:0xf bank_mask:0xf bound_ctrl:1
	s_nop 1
	v_add_f32_dpp v1, v1, v1 row_half_mirror row_mask:0xf bank_mask:0xf bound_ctrl:1
	s_nop 1
	v_add_f32_dpp v1, v1, v1 row_mirror row_mask:0xf bank_mask:0xf bound_ctrl:1
	s_nop 0
	v_readlane_b32 s82, v1, 0
	v_readlane_b32 s5, v1, 16
	v_readlane_b32 s83, v1, 32
	v_readlane_b32 s6, v1, 48
	s_and_saveexec_b64 s[44:45], s[42:43]
	s_cbranch_execz .LBB0_362
	v_mov_b32_e32 v2, s5
	v_mov_b32_e32 v3, s6
	v_pk_add_f32 v[2:3], s[82:83], v[2:3]
	s_nop 0
	v_add_f32_e32 v1, v2, v3
	v_fmamk_f32 v1, v1, 0x3b000000, v176
	v_rsq_f32_e32 v1, v1
	ds_write_b64 v30, v[0:1] offset:120
	s_branch .LBB0_362
